# removed the redundant s_waitcnt vmcnt(0) at the start of four GEMM epilogues (epre loads are long retired; next-unit LDS-DMA prefetch stays in flight during the epilogue)
# speedup vs baseline: 1.0164x; 1.0164x over previous
; __device__ __forceinline__ unsigned cvt_pk_bf16(float lo, float hi) { unsigned r; asm volatile("v_cvt_pk_bf16_f32 %0, %1, %2" : "=v"(r) : "v"(lo), "v"(hi)); return r; }
; #define GAS __attribute__((address_space(1)))
;     __device__ __forceinline__ void operator()(const f32x4 (&acc)[2][2][4][2], const Unit& u, int wr, int wc, int fr, int fq, const float (&pre)[8]) const {
;     ...
;         for (int ai = 0; ai < 2; ++ai)
; #pragma unroll
;             for (int m = 0; m < 4; ++m) {
;                 const int row = row0 + ai * 128 + m * 16; bf16_t* rowp = O + (size_t)row * ldc + col0; float rs = 0.f;
;                 float rsc = 1.f; if (RS == 1) rsc = pre[ai * 4 + m];
; #pragma unroll
;                 for (int bj = 0; bj < 2; ++bj) {
;                     f32x4 v0 = acc[ai][bj][m][0], v1 = acc[ai][bj][m][1];
;                     if (RS == 1) { v0 = v0 * rsc; v1 = v1 * rsc; }
;                     if (RS == 2) { v0 = v0 * csc[bj][0]; v1 = v1 * csc[bj][1]; }
;                     if (ACT == 1) { const f32x2 a = gelu_pk((f32x2){v0[0], v0[1]}), b = gelu_pk((f32x2){v0[2], v0[3]}), c = gelu_pk((f32x2){v1[0], v1[1]}), d = gelu_pk((f32x2){v1[2], v1[3]});
;                         v0 = (f32x4){a.x, a.y, b.x, b.y}; v1 = (f32x4){c.x, c.y, d.x, d.y}; }
;                     v0 = v0 * sc; v1 = v1 * sc;
;                     if (STAT == 1) rs += (v0[0] * v0[0] + v0[1] * v0[1]) + (v0[2] * v0[2] + v0[3] * v0[3]) + (v1[0] * v1[0] + v1[1] * v1[1]) + (v1[2] * v1[2] + v1[3] * v1[3]);
;                     if (STAT == 2) {
; #pragma unroll
;                         for (int e = 0; e < 4; ++e) { cs[bj][0][e] += v0[e]; cq[bj][0][e] += v0[e] * v0[e]; cs[bj][1][e] += v1[e]; cq[bj][1][e] += v1[e] * v1[e]; } }
;                     u32x4 w; w.x = cvt_pk_bf16(v0[0], v0[1]); w.y = cvt_pk_bf16(v0[2], v0[3]); w.z = cvt_pk_bf16(v1[0], v1[1]); w.w = cvt_pk_bf16(v1[2], v1[3]);
;                     *(GAS u32x4*)(rowp + bj * 128) = w; }
.LBB0_69:
	v_lshl_add_u32 v172, s88, 8, v33
	v_lshl_or_b32 v170, s3, 8, v141
	s_cmp_lt_i32 s3, 4
	v_ashrrev_i32_e32 v173, 31, v172
	s_cselect_b64 vcc, -1, 0
	v_ashrrev_i32_e32 v171, 31, v170
	v_lshlrev_b64 v[174:175], 12, v[172:173]
	v_cndmask_b32_e32 v160, 1.0, v190, vcc
	v_lshl_add_u64 v[174:175], s[82:83], 0, v[174:175]
	v_lshlrev_b64 v[176:177], 1, v[170:171]
	v_pk_mul_f32 v[128:129], v[158:159], v[128:129] op_sel_hi:[0,1]
	v_pk_mul_f32 v[126:127], v[158:159], v[126:127] op_sel_hi:[0,1]
	v_pk_mul_f32 v[124:125], v[158:159], v[124:125] op_sel_hi:[0,1]
	v_pk_mul_f32 v[122:123], v[158:159], v[122:123] op_sel_hi:[0,1]
	v_lshl_add_u64 v[170:171], v[174:175], 0, v[176:177]
	v_pk_mul_f32 v[128:129], v[160:161], v[128:129] op_sel_hi:[0,1]
	v_pk_mul_f32 v[126:127], v[160:161], v[126:127] op_sel_hi:[0,1]
	v_pk_mul_f32 v[174:175], v[160:161], v[124:125] op_sel_hi:[0,1]
	v_pk_mul_f32 v[124:125], v[160:161], v[122:123] op_sel_hi:[0,1]
	v_cvt_pk_bf16_f32 v122, v126, v127
	v_cvt_pk_bf16_f32 v123, v128, v129
	v_pk_mul_f32 v[118:119], v[158:159], v[118:119] op_sel_hi:[0,1]
	v_pk_mul_f32 v[116:117], v[158:159], v[116:117] op_sel_hi:[0,1]
	v_pk_mul_f32 v[114:115], v[158:159], v[114:115] op_sel_hi:[0,1]
	v_cvt_pk_bf16_f32 v124, v124, v125
	v_cvt_pk_bf16_f32 v125, v174, v175
	global_store_dwordx4 v[170:171], v[122:125], off
	v_pk_mul_f32 v[120:121], v[158:159], v[120:121] op_sel_hi:[0,1]
	v_pk_mul_f32 v[118:119], v[160:161], v[118:119] op_sel_hi:[0,1]
	v_pk_mul_f32 v[122:123], v[160:161], v[116:117] op_sel_hi:[0,1]
	v_pk_mul_f32 v[116:117], v[160:161], v[114:115] op_sel_hi:[0,1]
	v_cvt_pk_bf16_f32 v114, v118, v119
	v_pk_mul_f32 v[120:121], v[160:161], v[120:121] op_sel_hi:[0,1]
	v_cvt_pk_bf16_f32 v115, v120, v121
	v_cvt_pk_bf16_f32 v116, v116, v117
	v_cvt_pk_bf16_f32 v117, v122, v123
	global_store_dwordx4 v[170:171], v[114:117], off offset:256
	v_pk_mul_f32 v[112:113], v[156:157], v[112:113] op_sel_hi:[0,1]
	v_pk_mul_f32 v[110:111], v[156:157], v[110:111] op_sel_hi:[0,1]
	v_or_b32_e32 v114, 16, v172
	v_ashrrev_i32_e32 v115, 31, v114
	v_lshlrev_b64 v[114:115], 12, v[114:115]
	v_lshl_add_u64 v[114:115], s[82:83], 0, v[114:115]
	v_pk_mul_f32 v[108:109], v[156:157], v[108:109] op_sel_hi:[0,1]
	v_pk_mul_f32 v[106:107], v[156:157], v[106:107] op_sel_hi:[0,1]
	v_lshl_add_u64 v[114:115], v[114:115], 0, v[176:177]
	v_pk_mul_f32 v[112:113], v[160:161], v[112:113] op_sel_hi:[0,1]
	v_pk_mul_f32 v[110:111], v[160:161], v[110:111] op_sel_hi:[0,1]
	v_pk_mul_f32 v[116:117], v[160:161], v[108:109] op_sel_hi:[0,1]
	v_pk_mul_f32 v[108:109], v[160:161], v[106:107] op_sel_hi:[0,1]
	v_cvt_pk_bf16_f32 v106, v110, v111
	v_cvt_pk_bf16_f32 v107, v112, v113
	v_pk_mul_f32 v[102:103], v[156:157], v[102:103] op_sel_hi:[0,1]
	v_pk_mul_f32 v[100:101], v[156:157], v[100:101] op_sel_hi:[0,1]
	v_pk_mul_f32 v[98:99], v[156:157], v[98:99] op_sel_hi:[0,1]
	v_cvt_pk_bf16_f32 v108, v108, v109
	v_cvt_pk_bf16_f32 v109, v116, v117
	global_store_dwordx4 v[114:115], v[106:109], off
	v_pk_mul_f32 v[104:105], v[156:157], v[104:105] op_sel_hi:[0,1]
	v_pk_mul_f32 v[102:103], v[160:161], v[102:103] op_sel_hi:[0,1]
	v_pk_mul_f32 v[106:107], v[160:161], v[100:101] op_sel_hi:[0,1]
	v_pk_mul_f32 v[100:101], v[160:161], v[98:99] op_sel_hi:[0,1]
	v_cvt_pk_bf16_f32 v98, v102, v103
	v_pk_mul_f32 v[104:105], v[160:161], v[104:105] op_sel_hi:[0,1]
	v_cvt_pk_bf16_f32 v99, v104, v105
	v_cvt_pk_bf16_f32 v100, v100, v101
	v_cvt_pk_bf16_f32 v101, v106, v107
	global_store_dwordx4 v[114:115], v[98:101], off offset:256
	v_pk_mul_f32 v[96:97], v[154:155], v[96:97] op_sel_hi:[0,1]
	v_pk_mul_f32 v[94:95], v[154:155], v[94:95] op_sel_hi:[0,1]
	v_or_b32_e32 v98, 32, v172
	v_ashrrev_i32_e32 v99, 31, v98
	v_lshlrev_b64 v[98:99], 12, v[98:99]
	v_lshl_add_u64 v[98:99], s[82:83], 0, v[98:99]
	v_pk_mul_f32 v[92:93], v[154:155], v[92:93] op_sel_hi:[0,1]
	v_pk_mul_f32 v[90:91], v[154:155], v[90:91] op_sel_hi:[0,1]
	v_lshl_add_u64 v[98:99], v[98:99], 0, v[176:177]
	v_pk_mul_f32 v[96:97], v[160:161], v[96:97] op_sel_hi:[0,1]
	v_pk_mul_f32 v[94:95], v[160:161], v[94:95] op_sel_hi:[0,1]
	v_pk_mul_f32 v[100:101], v[160:161], v[92:93] op_sel_hi:[0,1]
	v_pk_mul_f32 v[92:93], v[160:161], v[90:91] op_sel_hi:[0,1]
	v_cvt_pk_bf16_f32 v90, v94, v95
	v_cvt_pk_bf16_f32 v91, v96, v97
	v_pk_mul_f32 v[86:87], v[154:155], v[86:87] op_sel_hi:[0,1]
	v_pk_mul_f32 v[84:85], v[154:155], v[84:85] op_sel_hi:[0,1]
	v_pk_mul_f32 v[82:83], v[154:155], v[82:83] op_sel_hi:[0,1]
	v_cvt_pk_bf16_f32 v92, v92, v93
	v_cvt_pk_bf16_f32 v93, v100, v101
	global_store_dwordx4 v[98:99], v[90:93], off
	v_pk_mul_f32 v[88:89], v[154:155], v[88:89] op_sel_hi:[0,1]
	v_pk_mul_f32 v[86:87], v[160:161], v[86:87] op_sel_hi:[0,1]
	v_pk_mul_f32 v[90:91], v[160:161], v[84:85] op_sel_hi:[0,1]
	v_pk_mul_f32 v[84:85], v[160:161], v[82:83] op_sel_hi:[0,1]
	v_cvt_pk_bf16_f32 v82, v86, v87
	v_pk_mul_f32 v[88:89], v[160:161], v[88:89] op_sel_hi:[0,1]
	v_cvt_pk_bf16_f32 v83, v88, v89
	v_cvt_pk_bf16_f32 v84, v84, v85
	v_cvt_pk_bf16_f32 v85, v90, v91
	global_store_dwordx4 v[98:99], v[82:85], off offset:256
	v_pk_mul_f32 v[80:81], v[152:153], v[80:81] op_sel_hi:[0,1]
	v_pk_mul_f32 v[78:79], v[152:153], v[78:79] op_sel_hi:[0,1]
	v_or_b32_e32 v82, 48, v172
	v_ashrrev_i32_e32 v83, 31, v82
	v_lshlrev_b64 v[82:83], 12, v[82:83]
	v_lshl_add_u64 v[82:83], s[82:83], 0, v[82:83]
	v_pk_mul_f32 v[76:77], v[152:153], v[76:77] op_sel_hi:[0,1]
	v_pk_mul_f32 v[74:75], v[152:153], v[74:75] op_sel_hi:[0,1]
	v_lshl_add_u64 v[82:83], v[82:83], 0, v[176:177]
	v_pk_mul_f32 v[80:81], v[160:161], v[80:81] op_sel_hi:[0,1]
	v_pk_mul_f32 v[78:79], v[160:161], v[78:79] op_sel_hi:[0,1]
	v_pk_mul_f32 v[84:85], v[160:161], v[76:77] op_sel_hi:[0,1]
; __device__ __forceinline__ unsigned cvt_pk_bf16(float lo, float hi) { unsigned r; asm volatile("v_cvt_pk_bf16_f32 %0, %1, %2" : "=v"(r) : "v"(lo), "v"(hi)); return r; }
; #define GAS __attribute__((address_space(1)))
;     __device__ __forceinline__ void operator()(const f32x4 (&acc)[2][2][4][2], const Unit& u, int wr, int wc, int fr, int fq, const float (&pre)[8]) const {
;     ...
;         for (int ai = 0; ai < 2; ++ai)
; #pragma unroll
;             for (int m = 0; m < 4; ++m) {
;                 const int row = row0 + ai * 128 + m * 16; bf16_t* rowp = O + (size_t)row * ldc + col0; float rs = 0.f;
;                 float rsc = 1.f; if (RS == 1) rsc = pre[ai * 4 + m];
; #pragma unroll
;                 for (int bj = 0; bj < 2; ++bj) {
;                     f32x4 v0 = acc[ai][bj][m][0], v1 = acc[ai][bj][m][1];
;                     if (RS == 1) { v0 = v0 * rsc; v1 = v1 * rsc; }
;                     if (RS == 2) { v0 = v0 * csc[bj][0]; v1 = v1 * csc[bj][1]; }
;                     if (ACT == 1) { const f32x2 a = gelu_pk((f32x2){v0[0], v0[1]}), b = gelu_pk((f32x2){v0[2], v0[3]}), c = gelu_pk((f32x2){v1[0], v1[1]}), d = gelu_pk((f32x2){v1[2], v1[3]});
;                         v0 = (f32x4){a.x, a.y, b.x, b.y}; v1 = (f32x4){c.x, c.y, d.x, d.y}; }
;                     v0 = v0 * sc; v1 = v1 * sc;
;                     if (STAT == 1) rs += (v0[0] * v0[0] + v0[1] * v0[1]) + (v0[2] * v0[2] + v0[3] * v0[3]) + (v1[0] * v1[0] + v1[1] * v1[1]) + (v1[2] * v1[2] + v1[3] * v1[3]);
;                     if (STAT == 2) {
; #pragma unroll
;                         for (int e = 0; e < 4; ++e) { cs[bj][0][e] += v0[e]; cq[bj][0][e] += v0[e] * v0[e]; cs[bj][1][e] += v1[e]; cq[bj][1][e] += v1[e] * v1[e]; } }
;                     u32x4 w; w.x = cvt_pk_bf16(v0[0], v0[1]); w.y = cvt_pk_bf16(v0[2], v0[3]); w.z = cvt_pk_bf16(v1[0], v1[1]); w.w = cvt_pk_bf16(v1[2], v1[3]);
;                     *(GAS u32x4*)(rowp + bj * 128) = w; }
	v_pk_mul_f32 v[76:77], v[160:161], v[74:75] op_sel_hi:[0,1]
	v_cvt_pk_bf16_f32 v74, v78, v79
	v_cvt_pk_bf16_f32 v75, v80, v81
	v_pk_mul_f32 v[68:69], v[152:153], v[68:69] op_sel_hi:[0,1]
	v_pk_mul_f32 v[66:67], v[152:153], v[66:67] op_sel_hi:[0,1]
	v_cvt_pk_bf16_f32 v76, v76, v77
	v_cvt_pk_bf16_f32 v77, v84, v85
	global_store_dwordx4 v[82:83], v[74:77], off
	v_pk_mul_f32 v[72:73], v[152:153], v[72:73] op_sel_hi:[0,1]
	v_pk_mul_f32 v[70:71], v[152:153], v[70:71] op_sel_hi:[0,1]
	v_pk_mul_f32 v[74:75], v[160:161], v[68:69] op_sel_hi:[0,1]
	v_pk_mul_f32 v[68:69], v[160:161], v[66:67] op_sel_hi:[0,1]
	v_pk_mul_f32 v[62:63], v[146:147], v[62:63] op_sel_hi:[0,1]
	v_pk_mul_f32 v[72:73], v[160:161], v[72:73] op_sel_hi:[0,1]
	v_pk_mul_f32 v[70:71], v[160:161], v[70:71] op_sel_hi:[0,1]
	v_cvt_pk_bf16_f32 v66, v70, v71
	v_cvt_pk_bf16_f32 v67, v72, v73
	v_cvt_pk_bf16_f32 v68, v68, v69
	v_cvt_pk_bf16_f32 v69, v74, v75
	v_pk_mul_f32 v[60:61], v[146:147], v[60:61] op_sel_hi:[0,1]
	v_pk_mul_f32 v[58:59], v[146:147], v[58:59] op_sel_hi:[0,1]
	v_pk_mul_f32 v[62:63], v[160:161], v[62:63] op_sel_hi:[0,1]
	s_mov_b32 s3, 0x80000
	global_store_dwordx4 v[82:83], v[66:69], off offset:256
	v_pk_mul_f32 v[64:65], v[146:147], v[64:65] op_sel_hi:[0,1]
	v_pk_mul_f32 v[64:65], v[160:161], v[64:65] op_sel_hi:[0,1]
	v_pk_mul_f32 v[68:69], v[160:161], v[60:61] op_sel_hi:[0,1]
	v_pk_mul_f32 v[60:61], v[160:161], v[58:59] op_sel_hi:[0,1]
	v_cvt_pk_bf16_f32 v58, v62, v63
	v_add_co_u32_e32 v62, vcc, s3, v170
	v_cvt_pk_bf16_f32 v59, v64, v65
	v_pk_mul_f32 v[48:49], v[146:147], v[48:49] op_sel_hi:[0,1]
	s_nop 0
	v_addc_co_u32_e32 v63, vcc, 0, v171, vcc
	v_pk_mul_f32 v[46:47], v[146:147], v[46:47] op_sel_hi:[0,1]
	s_mov_b64 s[76:77], 0x80000
	v_cvt_pk_bf16_f32 v60, v60, v61
	v_cvt_pk_bf16_f32 v61, v68, v69
	global_store_dwordx4 v[62:63], v[58:61], off
	v_pk_mul_f32 v[56:57], v[146:147], v[56:57] op_sel_hi:[0,1]
	v_pk_mul_f32 v[54:55], v[146:147], v[54:55] op_sel_hi:[0,1]
	v_pk_mul_f32 v[58:59], v[160:161], v[48:49] op_sel_hi:[0,1]
	v_pk_mul_f32 v[48:49], v[160:161], v[46:47] op_sel_hi:[0,1]
	v_lshl_add_u64 v[66:67], v[170:171], 0, s[76:77]
	v_pk_mul_f32 v[56:57], v[160:161], v[56:57] op_sel_hi:[0,1]
	v_pk_mul_f32 v[54:55], v[160:161], v[54:55] op_sel_hi:[0,1]
	v_cvt_pk_bf16_f32 v46, v54, v55
	v_cvt_pk_bf16_f32 v47, v56, v57
	v_cvt_pk_bf16_f32 v48, v48, v49
	v_cvt_pk_bf16_f32 v49, v58, v59
	global_store_dwordx4 v[66:67], v[46:49], off offset:256
	v_pk_mul_f32 v[50:51], v[142:143], v[50:51] op_sel_hi:[0,1]
	v_pk_mul_f32 v[44:45], v[142:143], v[44:45] op_sel_hi:[0,1]
	v_pk_mul_f32 v[48:49], v[142:143], v[52:53] op_sel_hi:[0,1]
	v_pk_mul_f32 v[42:43], v[142:143], v[42:43] op_sel_hi:[0,1]
	v_pk_mul_f32 v[48:49], v[160:161], v[48:49] op_sel_hi:[0,1]
	s_mov_b32 s3, 0x90000
	v_pk_mul_f32 v[50:51], v[160:161], v[50:51] op_sel_hi:[0,1]
	v_pk_mul_f32 v[52:53], v[160:161], v[44:45] op_sel_hi:[0,1]
	v_pk_mul_f32 v[44:45], v[160:161], v[42:43] op_sel_hi:[0,1]
	v_cvt_pk_bf16_f32 v42, v50, v51
	v_cvt_pk_bf16_f32 v43, v48, v49
	v_add_co_u32_e32 v48, vcc, s3, v170
	v_pk_mul_f32 v[30:31], v[142:143], v[30:31] op_sel_hi:[0,1]
	s_nop 0
	v_addc_co_u32_e32 v49, vcc, 0, v171, vcc
	v_pk_mul_f32 v[28:29], v[142:143], v[28:29] op_sel_hi:[0,1]
	s_mov_b64 s[76:77], 0x90000
	v_cvt_pk_bf16_f32 v44, v44, v45
	v_cvt_pk_bf16_f32 v45, v52, v53
	global_store_dwordx4 v[48:49], v[42:45], off
	v_pk_mul_f32 v[40:41], v[142:143], v[40:41] op_sel_hi:[0,1]
	v_pk_mul_f32 v[38:39], v[142:143], v[38:39] op_sel_hi:[0,1]
	v_pk_mul_f32 v[42:43], v[160:161], v[30:31] op_sel_hi:[0,1]
	v_pk_mul_f32 v[30:31], v[160:161], v[28:29] op_sel_hi:[0,1]
	v_lshl_add_u64 v[46:47], v[170:171], 0, s[76:77]
	v_pk_mul_f32 v[40:41], v[160:161], v[40:41] op_sel_hi:[0,1]
	v_pk_mul_f32 v[38:39], v[160:161], v[38:39] op_sel_hi:[0,1]
	v_cvt_pk_bf16_f32 v28, v38, v39
	v_cvt_pk_bf16_f32 v29, v40, v41
; __device__ __forceinline__ unsigned cvt_pk_bf16(float lo, float hi) { unsigned r; asm volatile("v_cvt_pk_bf16_f32 %0, %1, %2" : "=v"(r) : "v"(lo), "v"(hi)); return r; }
; #define GAS __attribute__((address_space(1)))
;     __device__ __forceinline__ void prefetch(const Unit& u, int wr, int fr, float (&pre)[8]) const {
; #pragma unroll
;         for (int i = 0; i < 8; ++i) pre[i] = *(const GAS float*)(rs + u.pm * 256 + wr * 64 + fr + (i >> 2) * 128 + (i & 3) * 16);
;     }
;     __device__ __forceinline__ void operator()(const f32x4 (&acc)[2][2][4][2], const Unit& u, int wr, int wc, int fr, int fq, const float (&pre)[8]) const {
;     ...
;                     u32x4 w; w.x = cvt_pk_bf16(v0[0], v0[1]); w.y = cvt_pk_bf16(v0[2], v0[3]); w.z = cvt_pk_bf16(v1[0], v1[1]); w.w = cvt_pk_bf16(v1[2], v1[3]);
;                     *(GAS u32x4*)(rowp + bj * 128) = w; }
	v_cvt_pk_bf16_f32 v30, v30, v31
	v_cvt_pk_bf16_f32 v31, v42, v43
	global_store_dwordx4 v[46:47], v[28:31], off offset:256
	v_pk_mul_f32 v[34:35], v[140:141], v[34:35] op_sel_hi:[0,1]
	v_pk_mul_f32 v[26:27], v[140:141], v[26:27] op_sel_hi:[0,1]
	v_pk_mul_f32 v[30:31], v[140:141], v[36:37] op_sel_hi:[0,1]
	v_pk_mul_f32 v[24:25], v[140:141], v[24:25] op_sel_hi:[0,1]
	v_pk_mul_f32 v[30:31], v[160:161], v[30:31] op_sel_hi:[0,1]
	s_mov_b32 s3, 0xa0000
	v_pk_mul_f32 v[34:35], v[160:161], v[34:35] op_sel_hi:[0,1]
	v_pk_mul_f32 v[36:37], v[160:161], v[26:27] op_sel_hi:[0,1]
	v_pk_mul_f32 v[26:27], v[160:161], v[24:25] op_sel_hi:[0,1]
	v_cvt_pk_bf16_f32 v24, v34, v35
	v_cvt_pk_bf16_f32 v25, v30, v31
	v_add_co_u32_e32 v30, vcc, s3, v170
	v_pk_mul_f32 v[14:15], v[140:141], v[14:15] op_sel_hi:[0,1]
	s_nop 0
	v_addc_co_u32_e32 v31, vcc, 0, v171, vcc
	v_pk_mul_f32 v[12:13], v[140:141], v[12:13] op_sel_hi:[0,1]
	s_mov_b64 s[76:77], 0xa0000
	v_cvt_pk_bf16_f32 v26, v26, v27
	v_cvt_pk_bf16_f32 v27, v36, v37
	global_store_dwordx4 v[30:31], v[24:27], off
	v_pk_mul_f32 v[22:23], v[140:141], v[22:23] op_sel_hi:[0,1]
	v_pk_mul_f32 v[20:21], v[140:141], v[20:21] op_sel_hi:[0,1]
	v_pk_mul_f32 v[24:25], v[160:161], v[14:15] op_sel_hi:[0,1]
	v_pk_mul_f32 v[14:15], v[160:161], v[12:13] op_sel_hi:[0,1]
	v_lshl_add_u64 v[28:29], v[170:171], 0, s[76:77]
	v_pk_mul_f32 v[22:23], v[160:161], v[22:23] op_sel_hi:[0,1]
	v_pk_mul_f32 v[20:21], v[160:161], v[20:21] op_sel_hi:[0,1]
	v_cvt_pk_bf16_f32 v12, v20, v21
	v_cvt_pk_bf16_f32 v13, v22, v23
	v_cvt_pk_bf16_f32 v14, v14, v15
	v_cvt_pk_bf16_f32 v15, v24, v25
	global_store_dwordx4 v[28:29], v[12:15], off offset:256
	v_pk_mul_f32 v[16:17], v[138:139], v[16:17] op_sel_hi:[0,1]
	v_pk_mul_f32 v[10:11], v[138:139], v[10:11] op_sel_hi:[0,1]
	v_pk_mul_f32 v[14:15], v[138:139], v[18:19] op_sel_hi:[0,1]
	v_pk_mul_f32 v[8:9], v[138:139], v[8:9] op_sel_hi:[0,1]
	v_pk_mul_f32 v[14:15], v[160:161], v[14:15] op_sel_hi:[0,1]
	s_mov_b32 s3, 0xb0000
	v_pk_mul_f32 v[16:17], v[160:161], v[16:17] op_sel_hi:[0,1]
	v_pk_mul_f32 v[18:19], v[160:161], v[10:11] op_sel_hi:[0,1]
	v_pk_mul_f32 v[10:11], v[160:161], v[8:9] op_sel_hi:[0,1]
	v_cvt_pk_bf16_f32 v8, v16, v17
	v_cvt_pk_bf16_f32 v9, v14, v15
	v_add_co_u32_e32 v14, vcc, s3, v170
	s_mov_b64 s[76:77], 0xb0000
	s_nop 0
	v_addc_co_u32_e32 v15, vcc, 0, v171, vcc
	v_pk_mul_f32 v[2:3], v[138:139], v[2:3] op_sel_hi:[0,1]
	v_pk_mul_f32 v[0:1], v[138:139], v[0:1] op_sel_hi:[0,1]
	v_lshl_add_u64 v[12:13], v[170:171], 0, s[76:77]
	v_cvt_pk_bf16_f32 v10, v10, v11
	v_cvt_pk_bf16_f32 v11, v18, v19
	global_store_dwordx4 v[14:15], v[8:11], off
	v_pk_mul_f32 v[6:7], v[138:139], v[6:7] op_sel_hi:[0,1]
	v_pk_mul_f32 v[4:5], v[138:139], v[4:5] op_sel_hi:[0,1]
	v_pk_mul_f32 v[8:9], v[160:161], v[2:3] op_sel_hi:[0,1]
	v_pk_mul_f32 v[2:3], v[160:161], v[0:1] op_sel_hi:[0,1]
	s_andn2_b64 vcc, exec, s[86:87]
	s_mov_b64 s[86:87], -1
	v_pk_mul_f32 v[6:7], v[160:161], v[6:7] op_sel_hi:[0,1]
	v_pk_mul_f32 v[4:5], v[160:161], v[4:5] op_sel_hi:[0,1]
	v_cvt_pk_bf16_f32 v0, v4, v5
	v_cvt_pk_bf16_f32 v1, v6, v7
	v_cvt_pk_bf16_f32 v2, v2, v3
	v_cvt_pk_bf16_f32 v3, v8, v9
	global_store_dwordx4 v[12:13], v[0:3], off offset:256
	s_cbranch_vccnz .LBB0_57
	s_lshl_b32 s76, s46, 8
	s_ashr_i32 s77, s76, 31
	v_lshl_add_u64 v[0:1], s[76:77], 2, v[144:145]
	global_load_dword v158, v[0:1], off
	global_load_dword v156, v[0:1], off offset:64
	global_load_dword v154, v[0:1], off offset:128
	global_load_dword v152, v[0:1], off offset:192
	global_load_dword v146, v[0:1], off offset:512
	global_load_dword v142, v[0:1], off offset:576
	global_load_dword v140, v[0:1], off offset:640
	global_load_dword v138, v[0:1], off offset:704
	v_readlane_b32 s72, v254, 49
	v_readlane_b32 s73, v254, 50
	s_andn2_b64 vcc, exec, s[72:73]
	s_cbranch_vccnz .LBB0_56
	s_barrier
	s_branch .LBB0_56

; #define GAS __attribute__((address_space(1)))
; __device__ __forceinline__ f32x2 gelu_pk(f32x2 v) {
;     const f32x2 av = __builtin_elementwise_abs(v), d = av * 0.2316418882f + 1.0f;
;     f32x2 t; t.x = __builtin_amdgcn_rcpf(d.x); t.y = __builtin_amdgcn_rcpf(d.y);
;     f32x2 q = t * 0.5307027145f + (-0.7265760135f); q = q * t + 0.7107068705f; q = q * t + (-0.142248368f); q = q * t + 0.127414796f; q = q * t;
;     const f32x2 s = (v * v) * (-0.72134752044f);
;     f32x2 e; e.x = __builtin_amdgcn_exp2f(s.x); e.y = __builtin_amdgcn_exp2f(s.y);
;     const f32x2 m = v * (q * e), r = v - m;
;     f32x2 o; o.x = v.x < 0.f ? m.x : r.x; o.y = v.y < 0.f ? m.y : r.y; return o;
; }
;     __device__ __forceinline__ void operator()(const f32x4 (&acc)[2][2][4][2], const Unit& u, int wr, int wc, int fr, int fq, const float (&pre)[8]) const {
;     ...
;         for (int ai = 0; ai < 2; ++ai)
; #pragma unroll
;             for (int m = 0; m < 4; ++m) {
;                 const int row = row0 + ai * 128 + m * 16; bf16_t* rowp = O + (size_t)row * ldc + col0; float rs = 0.f;
;                 float rsc = 1.f; if (RS == 1) rsc = pre[ai * 4 + m];
; #pragma unroll
;                 for (int bj = 0; bj < 2; ++bj) {
;                     f32x4 v0 = acc[ai][bj][m][0], v1 = acc[ai][bj][m][1];
;                     if (RS == 1) { v0 = v0 * rsc; v1 = v1 * rsc; }
;                     if (RS == 2) { v0 = v0 * csc[bj][0]; v1 = v1 * csc[bj][1]; }
;                     if (ACT == 1) { const f32x2 a = gelu_pk((f32x2){v0[0], v0[1]}), b = gelu_pk((f32x2){v0[2], v0[3]}), c = gelu_pk((f32x2){v1[0], v1[1]}), d = gelu_pk((f32x2){v1[2], v1[3]});
;                         v0 = (f32x4){a.x, a.y, b.x, b.y}; v1 = (f32x4){c.x, c.y, d.x, d.y}; }
;                     v0 = v0 * sc; v1 = v1 * sc;
;                     if (STAT == 1) rs += (v0[0] * v0[0] + v0[1] * v0[1]) + (v0[2] * v0[2] + v0[3] * v0[3]) + (v1[0] * v1[0] + v1[1] * v1[1]) + (v1[2] * v1[2] + v1[3] * v1[3]);
;                     if (STAT == 2) {
; #pragma unroll
;                         for (int e = 0; e < 4; ++e) { cs[bj][0][e] += v0[e]; cq[bj][0][e] += v0[e] * v0[e]; cs[bj][1][e] += v1[e]; cq[bj][1][e] += v1[e] * v1[e]; } }
;                     u32x4 w; w.x = cvt_pk_bf16(v0[0], v0[1]); w.y = cvt_pk_bf16(v0[2], v0[3]); w.z = cvt_pk_bf16(v1[0], v1[1]); w.w = cvt_pk_bf16(v1[2], v1[3]);
;                     *(GAS u32x4*)(rowp + bj * 128) = w; }
.LBB0_121:
	v_lshl_add_u32 v160, s44, 8, v33
	v_lshl_or_b32 v150, s4, 8, v147
	v_ashrrev_i32_e32 v161, 31, v160
	v_ashrrev_i32_e32 v151, 31, v150
	v_lshlrev_b64 v[170:171], 11, v[160:161]
	v_lshl_add_u64 v[174:175], s[40:41], 0, v[170:171]
	v_lshlrev_b64 v[170:171], 1, v[150:151]
	v_pk_mul_f32 v[126:127], v[172:173], v[126:127] op_sel_hi:[0,1]
	v_lshl_add_u64 v[150:151], v[174:175], 0, v[170:171]
	v_pk_mul_f32 v[174:175], v[172:173], v[122:123] op_sel_hi:[0,1]
	v_and_b32_e32 v123, 0x7fffffff, v127
	v_and_b32_e32 v122, 0x7fffffff, v126
	v_pk_fma_f32 v[122:123], v[122:123], s[28:29], 1.0 op_sel_hi:[1,0,0]
	s_mov_b32 s4, 0xbf3a00e3
	v_rcp_f32_e32 v176, v122
	v_rcp_f32_e32 v177, v123
	v_mov_b64_e32 v[122:123], s[4:5]
	v_pk_mul_f32 v[180:181], v[126:127], v[126:127]
	v_pk_mul_f32 v[128:129], v[172:173], v[128:129] op_sel_hi:[0,1]
	v_pk_fma_f32 v[178:179], v[176:177], s[30:31], v[122:123] op_sel_hi:[1,0,0]
	v_pk_mul_f32 v[180:181], v[180:181], s[58:59] op_sel_hi:[1,0]
	v_pk_fma_f32 v[178:179], v[176:177], v[178:179], s[52:53] op_sel_hi:[1,1,0]
	v_exp_f32_e32 v180, v180
	v_exp_f32_e32 v181, v181
	v_pk_fma_f32 v[178:179], v[176:177], v[178:179], s[54:55] op_sel_hi:[1,1,0]
	v_cmp_gt_f32_e32 vcc, 0, v126
	v_pk_fma_f32 v[178:179], v[176:177], v[178:179], s[56:57] op_sel_hi:[1,1,0]
	v_pk_mul_f32 v[124:125], v[172:173], v[124:125] op_sel_hi:[0,1]
	v_pk_mul_f32 v[176:177], v[176:177], v[178:179]
	v_pk_mul_f32 v[178:179], v[128:129], v[128:129]
	v_pk_mul_f32 v[176:177], v[180:181], v[176:177]
	s_mov_b64 s[4:5], 0x40000
	v_pk_mul_f32 v[180:181], v[126:127], v[176:177]
	v_pk_fma_f32 v[176:177], v[126:127], v[176:177], v[126:127] neg_lo:[1,0,0] neg_hi:[1,0,0]
	v_and_b32_e32 v126, 0x7fffffff, v128
	v_cndmask_b32_e32 v153, v176, v180, vcc
	v_cmp_gt_f32_e32 vcc, 0, v127
	v_and_b32_e32 v127, 0x7fffffff, v129
	v_pk_fma_f32 v[126:127], v[126:127], s[28:29], 1.0 op_sel_hi:[1,0,0]
	v_cndmask_b32_e32 v155, v177, v181, vcc
	v_rcp_f32_e32 v126, v126
	v_rcp_f32_e32 v127, v127
	v_cmp_gt_f32_e32 vcc, 0, v128
	v_pk_mul_f32 v[78:79], v[154:155], v[78:79] op_sel_hi:[0,1]
	v_pk_mul_f32 v[80:81], v[154:155], v[80:81] op_sel_hi:[0,1]
	v_pk_fma_f32 v[176:177], v[126:127], s[30:31], v[122:123] op_sel_hi:[1,0,0]
	v_pk_mul_f32 v[74:75], v[154:155], v[74:75] op_sel_hi:[0,1]
	v_pk_fma_f32 v[176:177], v[126:127], v[176:177], s[52:53] op_sel_hi:[1,1,0]
	v_pk_mul_f32 v[76:77], v[154:155], v[76:77] op_sel_hi:[0,1]
	v_pk_fma_f32 v[176:177], v[126:127], v[176:177], s[54:55] op_sel_hi:[1,1,0]
	v_pk_mul_f32 v[70:71], v[154:155], v[70:71] op_sel_hi:[0,1]
	v_pk_fma_f32 v[176:177], v[126:127], v[176:177], s[56:57] op_sel_hi:[1,1,0]
	v_pk_mul_f32 v[72:73], v[154:155], v[72:73] op_sel_hi:[0,1]
	v_pk_mul_f32 v[126:127], v[126:127], v[176:177]
	v_pk_mul_f32 v[176:177], v[178:179], s[58:59] op_sel_hi:[1,0]
	v_pk_mul_f32 v[66:67], v[154:155], v[66:67] op_sel_hi:[0,1]
	v_exp_f32_e32 v176, v176
	v_exp_f32_e32 v177, v177
	v_pk_mul_f32 v[68:69], v[154:155], v[68:69] op_sel_hi:[0,1]
	v_pk_mul_f32 v[62:63], v[152:153], v[62:63] op_sel_hi:[0,1]
	v_pk_mul_f32 v[64:65], v[152:153], v[64:65] op_sel_hi:[0,1]
	v_pk_mul_f32 v[126:127], v[176:177], v[126:127]
	v_pk_mul_f32 v[58:59], v[152:153], v[58:59] op_sel_hi:[0,1]
	v_pk_mul_f32 v[176:177], v[128:129], v[126:127]
	v_pk_fma_f32 v[126:127], v[128:129], v[126:127], v[128:129] neg_lo:[1,0,0] neg_hi:[1,0,0]
	v_pk_mul_f32 v[60:61], v[152:153], v[60:61] op_sel_hi:[0,1]
	v_cndmask_b32_e32 v157, v126, v176, vcc
	v_cmp_gt_f32_e32 vcc, 0, v129
	v_and_b32_e32 v126, 0x7fffffff, v174
	v_pk_mul_f32 v[94:95], v[156:157], v[94:95] op_sel_hi:[0,1]
	v_cndmask_b32_e32 v159, v127, v177, vcc
	v_and_b32_e32 v127, 0x7fffffff, v175
	v_pk_fma_f32 v[126:127], v[126:127], s[28:29], 1.0 op_sel_hi:[1,0,0]
	v_pk_mul_f32 v[176:177], v[174:175], v[174:175]
	v_rcp_f32_e32 v126, v126
	v_rcp_f32_e32 v127, v127
	v_pk_mul_f32 v[176:177], v[176:177], s[58:59] op_sel_hi:[1,0]
	v_cmp_gt_f32_e32 vcc, 0, v174
	v_exp_f32_e32 v176, v176
	v_pk_fma_f32 v[128:129], v[126:127], s[30:31], v[122:123] op_sel_hi:[1,0,0]
	v_exp_f32_e32 v177, v177
	v_pk_fma_f32 v[128:129], v[126:127], v[128:129], s[52:53] op_sel_hi:[1,1,0]
	v_pk_mul_f32 v[110:111], v[158:159], v[110:111] op_sel_hi:[0,1]
	v_pk_fma_f32 v[128:129], v[126:127], v[128:129], s[54:55] op_sel_hi:[1,1,0]
	v_pk_mul_f32 v[112:113], v[158:159], v[112:113] op_sel_hi:[0,1]
	v_pk_fma_f32 v[128:129], v[126:127], v[128:129], s[56:57] op_sel_hi:[1,1,0]
	v_pk_mul_f32 v[106:107], v[158:159], v[106:107] op_sel_hi:[0,1]
	v_pk_mul_f32 v[126:127], v[126:127], v[128:129]
	v_pk_mul_f32 v[128:129], v[124:125], v[124:125]
	v_pk_mul_f32 v[126:127], v[176:177], v[126:127]
	v_pk_mul_f32 v[128:129], v[128:129], s[58:59] op_sel_hi:[1,0]
	v_pk_mul_f32 v[176:177], v[174:175], v[126:127]
	v_pk_fma_f32 v[126:127], v[174:175], v[126:127], v[174:175] neg_lo:[1,0,0] neg_hi:[1,0,0]
	v_exp_f32_e32 v128, v128
	v_cndmask_b32_e32 v161, v126, v176, vcc
	v_cmp_gt_f32_e32 vcc, 0, v175
	v_and_b32_e32 v126, 0x7fffffff, v124
	v_exp_f32_e32 v129, v129
	v_cndmask_b32_e32 v173, v127, v177, vcc
	v_and_b32_e32 v127, 0x7fffffff, v125
	v_pk_fma_f32 v[126:127], v[126:127], s[28:29], 1.0 op_sel_hi:[1,0,0]
	v_cmp_gt_f32_e32 vcc, 0, v124
	v_rcp_f32_e32 v126, v126
	v_rcp_f32_e32 v127, v127
	v_pk_mul_f32 v[118:119], v[172:173], v[118:119] op_sel_hi:[0,1]
	v_pk_mul_f32 v[120:121], v[172:173], v[120:121] op_sel_hi:[0,1]
	v_pk_mul_f32 v[114:115], v[172:173], v[114:115] op_sel_hi:[0,1]
	v_pk_fma_f32 v[174:175], v[126:127], s[30:31], v[122:123] op_sel_hi:[1,0,0]
	v_pk_mul_f32 v[116:117], v[172:173], v[116:117] op_sel_hi:[0,1]
	v_pk_fma_f32 v[174:175], v[126:127], v[174:175], s[52:53] op_sel_hi:[1,1,0]
; __device__ __forceinline__ unsigned cvt_pk_bf16(float lo, float hi) { unsigned r; asm volatile("v_cvt_pk_bf16_f32 %0, %1, %2" : "=v"(r) : "v"(lo), "v"(hi)); return r; }
; #define GAS __attribute__((address_space(1)))
; __device__ __forceinline__ f32x2 gelu_pk(f32x2 v) {
;     const f32x2 av = __builtin_elementwise_abs(v), d = av * 0.2316418882f + 1.0f;
;     f32x2 t; t.x = __builtin_amdgcn_rcpf(d.x); t.y = __builtin_amdgcn_rcpf(d.y);
;     f32x2 q = t * 0.5307027145f + (-0.7265760135f); q = q * t + 0.7107068705f; q = q * t + (-0.142248368f); q = q * t + 0.127414796f; q = q * t;
;     const f32x2 s = (v * v) * (-0.72134752044f);
;     f32x2 e; e.x = __builtin_amdgcn_exp2f(s.x); e.y = __builtin_amdgcn_exp2f(s.y);
;     const f32x2 m = v * (q * e), r = v - m;
;     f32x2 o; o.x = v.x < 0.f ? m.x : r.x; o.y = v.y < 0.f ? m.y : r.y; return o;
; }
;     __device__ __forceinline__ void operator()(const f32x4 (&acc)[2][2][4][2], const Unit& u, int wr, int wc, int fr, int fq, const float (&pre)[8]) const {
;     ...
;                     f32x4 v0 = acc[ai][bj][m][0], v1 = acc[ai][bj][m][1];
;                     if (RS == 1) { v0 = v0 * rsc; v1 = v1 * rsc; }
;                     if (RS == 2) { v0 = v0 * csc[bj][0]; v1 = v1 * csc[bj][1]; }
;                     if (ACT == 1) { const f32x2 a = gelu_pk((f32x2){v0[0], v0[1]}), b = gelu_pk((f32x2){v0[2], v0[3]}), c = gelu_pk((f32x2){v1[0], v1[1]}), d = gelu_pk((f32x2){v1[2], v1[3]});
;                         v0 = (f32x4){a.x, a.y, b.x, b.y}; v1 = (f32x4){c.x, c.y, d.x, d.y}; }
;                     v0 = v0 * sc; v1 = v1 * sc;
;                     if (STAT == 1) rs += (v0[0] * v0[0] + v0[1] * v0[1]) + (v0[2] * v0[2] + v0[3] * v0[3]) + (v1[0] * v1[0] + v1[1] * v1[1]) + (v1[2] * v1[2] + v1[3] * v1[3]);
;                     if (STAT == 2) {
; #pragma unroll
;                         for (int e = 0; e < 4; ++e) { cs[bj][0][e] += v0[e]; cq[bj][0][e] += v0[e] * v0[e]; cs[bj][1][e] += v1[e]; cq[bj][1][e] += v1[e] * v1[e]; } }
;                     u32x4 w; w.x = cvt_pk_bf16(v0[0], v0[1]); w.y = cvt_pk_bf16(v0[2], v0[3]); w.z = cvt_pk_bf16(v1[0], v1[1]); w.w = cvt_pk_bf16(v1[2], v1[3]);
;                     *(GAS u32x4*)(rowp + bj * 128) = w; }
	v_pk_mul_f32 v[108:109], v[158:159], v[108:109] op_sel_hi:[0,1]
	v_pk_fma_f32 v[174:175], v[126:127], v[174:175], s[54:55] op_sel_hi:[1,1,0]
	v_pk_mul_f32 v[102:103], v[158:159], v[102:103] op_sel_hi:[0,1]
	v_pk_fma_f32 v[174:175], v[126:127], v[174:175], s[56:57] op_sel_hi:[1,1,0]
	v_pk_mul_f32 v[104:105], v[158:159], v[104:105] op_sel_hi:[0,1]
	v_pk_mul_f32 v[126:127], v[126:127], v[174:175]
	v_pk_mul_f32 v[98:99], v[158:159], v[98:99] op_sel_hi:[0,1]
	v_pk_mul_f32 v[126:127], v[128:129], v[126:127]
	v_pk_mul_f32 v[100:101], v[158:159], v[100:101] op_sel_hi:[0,1]
	v_pk_mul_f32 v[128:129], v[124:125], v[126:127]
	v_pk_fma_f32 v[126:127], v[124:125], v[126:127], v[124:125] neg_lo:[1,0,0] neg_hi:[1,0,0]
	v_cvt_pk_bf16_f32 v124, v153, v155
	v_pk_mul_f32 v[96:97], v[156:157], v[96:97] op_sel_hi:[0,1]
	v_cndmask_b32_e32 v128, v126, v128, vcc
	v_cmp_gt_f32_e32 vcc, 0, v125
	v_cvt_pk_bf16_f32 v125, v157, v159
	v_cvt_pk_bf16_f32 v126, v161, v173
	v_pk_mul_f32 v[90:91], v[156:157], v[90:91] op_sel_hi:[0,1]
	v_pk_mul_f32 v[92:93], v[156:157], v[92:93] op_sel_hi:[0,1]
	v_cndmask_b32_e32 v127, v127, v129, vcc
	v_cvt_pk_bf16_f32 v127, v128, v127
	global_store_dwordx4 v[150:151], v[124:127], off
	v_pk_mul_f32 v[128:129], v[118:119], v[118:119]
	v_cmp_gt_f32_e32 vcc, 0, v118
	v_and_b32_e32 v125, 0x7fffffff, v119
	v_and_b32_e32 v124, 0x7fffffff, v118
	v_pk_fma_f32 v[124:125], v[124:125], s[28:29], 1.0 op_sel_hi:[1,0,0]
	v_pk_mul_f32 v[128:129], v[128:129], s[58:59] op_sel_hi:[1,0]
	v_rcp_f32_e32 v124, v124
	v_rcp_f32_e32 v125, v125
	v_exp_f32_e32 v128, v128
	v_exp_f32_e32 v129, v129
	v_pk_mul_f32 v[86:87], v[156:157], v[86:87] op_sel_hi:[0,1]
	v_pk_fma_f32 v[126:127], v[124:125], s[30:31], v[122:123] op_sel_hi:[1,0,0]
	v_pk_mul_f32 v[88:89], v[156:157], v[88:89] op_sel_hi:[0,1]
	v_pk_fma_f32 v[126:127], v[124:125], v[126:127], s[52:53] op_sel_hi:[1,1,0]
	v_pk_mul_f32 v[82:83], v[156:157], v[82:83] op_sel_hi:[0,1]
	v_pk_fma_f32 v[126:127], v[124:125], v[126:127], s[54:55] op_sel_hi:[1,1,0]
	v_pk_mul_f32 v[84:85], v[156:157], v[84:85] op_sel_hi:[0,1]
	v_pk_fma_f32 v[126:127], v[124:125], v[126:127], s[56:57] op_sel_hi:[1,1,0]
	v_pk_mul_f32 v[54:55], v[152:153], v[54:55] op_sel_hi:[0,1]
	v_pk_mul_f32 v[124:125], v[124:125], v[126:127]
	v_pk_mul_f32 v[126:127], v[120:121], v[120:121]
	v_pk_mul_f32 v[124:125], v[128:129], v[124:125]
	v_pk_mul_f32 v[56:57], v[152:153], v[56:57] op_sel_hi:[0,1]
	v_pk_mul_f32 v[128:129], v[118:119], v[124:125]
	v_pk_fma_f32 v[124:125], v[118:119], v[124:125], v[118:119] neg_lo:[1,0,0] neg_hi:[1,0,0]
	v_and_b32_e32 v118, 0x7fffffff, v120
	v_cndmask_b32_e32 v128, v124, v128, vcc
	v_cmp_gt_f32_e32 vcc, 0, v119
	v_and_b32_e32 v119, 0x7fffffff, v121
	v_pk_fma_f32 v[118:119], v[118:119], s[28:29], 1.0 op_sel_hi:[1,0,0]
	v_cndmask_b32_e32 v129, v125, v129, vcc
	v_rcp_f32_e32 v118, v118
	v_rcp_f32_e32 v119, v119
	v_cmp_gt_f32_e32 vcc, 0, v120
	v_pk_mul_f32 v[50:51], v[152:153], v[50:51] op_sel_hi:[0,1]
	v_pk_mul_f32 v[52:53], v[152:153], v[52:53] op_sel_hi:[0,1]
	v_pk_fma_f32 v[124:125], v[118:119], s[30:31], v[122:123] op_sel_hi:[1,0,0]
	v_pk_mul_f32 v[46:47], v[148:149], v[46:47] op_sel_hi:[0,1]
	v_pk_fma_f32 v[124:125], v[118:119], v[124:125], s[52:53] op_sel_hi:[1,1,0]
	v_pk_mul_f32 v[48:49], v[148:149], v[48:49] op_sel_hi:[0,1]
	v_pk_fma_f32 v[124:125], v[118:119], v[124:125], s[54:55] op_sel_hi:[1,1,0]
	v_pk_mul_f32 v[42:43], v[148:149], v[42:43] op_sel_hi:[0,1]
	v_pk_fma_f32 v[124:125], v[118:119], v[124:125], s[56:57] op_sel_hi:[1,1,0]
	v_pk_mul_f32 v[44:45], v[148:149], v[44:45] op_sel_hi:[0,1]
	v_pk_mul_f32 v[118:119], v[118:119], v[124:125]
	v_pk_mul_f32 v[124:125], v[126:127], s[58:59] op_sel_hi:[1,0]
	v_pk_mul_f32 v[38:39], v[148:149], v[38:39] op_sel_hi:[0,1]
	v_exp_f32_e32 v124, v124
	v_exp_f32_e32 v125, v125
	v_pk_mul_f32 v[40:41], v[148:149], v[40:41] op_sel_hi:[0,1]
	v_pk_mul_f32 v[34:35], v[148:149], v[34:35] op_sel_hi:[0,1]
	v_pk_mul_f32 v[36:37], v[148:149], v[36:37] op_sel_hi:[0,1]
	v_pk_mul_f32 v[118:119], v[124:125], v[118:119]
	v_pk_mul_f32 v[28:29], v[146:147], v[28:29] op_sel_hi:[0,1]
	v_pk_mul_f32 v[124:125], v[120:121], v[118:119]
	v_pk_fma_f32 v[118:119], v[120:121], v[118:119], v[120:121] neg_lo:[1,0,0] neg_hi:[1,0,0]
	v_pk_mul_f32 v[30:31], v[146:147], v[30:31] op_sel_hi:[0,1]
	v_cndmask_b32_e32 v126, v118, v124, vcc
	v_cmp_gt_f32_e32 vcc, 0, v121
	v_and_b32_e32 v118, 0x7fffffff, v114
	v_pk_mul_f32 v[24:25], v[146:147], v[24:25] op_sel_hi:[0,1]
	v_cndmask_b32_e32 v127, v119, v125, vcc
	v_and_b32_e32 v119, 0x7fffffff, v115
	v_pk_fma_f32 v[118:119], v[118:119], s[28:29], 1.0 op_sel_hi:[1,0,0]
	v_pk_mul_f32 v[124:125], v[114:115], v[114:115]
	v_rcp_f32_e32 v118, v118
	v_rcp_f32_e32 v119, v119
	v_pk_mul_f32 v[124:125], v[124:125], s[58:59] op_sel_hi:[1,0]
	v_cmp_gt_f32_e32 vcc, 0, v114
	v_exp_f32_e32 v124, v124
	v_pk_fma_f32 v[120:121], v[118:119], s[30:31], v[122:123] op_sel_hi:[1,0,0]
	v_exp_f32_e32 v125, v125
	v_pk_fma_f32 v[120:121], v[118:119], v[120:121], s[52:53] op_sel_hi:[1,1,0]
	v_pk_mul_f32 v[26:27], v[146:147], v[26:27] op_sel_hi:[0,1]
	v_pk_fma_f32 v[120:121], v[118:119], v[120:121], s[54:55] op_sel_hi:[1,1,0]
	v_pk_mul_f32 v[20:21], v[146:147], v[20:21] op_sel_hi:[0,1]
	v_pk_fma_f32 v[120:121], v[118:119], v[120:121], s[56:57] op_sel_hi:[1,1,0]
	v_pk_mul_f32 v[22:23], v[146:147], v[22:23] op_sel_hi:[0,1]
	v_pk_mul_f32 v[118:119], v[118:119], v[120:121]
	v_pk_mul_f32 v[120:121], v[116:117], v[116:117]
	v_pk_mul_f32 v[118:119], v[124:125], v[118:119]
	v_pk_mul_f32 v[16:17], v[146:147], v[16:17] op_sel_hi:[0,1]
	v_pk_mul_f32 v[124:125], v[114:115], v[118:119]
; __device__ __forceinline__ unsigned cvt_pk_bf16(float lo, float hi) { unsigned r; asm volatile("v_cvt_pk_bf16_f32 %0, %1, %2" : "=v"(r) : "v"(lo), "v"(hi)); return r; }
; #define GAS __attribute__((address_space(1)))
; __device__ __forceinline__ f32x2 gelu_pk(f32x2 v) {
;     const f32x2 av = __builtin_elementwise_abs(v), d = av * 0.2316418882f + 1.0f;
;     f32x2 t; t.x = __builtin_amdgcn_rcpf(d.x); t.y = __builtin_amdgcn_rcpf(d.y);
;     f32x2 q = t * 0.5307027145f + (-0.7265760135f); q = q * t + 0.7107068705f; q = q * t + (-0.142248368f); q = q * t + 0.127414796f; q = q * t;
;     const f32x2 s = (v * v) * (-0.72134752044f);
;     f32x2 e; e.x = __builtin_amdgcn_exp2f(s.x); e.y = __builtin_amdgcn_exp2f(s.y);
;     const f32x2 m = v * (q * e), r = v - m;
;     f32x2 o; o.x = v.x < 0.f ? m.x : r.x; o.y = v.y < 0.f ? m.y : r.y; return o;
; }
;     __device__ __forceinline__ void operator()(const f32x4 (&acc)[2][2][4][2], const Unit& u, int wr, int wc, int fr, int fq, const float (&pre)[8]) const {
;     ...
;                     f32x4 v0 = acc[ai][bj][m][0], v1 = acc[ai][bj][m][1];
;                     if (RS == 1) { v0 = v0 * rsc; v1 = v1 * rsc; }
;                     if (RS == 2) { v0 = v0 * csc[bj][0]; v1 = v1 * csc[bj][1]; }
;                     if (ACT == 1) { const f32x2 a = gelu_pk((f32x2){v0[0], v0[1]}), b = gelu_pk((f32x2){v0[2], v0[3]}), c = gelu_pk((f32x2){v1[0], v1[1]}), d = gelu_pk((f32x2){v1[2], v1[3]});
;                         v0 = (f32x4){a.x, a.y, b.x, b.y}; v1 = (f32x4){c.x, c.y, d.x, d.y}; }
;                     v0 = v0 * sc; v1 = v1 * sc;
;                     if (STAT == 1) rs += (v0[0] * v0[0] + v0[1] * v0[1]) + (v0[2] * v0[2] + v0[3] * v0[3]) + (v1[0] * v1[0] + v1[1] * v1[1]) + (v1[2] * v1[2] + v1[3] * v1[3]);
;                     if (STAT == 2) {
; #pragma unroll
;                         for (int e = 0; e < 4; ++e) { cs[bj][0][e] += v0[e]; cq[bj][0][e] += v0[e] * v0[e]; cs[bj][1][e] += v1[e]; cq[bj][1][e] += v1[e] * v1[e]; } }
;                     u32x4 w; w.x = cvt_pk_bf16(v0[0], v0[1]); w.y = cvt_pk_bf16(v0[2], v0[3]); w.z = cvt_pk_bf16(v1[0], v1[1]); w.w = cvt_pk_bf16(v1[2], v1[3]);
;                     *(GAS u32x4*)(rowp + bj * 128) = w; }
	v_pk_fma_f32 v[118:119], v[114:115], v[118:119], v[114:115] neg_lo:[1,0,0] neg_hi:[1,0,0]
	v_and_b32_e32 v114, 0x7fffffff, v116
	v_cndmask_b32_e32 v124, v118, v124, vcc
	v_cmp_gt_f32_e32 vcc, 0, v115
	v_and_b32_e32 v115, 0x7fffffff, v117
	v_pk_fma_f32 v[114:115], v[114:115], s[28:29], 1.0 op_sel_hi:[1,0,0]
	v_cndmask_b32_e32 v125, v119, v125, vcc
	v_rcp_f32_e32 v114, v114
	v_rcp_f32_e32 v115, v115
	v_cmp_gt_f32_e32 vcc, 0, v116
	v_pk_mul_f32 v[18:19], v[146:147], v[18:19] op_sel_hi:[0,1]
	v_pk_mul_f32 v[12:13], v[144:145], v[12:13] op_sel_hi:[0,1]
	v_pk_fma_f32 v[118:119], v[114:115], s[30:31], v[122:123] op_sel_hi:[1,0,0]
	v_pk_mul_f32 v[14:15], v[144:145], v[14:15] op_sel_hi:[0,1]
	v_pk_fma_f32 v[118:119], v[114:115], v[118:119], s[52:53] op_sel_hi:[1,1,0]
	v_pk_mul_f32 v[8:9], v[144:145], v[8:9] op_sel_hi:[0,1]
	v_pk_fma_f32 v[118:119], v[114:115], v[118:119], s[54:55] op_sel_hi:[1,1,0]
	v_pk_mul_f32 v[10:11], v[144:145], v[10:11] op_sel_hi:[0,1]
	v_pk_fma_f32 v[118:119], v[114:115], v[118:119], s[56:57] op_sel_hi:[1,1,0]
	v_pk_mul_f32 v[4:5], v[144:145], v[4:5] op_sel_hi:[0,1]
	v_pk_mul_f32 v[114:115], v[114:115], v[118:119]
	v_pk_mul_f32 v[118:119], v[120:121], s[58:59] op_sel_hi:[1,0]
	v_pk_mul_f32 v[120:121], v[110:111], v[110:111]
	v_exp_f32_e32 v118, v118
	v_exp_f32_e32 v119, v119
	v_pk_mul_f32 v[120:121], v[120:121], s[58:59] op_sel_hi:[1,0]
	v_pk_mul_f32 v[6:7], v[144:145], v[6:7] op_sel_hi:[0,1]
	v_exp_f32_e32 v120, v120
	v_pk_mul_f32 v[114:115], v[118:119], v[114:115]
	v_exp_f32_e32 v121, v121
	v_pk_mul_f32 v[118:119], v[116:117], v[114:115]
	v_pk_fma_f32 v[114:115], v[116:117], v[114:115], v[116:117] neg_lo:[1,0,0] neg_hi:[1,0,0]
	v_pk_mul_f32 v[0:1], v[144:145], v[0:1] op_sel_hi:[0,1]
	v_cndmask_b32_e32 v118, v114, v118, vcc
	v_cmp_gt_f32_e32 vcc, 0, v117
	v_cvt_pk_bf16_f32 v114, v128, v129
	v_pk_mul_f32 v[2:3], v[144:145], v[2:3] op_sel_hi:[0,1]
	s_mov_b64 s[44:45], -1
	v_cndmask_b32_e32 v117, v115, v119, vcc
	v_cvt_pk_bf16_f32 v115, v126, v127
	v_cvt_pk_bf16_f32 v116, v124, v125
	v_cvt_pk_bf16_f32 v117, v118, v117
	global_store_dwordx4 v[150:151], v[114:117], off offset:256
	v_cmp_gt_f32_e32 vcc, 0, v110
	s_nop 0
	v_and_b32_e32 v117, 0x7fffffff, v111
	v_and_b32_e32 v116, 0x7fffffff, v110
	v_pk_fma_f32 v[116:117], v[116:117], s[28:29], 1.0 op_sel_hi:[1,0,0]
	v_or_b32_e32 v114, 16, v160
	v_rcp_f32_e32 v116, v116
	v_rcp_f32_e32 v117, v117
	v_ashrrev_i32_e32 v115, 31, v114
	v_lshlrev_b64 v[114:115], 11, v[114:115]
	v_lshl_add_u64 v[114:115], s[40:41], 0, v[114:115]
	v_pk_fma_f32 v[118:119], v[116:117], s[30:31], v[122:123] op_sel_hi:[1,0,0]
	v_lshl_add_u64 v[114:115], v[114:115], 0, v[170:171]
	v_pk_fma_f32 v[118:119], v[116:117], v[118:119], s[52:53] op_sel_hi:[1,1,0]
	s_nop 0
	v_pk_fma_f32 v[118:119], v[116:117], v[118:119], s[54:55] op_sel_hi:[1,1,0]
	s_nop 0
	v_pk_fma_f32 v[118:119], v[116:117], v[118:119], s[56:57] op_sel_hi:[1,1,0]
	s_nop 0
	v_pk_mul_f32 v[116:117], v[116:117], v[118:119]
	v_pk_mul_f32 v[118:119], v[112:113], v[112:113]
	v_pk_mul_f32 v[116:117], v[120:121], v[116:117]
	s_nop 0
	v_pk_mul_f32 v[120:121], v[110:111], v[116:117]
	v_pk_fma_f32 v[116:117], v[110:111], v[116:117], v[110:111] neg_lo:[1,0,0] neg_hi:[1,0,0]
	v_and_b32_e32 v110, 0x7fffffff, v112
	v_cndmask_b32_e32 v120, v116, v120, vcc
	v_cmp_gt_f32_e32 vcc, 0, v111
	v_and_b32_e32 v111, 0x7fffffff, v113
	v_pk_fma_f32 v[110:111], v[110:111], s[28:29], 1.0 op_sel_hi:[1,0,0]
	v_cndmask_b32_e32 v121, v117, v121, vcc
	v_rcp_f32_e32 v110, v110
	v_rcp_f32_e32 v111, v111
	v_cmp_gt_f32_e32 vcc, 0, v112
	v_pk_fma_f32 v[116:117], v[110:111], s[30:31], v[122:123] op_sel_hi:[1,0,0]
	s_nop 0
	v_pk_fma_f32 v[116:117], v[110:111], v[116:117], s[52:53] op_sel_hi:[1,1,0]
	s_nop 0
	v_pk_fma_f32 v[116:117], v[110:111], v[116:117], s[54:55] op_sel_hi:[1,1,0]
	s_nop 0
	v_pk_fma_f32 v[116:117], v[110:111], v[116:117], s[56:57] op_sel_hi:[1,1,0]
	s_nop 0
	v_pk_mul_f32 v[110:111], v[110:111], v[116:117]
	v_pk_mul_f32 v[116:117], v[118:119], s[58:59] op_sel_hi:[1,0]
	s_nop 0
	v_exp_f32_e32 v116, v116
	v_exp_f32_e32 v117, v117
	s_nop 0
	v_pk_mul_f32 v[110:111], v[116:117], v[110:111]
	s_nop 0
	v_pk_mul_f32 v[116:117], v[112:113], v[110:111]
	v_pk_fma_f32 v[110:111], v[112:113], v[110:111], v[112:113] neg_lo:[1,0,0] neg_hi:[1,0,0]
	s_nop 0
	v_cndmask_b32_e32 v118, v110, v116, vcc
	v_cmp_gt_f32_e32 vcc, 0, v113
	v_and_b32_e32 v110, 0x7fffffff, v106
	s_nop 0
	v_cndmask_b32_e32 v119, v111, v117, vcc
	v_and_b32_e32 v111, 0x7fffffff, v107
	v_pk_fma_f32 v[110:111], v[110:111], s[28:29], 1.0 op_sel_hi:[1,0,0]
	v_pk_mul_f32 v[116:117], v[106:107], v[106:107]
	v_rcp_f32_e32 v110, v110
	v_rcp_f32_e32 v111, v111
	v_pk_mul_f32 v[116:117], v[116:117], s[58:59] op_sel_hi:[1,0]
	v_cmp_gt_f32_e32 vcc, 0, v106
	v_exp_f32_e32 v116, v116
	v_pk_fma_f32 v[112:113], v[110:111], s[30:31], v[122:123] op_sel_hi:[1,0,0]
	v_exp_f32_e32 v117, v117
	v_pk_fma_f32 v[112:113], v[110:111], v[112:113], s[52:53] op_sel_hi:[1,1,0]
	s_nop 0
	v_pk_fma_f32 v[112:113], v[110:111], v[112:113], s[54:55] op_sel_hi:[1,1,0]
	s_nop 0
	v_pk_fma_f32 v[112:113], v[110:111], v[112:113], s[56:57] op_sel_hi:[1,1,0]
	s_nop 0
	v_pk_mul_f32 v[110:111], v[110:111], v[112:113]
	v_pk_mul_f32 v[112:113], v[108:109], v[108:109]
	v_pk_mul_f32 v[110:111], v[116:117], v[110:111]
	s_nop 0
	v_pk_mul_f32 v[116:117], v[106:107], v[110:111]
	v_pk_fma_f32 v[110:111], v[106:107], v[110:111], v[106:107] neg_lo:[1,0,0] neg_hi:[1,0,0]
	v_and_b32_e32 v106, 0x7fffffff, v108
	v_cndmask_b32_e32 v116, v110, v116, vcc
	v_cmp_gt_f32_e32 vcc, 0, v107
	v_and_b32_e32 v107, 0x7fffffff, v109
	v_pk_fma_f32 v[106:107], v[106:107], s[28:29], 1.0 op_sel_hi:[1,0,0]
; __device__ __forceinline__ unsigned cvt_pk_bf16(float lo, float hi) { unsigned r; asm volatile("v_cvt_pk_bf16_f32 %0, %1, %2" : "=v"(r) : "v"(lo), "v"(hi)); return r; }
; #define GAS __attribute__((address_space(1)))
; __device__ __forceinline__ f32x2 gelu_pk(f32x2 v) {
;     const f32x2 av = __builtin_elementwise_abs(v), d = av * 0.2316418882f + 1.0f;
;     f32x2 t; t.x = __builtin_amdgcn_rcpf(d.x); t.y = __builtin_amdgcn_rcpf(d.y);
;     f32x2 q = t * 0.5307027145f + (-0.7265760135f); q = q * t + 0.7107068705f; q = q * t + (-0.142248368f); q = q * t + 0.127414796f; q = q * t;
;     const f32x2 s = (v * v) * (-0.72134752044f);
;     f32x2 e; e.x = __builtin_amdgcn_exp2f(s.x); e.y = __builtin_amdgcn_exp2f(s.y);
;     const f32x2 m = v * (q * e), r = v - m;
;     f32x2 o; o.x = v.x < 0.f ? m.x : r.x; o.y = v.y < 0.f ? m.y : r.y; return o;
; }
;     __device__ __forceinline__ void operator()(const f32x4 (&acc)[2][2][4][2], const Unit& u, int wr, int wc, int fr, int fq, const float (&pre)[8]) const {
;     ...
;                     f32x4 v0 = acc[ai][bj][m][0], v1 = acc[ai][bj][m][1];
;                     if (RS == 1) { v0 = v0 * rsc; v1 = v1 * rsc; }
;                     if (RS == 2) { v0 = v0 * csc[bj][0]; v1 = v1 * csc[bj][1]; }
;                     if (ACT == 1) { const f32x2 a = gelu_pk((f32x2){v0[0], v0[1]}), b = gelu_pk((f32x2){v0[2], v0[3]}), c = gelu_pk((f32x2){v1[0], v1[1]}), d = gelu_pk((f32x2){v1[2], v1[3]});
;                         v0 = (f32x4){a.x, a.y, b.x, b.y}; v1 = (f32x4){c.x, c.y, d.x, d.y}; }
;                     v0 = v0 * sc; v1 = v1 * sc;
;                     if (STAT == 1) rs += (v0[0] * v0[0] + v0[1] * v0[1]) + (v0[2] * v0[2] + v0[3] * v0[3]) + (v1[0] * v1[0] + v1[1] * v1[1]) + (v1[2] * v1[2] + v1[3] * v1[3]);
;                     if (STAT == 2) {
; #pragma unroll
;                         for (int e = 0; e < 4; ++e) { cs[bj][0][e] += v0[e]; cq[bj][0][e] += v0[e] * v0[e]; cs[bj][1][e] += v1[e]; cq[bj][1][e] += v1[e] * v1[e]; } }
;                     u32x4 w; w.x = cvt_pk_bf16(v0[0], v0[1]); w.y = cvt_pk_bf16(v0[2], v0[3]); w.z = cvt_pk_bf16(v1[0], v1[1]); w.w = cvt_pk_bf16(v1[2], v1[3]);
;                     *(GAS u32x4*)(rowp + bj * 128) = w; }
	v_cndmask_b32_e32 v117, v111, v117, vcc
	v_rcp_f32_e32 v106, v106
	v_rcp_f32_e32 v107, v107
	v_cmp_gt_f32_e32 vcc, 0, v108
	v_pk_fma_f32 v[110:111], v[106:107], s[30:31], v[122:123] op_sel_hi:[1,0,0]
	s_nop 0
	v_pk_fma_f32 v[110:111], v[106:107], v[110:111], s[52:53] op_sel_hi:[1,1,0]
	s_nop 0
	v_pk_fma_f32 v[110:111], v[106:107], v[110:111], s[54:55] op_sel_hi:[1,1,0]
	s_nop 0
	v_pk_fma_f32 v[110:111], v[106:107], v[110:111], s[56:57] op_sel_hi:[1,1,0]
	s_nop 0
	v_pk_mul_f32 v[106:107], v[106:107], v[110:111]
	v_pk_mul_f32 v[110:111], v[112:113], s[58:59] op_sel_hi:[1,0]
	s_nop 0
	v_exp_f32_e32 v110, v110
	v_exp_f32_e32 v111, v111
	s_nop 0
	v_pk_mul_f32 v[106:107], v[110:111], v[106:107]
	s_nop 0
	v_pk_mul_f32 v[110:111], v[108:109], v[106:107]
	v_pk_fma_f32 v[106:107], v[108:109], v[106:107], v[108:109] neg_lo:[1,0,0] neg_hi:[1,0,0]
	s_nop 0
	v_cndmask_b32_e32 v110, v106, v110, vcc
	v_cmp_gt_f32_e32 vcc, 0, v109
	v_cvt_pk_bf16_f32 v106, v120, v121
	s_nop 1
	v_cndmask_b32_e32 v109, v107, v111, vcc
	v_cvt_pk_bf16_f32 v107, v118, v119
	v_cvt_pk_bf16_f32 v108, v116, v117
	v_cvt_pk_bf16_f32 v109, v110, v109
	global_store_dwordx4 v[114:115], v[106:109], off
	v_pk_mul_f32 v[110:111], v[102:103], v[102:103]
	v_cmp_gt_f32_e32 vcc, 0, v102
	v_and_b32_e32 v107, 0x7fffffff, v103
	v_and_b32_e32 v106, 0x7fffffff, v102
	v_pk_fma_f32 v[106:107], v[106:107], s[28:29], 1.0 op_sel_hi:[1,0,0]
	v_pk_mul_f32 v[110:111], v[110:111], s[58:59] op_sel_hi:[1,0]
	v_rcp_f32_e32 v106, v106
	v_rcp_f32_e32 v107, v107
	v_exp_f32_e32 v110, v110
	v_exp_f32_e32 v111, v111
	v_pk_fma_f32 v[108:109], v[106:107], s[30:31], v[122:123] op_sel_hi:[1,0,0]
	s_nop 0
	v_pk_fma_f32 v[108:109], v[106:107], v[108:109], s[52:53] op_sel_hi:[1,1,0]
	s_nop 0
	v_pk_fma_f32 v[108:109], v[106:107], v[108:109], s[54:55] op_sel_hi:[1,1,0]
	s_nop 0
	v_pk_fma_f32 v[108:109], v[106:107], v[108:109], s[56:57] op_sel_hi:[1,1,0]
	s_nop 0
	v_pk_mul_f32 v[106:107], v[106:107], v[108:109]
	v_pk_mul_f32 v[108:109], v[104:105], v[104:105]
	v_pk_mul_f32 v[106:107], v[110:111], v[106:107]
	s_nop 0
	v_pk_mul_f32 v[110:111], v[102:103], v[106:107]
	v_pk_fma_f32 v[106:107], v[102:103], v[106:107], v[102:103] neg_lo:[1,0,0] neg_hi:[1,0,0]
	v_and_b32_e32 v102, 0x7fffffff, v104
	v_cndmask_b32_e32 v110, v106, v110, vcc
	v_cmp_gt_f32_e32 vcc, 0, v103
	v_and_b32_e32 v103, 0x7fffffff, v105
	v_pk_fma_f32 v[102:103], v[102:103], s[28:29], 1.0 op_sel_hi:[1,0,0]
	v_cndmask_b32_e32 v111, v107, v111, vcc
	v_rcp_f32_e32 v102, v102
	v_rcp_f32_e32 v103, v103
	v_cmp_gt_f32_e32 vcc, 0, v104
	v_pk_fma_f32 v[106:107], v[102:103], s[30:31], v[122:123] op_sel_hi:[1,0,0]
	s_nop 0
	v_pk_fma_f32 v[106:107], v[102:103], v[106:107], s[52:53] op_sel_hi:[1,1,0]
	s_nop 0
	v_pk_fma_f32 v[106:107], v[102:103], v[106:107], s[54:55] op_sel_hi:[1,1,0]
	s_nop 0
	v_pk_fma_f32 v[106:107], v[102:103], v[106:107], s[56:57] op_sel_hi:[1,1,0]
	s_nop 0
	v_pk_mul_f32 v[102:103], v[102:103], v[106:107]
	v_pk_mul_f32 v[106:107], v[108:109], s[58:59] op_sel_hi:[1,0]
	s_nop 0
	v_exp_f32_e32 v106, v106
	v_exp_f32_e32 v107, v107
	s_nop 0
	v_pk_mul_f32 v[102:103], v[106:107], v[102:103]
	s_nop 0
	v_pk_mul_f32 v[106:107], v[104:105], v[102:103]
	v_pk_fma_f32 v[102:103], v[104:105], v[102:103], v[104:105] neg_lo:[1,0,0] neg_hi:[1,0,0]
	s_nop 0
	v_cndmask_b32_e32 v108, v102, v106, vcc
	v_cmp_gt_f32_e32 vcc, 0, v105
	v_and_b32_e32 v102, 0x7fffffff, v98
	s_nop 0
	v_cndmask_b32_e32 v109, v103, v107, vcc
	v_and_b32_e32 v103, 0x7fffffff, v99
	v_pk_fma_f32 v[102:103], v[102:103], s[28:29], 1.0 op_sel_hi:[1,0,0]
	v_pk_mul_f32 v[106:107], v[98:99], v[98:99]
	v_rcp_f32_e32 v102, v102
	v_rcp_f32_e32 v103, v103
	v_pk_mul_f32 v[106:107], v[106:107], s[58:59] op_sel_hi:[1,0]
	v_cmp_gt_f32_e32 vcc, 0, v98
	v_exp_f32_e32 v106, v106
	v_pk_fma_f32 v[104:105], v[102:103], s[30:31], v[122:123] op_sel_hi:[1,0,0]
	v_exp_f32_e32 v107, v107
	v_pk_fma_f32 v[104:105], v[102:103], v[104:105], s[52:53] op_sel_hi:[1,1,0]
	s_nop 0
	v_pk_fma_f32 v[104:105], v[102:103], v[104:105], s[54:55] op_sel_hi:[1,1,0]
	s_nop 0
	v_pk_fma_f32 v[104:105], v[102:103], v[104:105], s[56:57] op_sel_hi:[1,1,0]
	s_nop 0
	v_pk_mul_f32 v[102:103], v[102:103], v[104:105]
	v_pk_mul_f32 v[104:105], v[100:101], v[100:101]
	v_pk_mul_f32 v[102:103], v[106:107], v[102:103]
	s_nop 0
	v_pk_mul_f32 v[106:107], v[98:99], v[102:103]
	v_pk_fma_f32 v[102:103], v[98:99], v[102:103], v[98:99] neg_lo:[1,0,0] neg_hi:[1,0,0]
	v_and_b32_e32 v98, 0x7fffffff, v100
	v_cndmask_b32_e32 v106, v102, v106, vcc
	v_cmp_gt_f32_e32 vcc, 0, v99
	v_and_b32_e32 v99, 0x7fffffff, v101
	v_pk_fma_f32 v[98:99], v[98:99], s[28:29], 1.0 op_sel_hi:[1,0,0]
	v_cndmask_b32_e32 v107, v103, v107, vcc
	v_rcp_f32_e32 v98, v98
	v_rcp_f32_e32 v99, v99
	v_cmp_gt_f32_e32 vcc, 0, v100
	v_pk_fma_f32 v[102:103], v[98:99], s[30:31], v[122:123] op_sel_hi:[1,0,0]
	s_nop 0
	v_pk_fma_f32 v[102:103], v[98:99], v[102:103], s[52:53] op_sel_hi:[1,1,0]
	s_nop 0
	v_pk_fma_f32 v[102:103], v[98:99], v[102:103], s[54:55] op_sel_hi:[1,1,0]
	s_nop 0
	v_pk_fma_f32 v[102:103], v[98:99], v[102:103], s[56:57] op_sel_hi:[1,1,0]
	s_nop 0
	v_pk_mul_f32 v[98:99], v[98:99], v[102:103]
	v_pk_mul_f32 v[102:103], v[104:105], s[58:59] op_sel_hi:[1,0]
	v_pk_mul_f32 v[104:105], v[94:95], v[94:95]
	v_exp_f32_e32 v102, v102
	v_exp_f32_e32 v103, v103
	v_pk_mul_f32 v[104:105], v[104:105], s[58:59] op_sel_hi:[1,0]
	v_pk_mul_f32 v[98:99], v[102:103], v[98:99]
	s_nop 0
	v_pk_mul_f32 v[102:103], v[100:101], v[98:99]
	v_pk_fma_f32 v[98:99], v[100:101], v[98:99], v[100:101] neg_lo:[1,0,0] neg_hi:[1,0,0]
	v_exp_f32_e32 v104, v104
	v_cndmask_b32_e32 v102, v98, v102, vcc
	v_cmp_gt_f32_e32 vcc, 0, v101
; __device__ __forceinline__ unsigned cvt_pk_bf16(float lo, float hi) { unsigned r; asm volatile("v_cvt_pk_bf16_f32 %0, %1, %2" : "=v"(r) : "v"(lo), "v"(hi)); return r; }
; #define GAS __attribute__((address_space(1)))
; __device__ __forceinline__ f32x2 gelu_pk(f32x2 v) {
;     const f32x2 av = __builtin_elementwise_abs(v), d = av * 0.2316418882f + 1.0f;
;     f32x2 t; t.x = __builtin_amdgcn_rcpf(d.x); t.y = __builtin_amdgcn_rcpf(d.y);
;     f32x2 q = t * 0.5307027145f + (-0.7265760135f); q = q * t + 0.7107068705f; q = q * t + (-0.142248368f); q = q * t + 0.127414796f; q = q * t;
;     const f32x2 s = (v * v) * (-0.72134752044f);
;     f32x2 e; e.x = __builtin_amdgcn_exp2f(s.x); e.y = __builtin_amdgcn_exp2f(s.y);
;     const f32x2 m = v * (q * e), r = v - m;
;     f32x2 o; o.x = v.x < 0.f ? m.x : r.x; o.y = v.y < 0.f ? m.y : r.y; return o;
; }
;     __device__ __forceinline__ void operator()(const f32x4 (&acc)[2][2][4][2], const Unit& u, int wr, int wc, int fr, int fq, const float (&pre)[8]) const {
;     ...
;                     f32x4 v0 = acc[ai][bj][m][0], v1 = acc[ai][bj][m][1];
;                     if (RS == 1) { v0 = v0 * rsc; v1 = v1 * rsc; }
;                     if (RS == 2) { v0 = v0 * csc[bj][0]; v1 = v1 * csc[bj][1]; }
;                     if (ACT == 1) { const f32x2 a = gelu_pk((f32x2){v0[0], v0[1]}), b = gelu_pk((f32x2){v0[2], v0[3]}), c = gelu_pk((f32x2){v1[0], v1[1]}), d = gelu_pk((f32x2){v1[2], v1[3]});
;                         v0 = (f32x4){a.x, a.y, b.x, b.y}; v1 = (f32x4){c.x, c.y, d.x, d.y}; }
;                     v0 = v0 * sc; v1 = v1 * sc;
;                     if (STAT == 1) rs += (v0[0] * v0[0] + v0[1] * v0[1]) + (v0[2] * v0[2] + v0[3] * v0[3]) + (v1[0] * v1[0] + v1[1] * v1[1]) + (v1[2] * v1[2] + v1[3] * v1[3]);
;                     if (STAT == 2) {
; #pragma unroll
;                         for (int e = 0; e < 4; ++e) { cs[bj][0][e] += v0[e]; cq[bj][0][e] += v0[e] * v0[e]; cs[bj][1][e] += v1[e]; cq[bj][1][e] += v1[e] * v1[e]; } }
;                     u32x4 w; w.x = cvt_pk_bf16(v0[0], v0[1]); w.y = cvt_pk_bf16(v0[2], v0[3]); w.z = cvt_pk_bf16(v1[0], v1[1]); w.w = cvt_pk_bf16(v1[2], v1[3]);
;                     *(GAS u32x4*)(rowp + bj * 128) = w; }
	v_cvt_pk_bf16_f32 v98, v110, v111
	v_exp_f32_e32 v105, v105
	s_nop 0
	v_cndmask_b32_e32 v101, v99, v103, vcc
	v_cvt_pk_bf16_f32 v99, v108, v109
	v_cvt_pk_bf16_f32 v100, v106, v107
	v_cvt_pk_bf16_f32 v101, v102, v101
	global_store_dwordx4 v[114:115], v[98:101], off offset:256
	v_cmp_gt_f32_e32 vcc, 0, v94
	s_nop 0
	v_and_b32_e32 v101, 0x7fffffff, v95
	v_and_b32_e32 v100, 0x7fffffff, v94
	v_pk_fma_f32 v[100:101], v[100:101], s[28:29], 1.0 op_sel_hi:[1,0,0]
	v_or_b32_e32 v98, 32, v160
	v_rcp_f32_e32 v100, v100
	v_rcp_f32_e32 v101, v101
	v_ashrrev_i32_e32 v99, 31, v98
	v_lshlrev_b64 v[98:99], 11, v[98:99]
	v_lshl_add_u64 v[98:99], s[40:41], 0, v[98:99]
	v_pk_fma_f32 v[102:103], v[100:101], s[30:31], v[122:123] op_sel_hi:[1,0,0]
	v_lshl_add_u64 v[98:99], v[98:99], 0, v[170:171]
	v_pk_fma_f32 v[102:103], v[100:101], v[102:103], s[52:53] op_sel_hi:[1,1,0]
	s_nop 0
	v_pk_fma_f32 v[102:103], v[100:101], v[102:103], s[54:55] op_sel_hi:[1,1,0]
	s_nop 0
	v_pk_fma_f32 v[102:103], v[100:101], v[102:103], s[56:57] op_sel_hi:[1,1,0]
	s_nop 0
	v_pk_mul_f32 v[100:101], v[100:101], v[102:103]
	v_pk_mul_f32 v[102:103], v[96:97], v[96:97]
	v_pk_mul_f32 v[100:101], v[104:105], v[100:101]
	s_nop 0
	v_pk_mul_f32 v[104:105], v[94:95], v[100:101]
	v_pk_fma_f32 v[100:101], v[94:95], v[100:101], v[94:95] neg_lo:[1,0,0] neg_hi:[1,0,0]
	v_and_b32_e32 v94, 0x7fffffff, v96
	v_cndmask_b32_e32 v104, v100, v104, vcc
	v_cmp_gt_f32_e32 vcc, 0, v95
	v_and_b32_e32 v95, 0x7fffffff, v97
	v_pk_fma_f32 v[94:95], v[94:95], s[28:29], 1.0 op_sel_hi:[1,0,0]
	v_cndmask_b32_e32 v105, v101, v105, vcc
	v_rcp_f32_e32 v94, v94
	v_rcp_f32_e32 v95, v95
	v_cmp_gt_f32_e32 vcc, 0, v96
	v_pk_fma_f32 v[100:101], v[94:95], s[30:31], v[122:123] op_sel_hi:[1,0,0]
	s_nop 0
	v_pk_fma_f32 v[100:101], v[94:95], v[100:101], s[52:53] op_sel_hi:[1,1,0]
	s_nop 0
	v_pk_fma_f32 v[100:101], v[94:95], v[100:101], s[54:55] op_sel_hi:[1,1,0]
	s_nop 0
	v_pk_fma_f32 v[100:101], v[94:95], v[100:101], s[56:57] op_sel_hi:[1,1,0]
	s_nop 0
	v_pk_mul_f32 v[94:95], v[94:95], v[100:101]
	v_pk_mul_f32 v[100:101], v[102:103], s[58:59] op_sel_hi:[1,0]
	s_nop 0
	v_exp_f32_e32 v100, v100
	v_exp_f32_e32 v101, v101
	s_nop 0
	v_pk_mul_f32 v[94:95], v[100:101], v[94:95]
	s_nop 0
	v_pk_mul_f32 v[100:101], v[96:97], v[94:95]
	v_pk_fma_f32 v[94:95], v[96:97], v[94:95], v[96:97] neg_lo:[1,0,0] neg_hi:[1,0,0]
	s_nop 0
	v_cndmask_b32_e32 v102, v94, v100, vcc
	v_cmp_gt_f32_e32 vcc, 0, v97
	v_and_b32_e32 v94, 0x7fffffff, v90
	s_nop 0
	v_cndmask_b32_e32 v103, v95, v101, vcc
	v_and_b32_e32 v95, 0x7fffffff, v91
	v_pk_fma_f32 v[94:95], v[94:95], s[28:29], 1.0 op_sel_hi:[1,0,0]
	v_pk_mul_f32 v[100:101], v[90:91], v[90:91]
	v_rcp_f32_e32 v94, v94
	v_rcp_f32_e32 v95, v95
	v_pk_mul_f32 v[100:101], v[100:101], s[58:59] op_sel_hi:[1,0]
	v_cmp_gt_f32_e32 vcc, 0, v90
	v_exp_f32_e32 v100, v100
	v_pk_fma_f32 v[96:97], v[94:95], s[30:31], v[122:123] op_sel_hi:[1,0,0]
	v_exp_f32_e32 v101, v101
	v_pk_fma_f32 v[96:97], v[94:95], v[96:97], s[52:53] op_sel_hi:[1,1,0]
	s_nop 0
	v_pk_fma_f32 v[96:97], v[94:95], v[96:97], s[54:55] op_sel_hi:[1,1,0]
	s_nop 0
	v_pk_fma_f32 v[96:97], v[94:95], v[96:97], s[56:57] op_sel_hi:[1,1,0]
	s_nop 0
	v_pk_mul_f32 v[94:95], v[94:95], v[96:97]
	v_pk_mul_f32 v[96:97], v[92:93], v[92:93]
	v_pk_mul_f32 v[94:95], v[100:101], v[94:95]
	s_nop 0
	v_pk_mul_f32 v[100:101], v[90:91], v[94:95]
	v_pk_fma_f32 v[94:95], v[90:91], v[94:95], v[90:91] neg_lo:[1,0,0] neg_hi:[1,0,0]
	v_and_b32_e32 v90, 0x7fffffff, v92
	v_cndmask_b32_e32 v100, v94, v100, vcc
	v_cmp_gt_f32_e32 vcc, 0, v91
	v_and_b32_e32 v91, 0x7fffffff, v93
	v_pk_fma_f32 v[90:91], v[90:91], s[28:29], 1.0 op_sel_hi:[1,0,0]
	v_cndmask_b32_e32 v101, v95, v101, vcc
	v_rcp_f32_e32 v90, v90
	v_rcp_f32_e32 v91, v91
	v_cmp_gt_f32_e32 vcc, 0, v92
	v_pk_fma_f32 v[94:95], v[90:91], s[30:31], v[122:123] op_sel_hi:[1,0,0]
	s_nop 0
	v_pk_fma_f32 v[94:95], v[90:91], v[94:95], s[52:53] op_sel_hi:[1,1,0]
	s_nop 0
	v_pk_fma_f32 v[94:95], v[90:91], v[94:95], s[54:55] op_sel_hi:[1,1,0]
	s_nop 0
	v_pk_fma_f32 v[94:95], v[90:91], v[94:95], s[56:57] op_sel_hi:[1,1,0]
	s_nop 0
	v_pk_mul_f32 v[90:91], v[90:91], v[94:95]
	v_pk_mul_f32 v[94:95], v[96:97], s[58:59] op_sel_hi:[1,0]
	s_nop 0
	v_exp_f32_e32 v94, v94
	v_exp_f32_e32 v95, v95
	s_nop 0
	v_pk_mul_f32 v[90:91], v[94:95], v[90:91]
	s_nop 0
	v_pk_mul_f32 v[94:95], v[92:93], v[90:91]
	v_pk_fma_f32 v[90:91], v[92:93], v[90:91], v[92:93] neg_lo:[1,0,0] neg_hi:[1,0,0]
	s_nop 0
	v_cndmask_b32_e32 v94, v90, v94, vcc
	v_cmp_gt_f32_e32 vcc, 0, v93
	v_cvt_pk_bf16_f32 v90, v104, v105
	s_nop 1
	v_cndmask_b32_e32 v93, v91, v95, vcc
	v_cvt_pk_bf16_f32 v91, v102, v103
	v_cvt_pk_bf16_f32 v92, v100, v101
	v_cvt_pk_bf16_f32 v93, v94, v93
	global_store_dwordx4 v[98:99], v[90:93], off
	v_pk_mul_f32 v[94:95], v[86:87], v[86:87]
	v_cmp_gt_f32_e32 vcc, 0, v86
	v_and_b32_e32 v91, 0x7fffffff, v87
	v_and_b32_e32 v90, 0x7fffffff, v86
	v_pk_fma_f32 v[90:91], v[90:91], s[28:29], 1.0 op_sel_hi:[1,0,0]
	v_pk_mul_f32 v[94:95], v[94:95], s[58:59] op_sel_hi:[1,0]
	v_rcp_f32_e32 v90, v90
	v_rcp_f32_e32 v91, v91
	v_exp_f32_e32 v94, v94
	v_exp_f32_e32 v95, v95
	v_pk_fma_f32 v[92:93], v[90:91], s[30:31], v[122:123] op_sel_hi:[1,0,0]
	s_nop 0
	v_pk_fma_f32 v[92:93], v[90:91], v[92:93], s[52:53] op_sel_hi:[1,1,0]
	s_nop 0
	v_pk_fma_f32 v[92:93], v[90:91], v[92:93], s[54:55] op_sel_hi:[1,1,0]
	s_nop 0
	v_pk_fma_f32 v[92:93], v[90:91], v[92:93], s[56:57] op_sel_hi:[1,1,0]
	s_nop 0
	v_pk_mul_f32 v[90:91], v[90:91], v[92:93]
	v_pk_mul_f32 v[92:93], v[88:89], v[88:89]
	v_pk_mul_f32 v[90:91], v[94:95], v[90:91]
	s_nop 0
	v_pk_mul_f32 v[94:95], v[86:87], v[90:91]
; __device__ __forceinline__ unsigned cvt_pk_bf16(float lo, float hi) { unsigned r; asm volatile("v_cvt_pk_bf16_f32 %0, %1, %2" : "=v"(r) : "v"(lo), "v"(hi)); return r; }
; #define GAS __attribute__((address_space(1)))
; __device__ __forceinline__ f32x2 gelu_pk(f32x2 v) {
;     const f32x2 av = __builtin_elementwise_abs(v), d = av * 0.2316418882f + 1.0f;
;     f32x2 t; t.x = __builtin_amdgcn_rcpf(d.x); t.y = __builtin_amdgcn_rcpf(d.y);
;     f32x2 q = t * 0.5307027145f + (-0.7265760135f); q = q * t + 0.7107068705f; q = q * t + (-0.142248368f); q = q * t + 0.127414796f; q = q * t;
;     const f32x2 s = (v * v) * (-0.72134752044f);
;     f32x2 e; e.x = __builtin_amdgcn_exp2f(s.x); e.y = __builtin_amdgcn_exp2f(s.y);
;     const f32x2 m = v * (q * e), r = v - m;
;     f32x2 o; o.x = v.x < 0.f ? m.x : r.x; o.y = v.y < 0.f ? m.y : r.y; return o;
; }
;     __device__ __forceinline__ void operator()(const f32x4 (&acc)[2][2][4][2], const Unit& u, int wr, int wc, int fr, int fq, const float (&pre)[8]) const {
;     ...
;                     f32x4 v0 = acc[ai][bj][m][0], v1 = acc[ai][bj][m][1];
;                     if (RS == 1) { v0 = v0 * rsc; v1 = v1 * rsc; }
;                     if (RS == 2) { v0 = v0 * csc[bj][0]; v1 = v1 * csc[bj][1]; }
;                     if (ACT == 1) { const f32x2 a = gelu_pk((f32x2){v0[0], v0[1]}), b = gelu_pk((f32x2){v0[2], v0[3]}), c = gelu_pk((f32x2){v1[0], v1[1]}), d = gelu_pk((f32x2){v1[2], v1[3]});
;                         v0 = (f32x4){a.x, a.y, b.x, b.y}; v1 = (f32x4){c.x, c.y, d.x, d.y}; }
;                     v0 = v0 * sc; v1 = v1 * sc;
;                     if (STAT == 1) rs += (v0[0] * v0[0] + v0[1] * v0[1]) + (v0[2] * v0[2] + v0[3] * v0[3]) + (v1[0] * v1[0] + v1[1] * v1[1]) + (v1[2] * v1[2] + v1[3] * v1[3]);
;                     if (STAT == 2) {
; #pragma unroll
;                         for (int e = 0; e < 4; ++e) { cs[bj][0][e] += v0[e]; cq[bj][0][e] += v0[e] * v0[e]; cs[bj][1][e] += v1[e]; cq[bj][1][e] += v1[e] * v1[e]; } }
;                     u32x4 w; w.x = cvt_pk_bf16(v0[0], v0[1]); w.y = cvt_pk_bf16(v0[2], v0[3]); w.z = cvt_pk_bf16(v1[0], v1[1]); w.w = cvt_pk_bf16(v1[2], v1[3]);
;                     *(GAS u32x4*)(rowp + bj * 128) = w; }
	v_pk_fma_f32 v[90:91], v[86:87], v[90:91], v[86:87] neg_lo:[1,0,0] neg_hi:[1,0,0]
	v_and_b32_e32 v86, 0x7fffffff, v88
	v_cndmask_b32_e32 v94, v90, v94, vcc
	v_cmp_gt_f32_e32 vcc, 0, v87
	v_and_b32_e32 v87, 0x7fffffff, v89
	v_pk_fma_f32 v[86:87], v[86:87], s[28:29], 1.0 op_sel_hi:[1,0,0]
	v_cndmask_b32_e32 v95, v91, v95, vcc
	v_rcp_f32_e32 v86, v86
	v_rcp_f32_e32 v87, v87
	v_cmp_gt_f32_e32 vcc, 0, v88
	v_pk_fma_f32 v[90:91], v[86:87], s[30:31], v[122:123] op_sel_hi:[1,0,0]
	s_nop 0
	v_pk_fma_f32 v[90:91], v[86:87], v[90:91], s[52:53] op_sel_hi:[1,1,0]
	s_nop 0
	v_pk_fma_f32 v[90:91], v[86:87], v[90:91], s[54:55] op_sel_hi:[1,1,0]
	s_nop 0
	v_pk_fma_f32 v[90:91], v[86:87], v[90:91], s[56:57] op_sel_hi:[1,1,0]
	s_nop 0
	v_pk_mul_f32 v[86:87], v[86:87], v[90:91]
	v_pk_mul_f32 v[90:91], v[92:93], s[58:59] op_sel_hi:[1,0]
	s_nop 0
	v_exp_f32_e32 v90, v90
	v_exp_f32_e32 v91, v91
	s_nop 0
	v_pk_mul_f32 v[86:87], v[90:91], v[86:87]
	s_nop 0
	v_pk_mul_f32 v[90:91], v[88:89], v[86:87]
	v_pk_fma_f32 v[86:87], v[88:89], v[86:87], v[88:89] neg_lo:[1,0,0] neg_hi:[1,0,0]
	s_nop 0
	v_cndmask_b32_e32 v92, v86, v90, vcc
	v_cmp_gt_f32_e32 vcc, 0, v89
	v_and_b32_e32 v86, 0x7fffffff, v82
	s_nop 0
	v_cndmask_b32_e32 v93, v87, v91, vcc
	v_and_b32_e32 v87, 0x7fffffff, v83
	v_pk_fma_f32 v[86:87], v[86:87], s[28:29], 1.0 op_sel_hi:[1,0,0]
	v_pk_mul_f32 v[90:91], v[82:83], v[82:83]
	v_rcp_f32_e32 v86, v86
	v_rcp_f32_e32 v87, v87
	v_pk_mul_f32 v[90:91], v[90:91], s[58:59] op_sel_hi:[1,0]
	v_cmp_gt_f32_e32 vcc, 0, v82
	v_exp_f32_e32 v90, v90
	v_pk_fma_f32 v[88:89], v[86:87], s[30:31], v[122:123] op_sel_hi:[1,0,0]
	v_exp_f32_e32 v91, v91
	v_pk_fma_f32 v[88:89], v[86:87], v[88:89], s[52:53] op_sel_hi:[1,1,0]
	s_nop 0
	v_pk_fma_f32 v[88:89], v[86:87], v[88:89], s[54:55] op_sel_hi:[1,1,0]
	s_nop 0
	v_pk_fma_f32 v[88:89], v[86:87], v[88:89], s[56:57] op_sel_hi:[1,1,0]
	s_nop 0
	v_pk_mul_f32 v[86:87], v[86:87], v[88:89]
	v_pk_mul_f32 v[88:89], v[84:85], v[84:85]
	v_pk_mul_f32 v[86:87], v[90:91], v[86:87]
	s_nop 0
	v_pk_mul_f32 v[90:91], v[82:83], v[86:87]
	v_pk_fma_f32 v[86:87], v[82:83], v[86:87], v[82:83] neg_lo:[1,0,0] neg_hi:[1,0,0]
	v_and_b32_e32 v82, 0x7fffffff, v84
	v_cndmask_b32_e32 v90, v86, v90, vcc
	v_cmp_gt_f32_e32 vcc, 0, v83
	v_and_b32_e32 v83, 0x7fffffff, v85
	v_pk_fma_f32 v[82:83], v[82:83], s[28:29], 1.0 op_sel_hi:[1,0,0]
	v_cndmask_b32_e32 v91, v87, v91, vcc
	v_rcp_f32_e32 v82, v82
	v_rcp_f32_e32 v83, v83
	v_cmp_gt_f32_e32 vcc, 0, v84
	v_pk_fma_f32 v[86:87], v[82:83], s[30:31], v[122:123] op_sel_hi:[1,0,0]
	s_nop 0
	v_pk_fma_f32 v[86:87], v[82:83], v[86:87], s[52:53] op_sel_hi:[1,1,0]
	s_nop 0
	v_pk_fma_f32 v[86:87], v[82:83], v[86:87], s[54:55] op_sel_hi:[1,1,0]
	s_nop 0
	v_pk_fma_f32 v[86:87], v[82:83], v[86:87], s[56:57] op_sel_hi:[1,1,0]
	s_nop 0
	v_pk_mul_f32 v[82:83], v[82:83], v[86:87]
	v_pk_mul_f32 v[86:87], v[88:89], s[58:59] op_sel_hi:[1,0]
	v_pk_mul_f32 v[88:89], v[78:79], v[78:79]
	v_exp_f32_e32 v86, v86
	v_exp_f32_e32 v87, v87
	v_pk_mul_f32 v[88:89], v[88:89], s[58:59] op_sel_hi:[1,0]
	v_pk_mul_f32 v[82:83], v[86:87], v[82:83]
	s_nop 0
	v_pk_mul_f32 v[86:87], v[84:85], v[82:83]
	v_pk_fma_f32 v[82:83], v[84:85], v[82:83], v[84:85] neg_lo:[1,0,0] neg_hi:[1,0,0]
	v_exp_f32_e32 v88, v88
	v_cndmask_b32_e32 v86, v82, v86, vcc
	v_cmp_gt_f32_e32 vcc, 0, v85
	v_cvt_pk_bf16_f32 v82, v94, v95
	v_exp_f32_e32 v89, v89
	s_nop 0
	v_cndmask_b32_e32 v85, v83, v87, vcc
	v_cvt_pk_bf16_f32 v83, v92, v93
	v_cvt_pk_bf16_f32 v84, v90, v91
	v_cvt_pk_bf16_f32 v85, v86, v85
	global_store_dwordx4 v[98:99], v[82:85], off offset:256
	v_cmp_gt_f32_e32 vcc, 0, v78
	s_nop 0
	v_and_b32_e32 v85, 0x7fffffff, v79
	v_and_b32_e32 v84, 0x7fffffff, v78
	v_pk_fma_f32 v[84:85], v[84:85], s[28:29], 1.0 op_sel_hi:[1,0,0]
	v_or_b32_e32 v82, 48, v160
	v_rcp_f32_e32 v84, v84
	v_rcp_f32_e32 v85, v85
	v_ashrrev_i32_e32 v83, 31, v82
	v_lshlrev_b64 v[82:83], 11, v[82:83]
	v_lshl_add_u64 v[82:83], s[40:41], 0, v[82:83]
	v_pk_fma_f32 v[86:87], v[84:85], s[30:31], v[122:123] op_sel_hi:[1,0,0]
	v_lshl_add_u64 v[82:83], v[82:83], 0, v[170:171]
	v_pk_fma_f32 v[86:87], v[84:85], v[86:87], s[52:53] op_sel_hi:[1,1,0]
	s_nop 0
	v_pk_fma_f32 v[86:87], v[84:85], v[86:87], s[54:55] op_sel_hi:[1,1,0]
	s_nop 0
	v_pk_fma_f32 v[86:87], v[84:85], v[86:87], s[56:57] op_sel_hi:[1,1,0]
	s_nop 0
	v_pk_mul_f32 v[84:85], v[84:85], v[86:87]
	v_pk_mul_f32 v[86:87], v[80:81], v[80:81]
	v_pk_mul_f32 v[84:85], v[88:89], v[84:85]
	s_nop 0
	v_pk_mul_f32 v[88:89], v[78:79], v[84:85]
	v_pk_fma_f32 v[84:85], v[78:79], v[84:85], v[78:79] neg_lo:[1,0,0] neg_hi:[1,0,0]
	v_and_b32_e32 v78, 0x7fffffff, v80
	v_cndmask_b32_e32 v88, v84, v88, vcc
	v_cmp_gt_f32_e32 vcc, 0, v79
	v_and_b32_e32 v79, 0x7fffffff, v81
	v_pk_fma_f32 v[78:79], v[78:79], s[28:29], 1.0 op_sel_hi:[1,0,0]
	v_cndmask_b32_e32 v89, v85, v89, vcc
	v_rcp_f32_e32 v78, v78
	v_rcp_f32_e32 v79, v79
	v_cmp_gt_f32_e32 vcc, 0, v80
	v_pk_fma_f32 v[84:85], v[78:79], s[30:31], v[122:123] op_sel_hi:[1,0,0]
	s_nop 0
	v_pk_fma_f32 v[84:85], v[78:79], v[84:85], s[52:53] op_sel_hi:[1,1,0]
	s_nop 0
	v_pk_fma_f32 v[84:85], v[78:79], v[84:85], s[54:55] op_sel_hi:[1,1,0]
	s_nop 0
	v_pk_fma_f32 v[84:85], v[78:79], v[84:85], s[56:57] op_sel_hi:[1,1,0]
	s_nop 0
	v_pk_mul_f32 v[78:79], v[78:79], v[84:85]
	v_pk_mul_f32 v[84:85], v[86:87], s[58:59] op_sel_hi:[1,0]
	s_nop 0
	v_exp_f32_e32 v84, v84
	v_exp_f32_e32 v85, v85
	s_nop 0
	v_pk_mul_f32 v[78:79], v[84:85], v[78:79]
	s_nop 0
	v_pk_mul_f32 v[84:85], v[80:81], v[78:79]
	v_pk_fma_f32 v[78:79], v[80:81], v[78:79], v[80:81] neg_lo:[1,0,0] neg_hi:[1,0,0]
	s_nop 0
	v_cndmask_b32_e32 v86, v78, v84, vcc
	v_cmp_gt_f32_e32 vcc, 0, v81
; __device__ __forceinline__ unsigned cvt_pk_bf16(float lo, float hi) { unsigned r; asm volatile("v_cvt_pk_bf16_f32 %0, %1, %2" : "=v"(r) : "v"(lo), "v"(hi)); return r; }
; #define GAS __attribute__((address_space(1)))
; __device__ __forceinline__ f32x2 gelu_pk(f32x2 v) {
;     const f32x2 av = __builtin_elementwise_abs(v), d = av * 0.2316418882f + 1.0f;
;     f32x2 t; t.x = __builtin_amdgcn_rcpf(d.x); t.y = __builtin_amdgcn_rcpf(d.y);
;     f32x2 q = t * 0.5307027145f + (-0.7265760135f); q = q * t + 0.7107068705f; q = q * t + (-0.142248368f); q = q * t + 0.127414796f; q = q * t;
;     const f32x2 s = (v * v) * (-0.72134752044f);
;     f32x2 e; e.x = __builtin_amdgcn_exp2f(s.x); e.y = __builtin_amdgcn_exp2f(s.y);
;     const f32x2 m = v * (q * e), r = v - m;
;     f32x2 o; o.x = v.x < 0.f ? m.x : r.x; o.y = v.y < 0.f ? m.y : r.y; return o;
; }
;     __device__ __forceinline__ void operator()(const f32x4 (&acc)[2][2][4][2], const Unit& u, int wr, int wc, int fr, int fq, const float (&pre)[8]) const {
;     ...
;                     f32x4 v0 = acc[ai][bj][m][0], v1 = acc[ai][bj][m][1];
;                     if (RS == 1) { v0 = v0 * rsc; v1 = v1 * rsc; }
;                     if (RS == 2) { v0 = v0 * csc[bj][0]; v1 = v1 * csc[bj][1]; }
;                     if (ACT == 1) { const f32x2 a = gelu_pk((f32x2){v0[0], v0[1]}), b = gelu_pk((f32x2){v0[2], v0[3]}), c = gelu_pk((f32x2){v1[0], v1[1]}), d = gelu_pk((f32x2){v1[2], v1[3]});
;                         v0 = (f32x4){a.x, a.y, b.x, b.y}; v1 = (f32x4){c.x, c.y, d.x, d.y}; }
;                     v0 = v0 * sc; v1 = v1 * sc;
;                     if (STAT == 1) rs += (v0[0] * v0[0] + v0[1] * v0[1]) + (v0[2] * v0[2] + v0[3] * v0[3]) + (v1[0] * v1[0] + v1[1] * v1[1]) + (v1[2] * v1[2] + v1[3] * v1[3]);
;                     if (STAT == 2) {
; #pragma unroll
;                         for (int e = 0; e < 4; ++e) { cs[bj][0][e] += v0[e]; cq[bj][0][e] += v0[e] * v0[e]; cs[bj][1][e] += v1[e]; cq[bj][1][e] += v1[e] * v1[e]; } }
;                     u32x4 w; w.x = cvt_pk_bf16(v0[0], v0[1]); w.y = cvt_pk_bf16(v0[2], v0[3]); w.z = cvt_pk_bf16(v1[0], v1[1]); w.w = cvt_pk_bf16(v1[2], v1[3]);
;                     *(GAS u32x4*)(rowp + bj * 128) = w; }
	v_and_b32_e32 v78, 0x7fffffff, v74
	s_nop 0
	v_cndmask_b32_e32 v87, v79, v85, vcc
	v_and_b32_e32 v79, 0x7fffffff, v75
	v_pk_fma_f32 v[78:79], v[78:79], s[28:29], 1.0 op_sel_hi:[1,0,0]
	v_pk_mul_f32 v[84:85], v[74:75], v[74:75]
	v_rcp_f32_e32 v78, v78
	v_rcp_f32_e32 v79, v79
	v_pk_mul_f32 v[84:85], v[84:85], s[58:59] op_sel_hi:[1,0]
	v_cmp_gt_f32_e32 vcc, 0, v74
	v_exp_f32_e32 v84, v84
	v_pk_fma_f32 v[80:81], v[78:79], s[30:31], v[122:123] op_sel_hi:[1,0,0]
	v_exp_f32_e32 v85, v85
	v_pk_fma_f32 v[80:81], v[78:79], v[80:81], s[52:53] op_sel_hi:[1,1,0]
	s_nop 0
	v_pk_fma_f32 v[80:81], v[78:79], v[80:81], s[54:55] op_sel_hi:[1,1,0]
	s_nop 0
	v_pk_fma_f32 v[80:81], v[78:79], v[80:81], s[56:57] op_sel_hi:[1,1,0]
	s_nop 0
	v_pk_mul_f32 v[78:79], v[78:79], v[80:81]
	v_pk_mul_f32 v[80:81], v[76:77], v[76:77]
	v_pk_mul_f32 v[78:79], v[84:85], v[78:79]
	s_nop 0
	v_pk_mul_f32 v[84:85], v[74:75], v[78:79]
	v_pk_fma_f32 v[78:79], v[74:75], v[78:79], v[74:75] neg_lo:[1,0,0] neg_hi:[1,0,0]
	v_and_b32_e32 v74, 0x7fffffff, v76
	v_cndmask_b32_e32 v84, v78, v84, vcc
	v_cmp_gt_f32_e32 vcc, 0, v75
	v_and_b32_e32 v75, 0x7fffffff, v77
	v_pk_fma_f32 v[74:75], v[74:75], s[28:29], 1.0 op_sel_hi:[1,0,0]
	v_cndmask_b32_e32 v85, v79, v85, vcc
	v_rcp_f32_e32 v74, v74
	v_rcp_f32_e32 v75, v75
	v_cmp_gt_f32_e32 vcc, 0, v76
	v_pk_fma_f32 v[78:79], v[74:75], s[30:31], v[122:123] op_sel_hi:[1,0,0]
	s_nop 0
	v_pk_fma_f32 v[78:79], v[74:75], v[78:79], s[52:53] op_sel_hi:[1,1,0]
	s_nop 0
	v_pk_fma_f32 v[78:79], v[74:75], v[78:79], s[54:55] op_sel_hi:[1,1,0]
	s_nop 0
	v_pk_fma_f32 v[78:79], v[74:75], v[78:79], s[56:57] op_sel_hi:[1,1,0]
	s_nop 0
	v_pk_mul_f32 v[74:75], v[74:75], v[78:79]
	v_pk_mul_f32 v[78:79], v[80:81], s[58:59] op_sel_hi:[1,0]
	s_nop 0
	v_exp_f32_e32 v78, v78
	v_exp_f32_e32 v79, v79
	s_nop 0
	v_pk_mul_f32 v[74:75], v[78:79], v[74:75]
	s_nop 0
	v_pk_mul_f32 v[78:79], v[76:77], v[74:75]
	v_pk_fma_f32 v[74:75], v[76:77], v[74:75], v[76:77] neg_lo:[1,0,0] neg_hi:[1,0,0]
	s_nop 0
	v_cndmask_b32_e32 v78, v74, v78, vcc
	v_cmp_gt_f32_e32 vcc, 0, v77
	v_cvt_pk_bf16_f32 v74, v88, v89
	s_nop 1
	v_cndmask_b32_e32 v77, v75, v79, vcc
	v_cvt_pk_bf16_f32 v75, v86, v87
	v_cvt_pk_bf16_f32 v76, v84, v85
	v_cvt_pk_bf16_f32 v77, v78, v77
	global_store_dwordx4 v[82:83], v[74:77], off
	v_pk_mul_f32 v[78:79], v[70:71], v[70:71]
	v_cmp_gt_f32_e32 vcc, 0, v70
	v_and_b32_e32 v75, 0x7fffffff, v71
	v_and_b32_e32 v74, 0x7fffffff, v70
	v_pk_fma_f32 v[74:75], v[74:75], s[28:29], 1.0 op_sel_hi:[1,0,0]
	v_pk_mul_f32 v[78:79], v[78:79], s[58:59] op_sel_hi:[1,0]
	v_rcp_f32_e32 v74, v74
	v_rcp_f32_e32 v75, v75
	v_exp_f32_e32 v78, v78
	v_exp_f32_e32 v79, v79
	v_pk_fma_f32 v[76:77], v[74:75], s[30:31], v[122:123] op_sel_hi:[1,0,0]
	s_nop 0
	v_pk_fma_f32 v[76:77], v[74:75], v[76:77], s[52:53] op_sel_hi:[1,1,0]
	s_nop 0
	v_pk_fma_f32 v[76:77], v[74:75], v[76:77], s[54:55] op_sel_hi:[1,1,0]
	s_nop 0
	v_pk_fma_f32 v[76:77], v[74:75], v[76:77], s[56:57] op_sel_hi:[1,1,0]
	s_nop 0
	v_pk_mul_f32 v[74:75], v[74:75], v[76:77]
	v_pk_mul_f32 v[76:77], v[72:73], v[72:73]
	v_pk_mul_f32 v[74:75], v[78:79], v[74:75]
	s_nop 0
	v_pk_mul_f32 v[78:79], v[70:71], v[74:75]
	v_pk_fma_f32 v[74:75], v[70:71], v[74:75], v[70:71] neg_lo:[1,0,0] neg_hi:[1,0,0]
	v_and_b32_e32 v70, 0x7fffffff, v72
	v_cndmask_b32_e32 v78, v74, v78, vcc
	v_cmp_gt_f32_e32 vcc, 0, v71
	v_and_b32_e32 v71, 0x7fffffff, v73
	v_pk_fma_f32 v[70:71], v[70:71], s[28:29], 1.0 op_sel_hi:[1,0,0]
	v_cndmask_b32_e32 v79, v75, v79, vcc
	v_rcp_f32_e32 v70, v70
	v_rcp_f32_e32 v71, v71
	v_cmp_gt_f32_e32 vcc, 0, v72
	v_pk_fma_f32 v[74:75], v[70:71], s[30:31], v[122:123] op_sel_hi:[1,0,0]
	s_nop 0
	v_pk_fma_f32 v[74:75], v[70:71], v[74:75], s[52:53] op_sel_hi:[1,1,0]
	s_nop 0
	v_pk_fma_f32 v[74:75], v[70:71], v[74:75], s[54:55] op_sel_hi:[1,1,0]
	s_nop 0
	v_pk_fma_f32 v[74:75], v[70:71], v[74:75], s[56:57] op_sel_hi:[1,1,0]
	s_nop 0
	v_pk_mul_f32 v[70:71], v[70:71], v[74:75]
	v_pk_mul_f32 v[74:75], v[76:77], s[58:59] op_sel_hi:[1,0]
	s_nop 0
	v_exp_f32_e32 v74, v74
	v_exp_f32_e32 v75, v75
	s_nop 0
	v_pk_mul_f32 v[70:71], v[74:75], v[70:71]
	s_nop 0
	v_pk_mul_f32 v[74:75], v[72:73], v[70:71]
	v_pk_fma_f32 v[70:71], v[72:73], v[70:71], v[72:73] neg_lo:[1,0,0] neg_hi:[1,0,0]
	s_nop 0
	v_cndmask_b32_e32 v76, v70, v74, vcc
	v_cmp_gt_f32_e32 vcc, 0, v73
	v_and_b32_e32 v70, 0x7fffffff, v66
	s_nop 0
	v_cndmask_b32_e32 v77, v71, v75, vcc
	v_and_b32_e32 v71, 0x7fffffff, v67
	v_pk_fma_f32 v[70:71], v[70:71], s[28:29], 1.0 op_sel_hi:[1,0,0]
	v_pk_mul_f32 v[74:75], v[66:67], v[66:67]
	v_rcp_f32_e32 v70, v70
	v_rcp_f32_e32 v71, v71
	v_pk_mul_f32 v[74:75], v[74:75], s[58:59] op_sel_hi:[1,0]
	v_cmp_gt_f32_e32 vcc, 0, v66
	v_exp_f32_e32 v74, v74
	v_pk_fma_f32 v[72:73], v[70:71], s[30:31], v[122:123] op_sel_hi:[1,0,0]
	v_exp_f32_e32 v75, v75
	v_pk_fma_f32 v[72:73], v[70:71], v[72:73], s[52:53] op_sel_hi:[1,1,0]
	s_nop 0
	v_pk_fma_f32 v[72:73], v[70:71], v[72:73], s[54:55] op_sel_hi:[1,1,0]
	s_nop 0
	v_pk_fma_f32 v[72:73], v[70:71], v[72:73], s[56:57] op_sel_hi:[1,1,0]
	s_nop 0
	v_pk_mul_f32 v[70:71], v[70:71], v[72:73]
	v_pk_mul_f32 v[72:73], v[68:69], v[68:69]
	v_pk_mul_f32 v[70:71], v[74:75], v[70:71]
	s_nop 0
	v_pk_mul_f32 v[74:75], v[66:67], v[70:71]
	v_pk_fma_f32 v[70:71], v[66:67], v[70:71], v[66:67] neg_lo:[1,0,0] neg_hi:[1,0,0]
	v_and_b32_e32 v66, 0x7fffffff, v68
	v_cndmask_b32_e32 v74, v70, v74, vcc
	v_cmp_gt_f32_e32 vcc, 0, v67
	v_and_b32_e32 v67, 0x7fffffff, v69
	v_pk_fma_f32 v[66:67], v[66:67], s[28:29], 1.0 op_sel_hi:[1,0,0]
	v_cndmask_b32_e32 v75, v71, v75, vcc
	v_rcp_f32_e32 v66, v66
	v_rcp_f32_e32 v67, v67
	v_cmp_gt_f32_e32 vcc, 0, v68
; __device__ __forceinline__ unsigned cvt_pk_bf16(float lo, float hi) { unsigned r; asm volatile("v_cvt_pk_bf16_f32 %0, %1, %2" : "=v"(r) : "v"(lo), "v"(hi)); return r; }
; #define GAS __attribute__((address_space(1)))
; __device__ __forceinline__ f32x2 gelu_pk(f32x2 v) {
;     const f32x2 av = __builtin_elementwise_abs(v), d = av * 0.2316418882f + 1.0f;
;     f32x2 t; t.x = __builtin_amdgcn_rcpf(d.x); t.y = __builtin_amdgcn_rcpf(d.y);
;     f32x2 q = t * 0.5307027145f + (-0.7265760135f); q = q * t + 0.7107068705f; q = q * t + (-0.142248368f); q = q * t + 0.127414796f; q = q * t;
;     const f32x2 s = (v * v) * (-0.72134752044f);
;     f32x2 e; e.x = __builtin_amdgcn_exp2f(s.x); e.y = __builtin_amdgcn_exp2f(s.y);
;     const f32x2 m = v * (q * e), r = v - m;
;     f32x2 o; o.x = v.x < 0.f ? m.x : r.x; o.y = v.y < 0.f ? m.y : r.y; return o;
; }
;     __device__ __forceinline__ void operator()(const f32x4 (&acc)[2][2][4][2], const Unit& u, int wr, int wc, int fr, int fq, const float (&pre)[8]) const {
;     ...
;                     f32x4 v0 = acc[ai][bj][m][0], v1 = acc[ai][bj][m][1];
;                     if (RS == 1) { v0 = v0 * rsc; v1 = v1 * rsc; }
;                     if (RS == 2) { v0 = v0 * csc[bj][0]; v1 = v1 * csc[bj][1]; }
;                     if (ACT == 1) { const f32x2 a = gelu_pk((f32x2){v0[0], v0[1]}), b = gelu_pk((f32x2){v0[2], v0[3]}), c = gelu_pk((f32x2){v1[0], v1[1]}), d = gelu_pk((f32x2){v1[2], v1[3]});
;                         v0 = (f32x4){a.x, a.y, b.x, b.y}; v1 = (f32x4){c.x, c.y, d.x, d.y}; }
;                     v0 = v0 * sc; v1 = v1 * sc;
;                     if (STAT == 1) rs += (v0[0] * v0[0] + v0[1] * v0[1]) + (v0[2] * v0[2] + v0[3] * v0[3]) + (v1[0] * v1[0] + v1[1] * v1[1]) + (v1[2] * v1[2] + v1[3] * v1[3]);
;                     if (STAT == 2) {
; #pragma unroll
;                         for (int e = 0; e < 4; ++e) { cs[bj][0][e] += v0[e]; cq[bj][0][e] += v0[e] * v0[e]; cs[bj][1][e] += v1[e]; cq[bj][1][e] += v1[e] * v1[e]; } }
;                     u32x4 w; w.x = cvt_pk_bf16(v0[0], v0[1]); w.y = cvt_pk_bf16(v0[2], v0[3]); w.z = cvt_pk_bf16(v1[0], v1[1]); w.w = cvt_pk_bf16(v1[2], v1[3]);
;                     *(GAS u32x4*)(rowp + bj * 128) = w; }
	v_pk_fma_f32 v[70:71], v[66:67], s[30:31], v[122:123] op_sel_hi:[1,0,0]
	s_nop 0
	v_pk_fma_f32 v[70:71], v[66:67], v[70:71], s[52:53] op_sel_hi:[1,1,0]
	s_nop 0
	v_pk_fma_f32 v[70:71], v[66:67], v[70:71], s[54:55] op_sel_hi:[1,1,0]
	s_nop 0
	v_pk_fma_f32 v[70:71], v[66:67], v[70:71], s[56:57] op_sel_hi:[1,1,0]
	s_nop 0
	v_pk_mul_f32 v[66:67], v[66:67], v[70:71]
	v_pk_mul_f32 v[70:71], v[72:73], s[58:59] op_sel_hi:[1,0]
	v_pk_mul_f32 v[72:73], v[62:63], v[62:63]
	v_exp_f32_e32 v70, v70
	v_exp_f32_e32 v71, v71
	v_pk_mul_f32 v[72:73], v[72:73], s[58:59] op_sel_hi:[1,0]
	v_pk_mul_f32 v[66:67], v[70:71], v[66:67]
	s_nop 0
	v_pk_mul_f32 v[70:71], v[68:69], v[66:67]
	v_pk_fma_f32 v[66:67], v[68:69], v[66:67], v[68:69] neg_lo:[1,0,0] neg_hi:[1,0,0]
	v_exp_f32_e32 v72, v72
	v_cndmask_b32_e32 v70, v66, v70, vcc
	v_cmp_gt_f32_e32 vcc, 0, v69
	v_cvt_pk_bf16_f32 v66, v78, v79
	v_exp_f32_e32 v73, v73
	s_nop 0
	v_cndmask_b32_e32 v69, v67, v71, vcc
	v_cvt_pk_bf16_f32 v67, v76, v77
	v_cvt_pk_bf16_f32 v68, v74, v75
	v_cvt_pk_bf16_f32 v69, v70, v69
	global_store_dwordx4 v[82:83], v[66:69], off offset:256
	v_cmp_gt_f32_e32 vcc, 0, v62
	s_nop 0
	v_and_b32_e32 v69, 0x7fffffff, v63
	v_and_b32_e32 v68, 0x7fffffff, v62
	v_pk_fma_f32 v[68:69], v[68:69], s[28:29], 1.0 op_sel_hi:[1,0,0]
	v_lshl_add_u64 v[66:67], v[150:151], 0, s[4:5]
	v_rcp_f32_e32 v68, v68
	v_rcp_f32_e32 v69, v69
	s_mov_b32 s4, 0x40000
	v_pk_fma_f32 v[70:71], v[68:69], s[30:31], v[122:123] op_sel_hi:[1,0,0]
	s_nop 0
	v_pk_fma_f32 v[70:71], v[68:69], v[70:71], s[52:53] op_sel_hi:[1,1,0]
	s_nop 0
	v_pk_fma_f32 v[70:71], v[68:69], v[70:71], s[54:55] op_sel_hi:[1,1,0]
	s_nop 0
	v_pk_fma_f32 v[70:71], v[68:69], v[70:71], s[56:57] op_sel_hi:[1,1,0]
	s_nop 0
	v_pk_mul_f32 v[68:69], v[68:69], v[70:71]
	v_pk_mul_f32 v[70:71], v[64:65], v[64:65]
	v_pk_mul_f32 v[68:69], v[72:73], v[68:69]
	s_nop 0
	v_pk_mul_f32 v[72:73], v[62:63], v[68:69]
	v_pk_fma_f32 v[68:69], v[62:63], v[68:69], v[62:63] neg_lo:[1,0,0] neg_hi:[1,0,0]
	v_and_b32_e32 v62, 0x7fffffff, v64
	v_cndmask_b32_e32 v72, v68, v72, vcc
	v_cmp_gt_f32_e32 vcc, 0, v63
	v_and_b32_e32 v63, 0x7fffffff, v65
	v_pk_fma_f32 v[62:63], v[62:63], s[28:29], 1.0 op_sel_hi:[1,0,0]
	v_cndmask_b32_e32 v73, v69, v73, vcc
	v_rcp_f32_e32 v62, v62
	v_rcp_f32_e32 v63, v63
	v_cmp_gt_f32_e32 vcc, 0, v64
	v_pk_fma_f32 v[68:69], v[62:63], s[30:31], v[122:123] op_sel_hi:[1,0,0]
	s_nop 0
	v_pk_fma_f32 v[68:69], v[62:63], v[68:69], s[52:53] op_sel_hi:[1,1,0]
	s_nop 0
	v_pk_fma_f32 v[68:69], v[62:63], v[68:69], s[54:55] op_sel_hi:[1,1,0]
	s_nop 0
	v_pk_fma_f32 v[68:69], v[62:63], v[68:69], s[56:57] op_sel_hi:[1,1,0]
	s_nop 0
	v_pk_mul_f32 v[62:63], v[62:63], v[68:69]
	v_pk_mul_f32 v[68:69], v[70:71], s[58:59] op_sel_hi:[1,0]
	s_nop 0
	v_exp_f32_e32 v68, v68
	v_exp_f32_e32 v69, v69
	s_nop 0
	v_pk_mul_f32 v[62:63], v[68:69], v[62:63]
	s_nop 0
	v_pk_mul_f32 v[68:69], v[64:65], v[62:63]
	v_pk_fma_f32 v[62:63], v[64:65], v[62:63], v[64:65] neg_lo:[1,0,0] neg_hi:[1,0,0]
	s_nop 0
	v_cndmask_b32_e32 v70, v62, v68, vcc
	v_cmp_gt_f32_e32 vcc, 0, v65
	v_and_b32_e32 v62, 0x7fffffff, v58
	s_nop 0
	v_cndmask_b32_e32 v71, v63, v69, vcc
	v_and_b32_e32 v63, 0x7fffffff, v59
	v_pk_fma_f32 v[62:63], v[62:63], s[28:29], 1.0 op_sel_hi:[1,0,0]
	v_pk_mul_f32 v[68:69], v[58:59], v[58:59]
	v_rcp_f32_e32 v62, v62
	v_rcp_f32_e32 v63, v63
	v_pk_mul_f32 v[68:69], v[68:69], s[58:59] op_sel_hi:[1,0]
	v_cmp_gt_f32_e32 vcc, 0, v58
	v_exp_f32_e32 v68, v68
	v_pk_fma_f32 v[64:65], v[62:63], s[30:31], v[122:123] op_sel_hi:[1,0,0]
	v_exp_f32_e32 v69, v69
	v_pk_fma_f32 v[64:65], v[62:63], v[64:65], s[52:53] op_sel_hi:[1,1,0]
	s_nop 0
	v_pk_fma_f32 v[64:65], v[62:63], v[64:65], s[54:55] op_sel_hi:[1,1,0]
	s_nop 0
	v_pk_fma_f32 v[64:65], v[62:63], v[64:65], s[56:57] op_sel_hi:[1,1,0]
	s_nop 0
	v_pk_mul_f32 v[62:63], v[62:63], v[64:65]
	v_pk_mul_f32 v[64:65], v[60:61], v[60:61]
	v_pk_mul_f32 v[62:63], v[68:69], v[62:63]
	s_nop 0
	v_pk_mul_f32 v[68:69], v[58:59], v[62:63]
	v_pk_fma_f32 v[62:63], v[58:59], v[62:63], v[58:59] neg_lo:[1,0,0] neg_hi:[1,0,0]
	v_and_b32_e32 v58, 0x7fffffff, v60
	v_cndmask_b32_e32 v68, v62, v68, vcc
	v_cmp_gt_f32_e32 vcc, 0, v59
	v_and_b32_e32 v59, 0x7fffffff, v61
	v_pk_fma_f32 v[58:59], v[58:59], s[28:29], 1.0 op_sel_hi:[1,0,0]
	v_cndmask_b32_e32 v69, v63, v69, vcc
	v_rcp_f32_e32 v58, v58
	v_rcp_f32_e32 v59, v59
	v_cmp_gt_f32_e32 vcc, 0, v60
	v_pk_fma_f32 v[62:63], v[58:59], s[30:31], v[122:123] op_sel_hi:[1,0,0]
	s_nop 0
	v_pk_fma_f32 v[62:63], v[58:59], v[62:63], s[52:53] op_sel_hi:[1,1,0]
	s_nop 0
	v_pk_fma_f32 v[62:63], v[58:59], v[62:63], s[54:55] op_sel_hi:[1,1,0]
	s_nop 0
	v_pk_fma_f32 v[62:63], v[58:59], v[62:63], s[56:57] op_sel_hi:[1,1,0]
	s_nop 0
	v_pk_mul_f32 v[58:59], v[58:59], v[62:63]
	v_pk_mul_f32 v[62:63], v[64:65], s[58:59] op_sel_hi:[1,0]
	s_nop 0
	v_exp_f32_e32 v62, v62
	v_exp_f32_e32 v63, v63
	s_nop 0
	v_pk_mul_f32 v[58:59], v[62:63], v[58:59]
	s_nop 0
	v_pk_mul_f32 v[62:63], v[60:61], v[58:59]
	v_pk_fma_f32 v[58:59], v[60:61], v[58:59], v[60:61] neg_lo:[1,0,0] neg_hi:[1,0,0]
	s_nop 0
	v_cndmask_b32_e32 v62, v58, v62, vcc
	v_cmp_gt_f32_e32 vcc, 0, v61
	v_cvt_pk_bf16_f32 v58, v72, v73
	s_nop 1
	v_cndmask_b32_e32 v61, v59, v63, vcc
	v_cvt_pk_bf16_f32 v59, v70, v71
	v_cvt_pk_bf16_f32 v60, v68, v69
	v_cvt_pk_bf16_f32 v61, v62, v61
	v_add_co_u32_e32 v62, vcc, s4, v150
	s_mov_b64 s[4:5], 0x48000
	s_nop 0
	v_addc_co_u32_e32 v63, vcc, 0, v151, vcc
	global_store_dwordx4 v[62:63], v[58:61], off
	v_pk_mul_f32 v[62:63], v[54:55], v[54:55]
	v_cmp_gt_f32_e32 vcc, 0, v54
	v_and_b32_e32 v59, 0x7fffffff, v55
	v_and_b32_e32 v58, 0x7fffffff, v54
	v_pk_fma_f32 v[58:59], v[58:59], s[28:29], 1.0 op_sel_hi:[1,0,0]
; __device__ __forceinline__ unsigned cvt_pk_bf16(float lo, float hi) { unsigned r; asm volatile("v_cvt_pk_bf16_f32 %0, %1, %2" : "=v"(r) : "v"(lo), "v"(hi)); return r; }
; #define GAS __attribute__((address_space(1)))
; __device__ __forceinline__ f32x2 gelu_pk(f32x2 v) {
;     const f32x2 av = __builtin_elementwise_abs(v), d = av * 0.2316418882f + 1.0f;
;     f32x2 t; t.x = __builtin_amdgcn_rcpf(d.x); t.y = __builtin_amdgcn_rcpf(d.y);
;     f32x2 q = t * 0.5307027145f + (-0.7265760135f); q = q * t + 0.7107068705f; q = q * t + (-0.142248368f); q = q * t + 0.127414796f; q = q * t;
;     const f32x2 s = (v * v) * (-0.72134752044f);
;     f32x2 e; e.x = __builtin_amdgcn_exp2f(s.x); e.y = __builtin_amdgcn_exp2f(s.y);
;     const f32x2 m = v * (q * e), r = v - m;
;     f32x2 o; o.x = v.x < 0.f ? m.x : r.x; o.y = v.y < 0.f ? m.y : r.y; return o;
; }
;     __device__ __forceinline__ void operator()(const f32x4 (&acc)[2][2][4][2], const Unit& u, int wr, int wc, int fr, int fq, const float (&pre)[8]) const {
;     ...
;                     f32x4 v0 = acc[ai][bj][m][0], v1 = acc[ai][bj][m][1];
;                     if (RS == 1) { v0 = v0 * rsc; v1 = v1 * rsc; }
;                     if (RS == 2) { v0 = v0 * csc[bj][0]; v1 = v1 * csc[bj][1]; }
;                     if (ACT == 1) { const f32x2 a = gelu_pk((f32x2){v0[0], v0[1]}), b = gelu_pk((f32x2){v0[2], v0[3]}), c = gelu_pk((f32x2){v1[0], v1[1]}), d = gelu_pk((f32x2){v1[2], v1[3]});
;                         v0 = (f32x4){a.x, a.y, b.x, b.y}; v1 = (f32x4){c.x, c.y, d.x, d.y}; }
;                     v0 = v0 * sc; v1 = v1 * sc;
;                     if (STAT == 1) rs += (v0[0] * v0[0] + v0[1] * v0[1]) + (v0[2] * v0[2] + v0[3] * v0[3]) + (v1[0] * v1[0] + v1[1] * v1[1]) + (v1[2] * v1[2] + v1[3] * v1[3]);
;                     if (STAT == 2) {
; #pragma unroll
;                         for (int e = 0; e < 4; ++e) { cs[bj][0][e] += v0[e]; cq[bj][0][e] += v0[e] * v0[e]; cs[bj][1][e] += v1[e]; cq[bj][1][e] += v1[e] * v1[e]; } }
;                     u32x4 w; w.x = cvt_pk_bf16(v0[0], v0[1]); w.y = cvt_pk_bf16(v0[2], v0[3]); w.z = cvt_pk_bf16(v1[0], v1[1]); w.w = cvt_pk_bf16(v1[2], v1[3]);
;                     *(GAS u32x4*)(rowp + bj * 128) = w; }
	v_pk_mul_f32 v[62:63], v[62:63], s[58:59] op_sel_hi:[1,0]
	v_rcp_f32_e32 v58, v58
	v_rcp_f32_e32 v59, v59
	v_exp_f32_e32 v62, v62
	v_exp_f32_e32 v63, v63
	v_pk_fma_f32 v[60:61], v[58:59], s[30:31], v[122:123] op_sel_hi:[1,0,0]
	s_nop 0
	v_pk_fma_f32 v[60:61], v[58:59], v[60:61], s[52:53] op_sel_hi:[1,1,0]
	s_nop 0
	v_pk_fma_f32 v[60:61], v[58:59], v[60:61], s[54:55] op_sel_hi:[1,1,0]
	s_nop 0
	v_pk_fma_f32 v[60:61], v[58:59], v[60:61], s[56:57] op_sel_hi:[1,1,0]
	s_nop 0
	v_pk_mul_f32 v[58:59], v[58:59], v[60:61]
	v_pk_mul_f32 v[60:61], v[56:57], v[56:57]
	v_pk_mul_f32 v[58:59], v[62:63], v[58:59]
	s_nop 0
	v_pk_mul_f32 v[62:63], v[54:55], v[58:59]
	v_pk_fma_f32 v[58:59], v[54:55], v[58:59], v[54:55] neg_lo:[1,0,0] neg_hi:[1,0,0]
	v_and_b32_e32 v54, 0x7fffffff, v56
	v_cndmask_b32_e32 v62, v58, v62, vcc
	v_cmp_gt_f32_e32 vcc, 0, v55
	v_and_b32_e32 v55, 0x7fffffff, v57
	v_pk_fma_f32 v[54:55], v[54:55], s[28:29], 1.0 op_sel_hi:[1,0,0]
	v_cndmask_b32_e32 v63, v59, v63, vcc
	v_rcp_f32_e32 v54, v54
	v_rcp_f32_e32 v55, v55
	v_cmp_gt_f32_e32 vcc, 0, v56
	v_pk_fma_f32 v[58:59], v[54:55], s[30:31], v[122:123] op_sel_hi:[1,0,0]
	s_nop 0
	v_pk_fma_f32 v[58:59], v[54:55], v[58:59], s[52:53] op_sel_hi:[1,1,0]
	s_nop 0
	v_pk_fma_f32 v[58:59], v[54:55], v[58:59], s[54:55] op_sel_hi:[1,1,0]
	s_nop 0
	v_pk_fma_f32 v[58:59], v[54:55], v[58:59], s[56:57] op_sel_hi:[1,1,0]
	s_nop 0
	v_pk_mul_f32 v[54:55], v[54:55], v[58:59]
	v_pk_mul_f32 v[58:59], v[60:61], s[58:59] op_sel_hi:[1,0]
	s_nop 0
	v_exp_f32_e32 v58, v58
	v_exp_f32_e32 v59, v59
	s_nop 0
	v_pk_mul_f32 v[54:55], v[58:59], v[54:55]
	s_nop 0
	v_pk_mul_f32 v[58:59], v[56:57], v[54:55]
	v_pk_fma_f32 v[54:55], v[56:57], v[54:55], v[56:57] neg_lo:[1,0,0] neg_hi:[1,0,0]
	s_nop 0
	v_cndmask_b32_e32 v60, v54, v58, vcc
	v_cmp_gt_f32_e32 vcc, 0, v57
	v_and_b32_e32 v54, 0x7fffffff, v50
	s_nop 0
	v_cndmask_b32_e32 v61, v55, v59, vcc
	v_and_b32_e32 v55, 0x7fffffff, v51
	v_pk_fma_f32 v[54:55], v[54:55], s[28:29], 1.0 op_sel_hi:[1,0,0]
	v_pk_mul_f32 v[58:59], v[50:51], v[50:51]
	v_rcp_f32_e32 v54, v54
	v_rcp_f32_e32 v55, v55
	v_pk_mul_f32 v[58:59], v[58:59], s[58:59] op_sel_hi:[1,0]
	v_cmp_gt_f32_e32 vcc, 0, v50
	v_exp_f32_e32 v58, v58
	v_pk_fma_f32 v[56:57], v[54:55], s[30:31], v[122:123] op_sel_hi:[1,0,0]
	v_exp_f32_e32 v59, v59
	v_pk_fma_f32 v[56:57], v[54:55], v[56:57], s[52:53] op_sel_hi:[1,1,0]
	s_nop 0
	v_pk_fma_f32 v[56:57], v[54:55], v[56:57], s[54:55] op_sel_hi:[1,1,0]
	s_nop 0
	v_pk_fma_f32 v[56:57], v[54:55], v[56:57], s[56:57] op_sel_hi:[1,1,0]
	s_nop 0
	v_pk_mul_f32 v[54:55], v[54:55], v[56:57]
	v_pk_mul_f32 v[56:57], v[52:53], v[52:53]
	v_pk_mul_f32 v[54:55], v[58:59], v[54:55]
	s_nop 0
	v_pk_mul_f32 v[58:59], v[50:51], v[54:55]
	v_pk_fma_f32 v[54:55], v[50:51], v[54:55], v[50:51] neg_lo:[1,0,0] neg_hi:[1,0,0]
	v_and_b32_e32 v50, 0x7fffffff, v52
	v_cndmask_b32_e32 v58, v54, v58, vcc
	v_cmp_gt_f32_e32 vcc, 0, v51
	v_and_b32_e32 v51, 0x7fffffff, v53
	v_pk_fma_f32 v[50:51], v[50:51], s[28:29], 1.0 op_sel_hi:[1,0,0]
	v_cndmask_b32_e32 v59, v55, v59, vcc
	v_rcp_f32_e32 v50, v50
	v_rcp_f32_e32 v51, v51
	v_cmp_gt_f32_e32 vcc, 0, v52
	v_pk_fma_f32 v[54:55], v[50:51], s[30:31], v[122:123] op_sel_hi:[1,0,0]
	s_nop 0
	v_pk_fma_f32 v[54:55], v[50:51], v[54:55], s[52:53] op_sel_hi:[1,1,0]
	s_nop 0
	v_pk_fma_f32 v[54:55], v[50:51], v[54:55], s[54:55] op_sel_hi:[1,1,0]
	s_nop 0
	v_pk_fma_f32 v[54:55], v[50:51], v[54:55], s[56:57] op_sel_hi:[1,1,0]
	s_nop 0
	v_pk_mul_f32 v[50:51], v[50:51], v[54:55]
	v_pk_mul_f32 v[54:55], v[56:57], s[58:59] op_sel_hi:[1,0]
	v_pk_mul_f32 v[56:57], v[46:47], v[46:47]
	v_exp_f32_e32 v54, v54
	v_exp_f32_e32 v55, v55
	v_pk_mul_f32 v[56:57], v[56:57], s[58:59] op_sel_hi:[1,0]
	v_pk_mul_f32 v[50:51], v[54:55], v[50:51]
	s_nop 0
	v_pk_mul_f32 v[54:55], v[52:53], v[50:51]
	v_pk_fma_f32 v[50:51], v[52:53], v[50:51], v[52:53] neg_lo:[1,0,0] neg_hi:[1,0,0]
	v_exp_f32_e32 v56, v56
	v_cndmask_b32_e32 v54, v50, v54, vcc
	v_cmp_gt_f32_e32 vcc, 0, v53
	v_cvt_pk_bf16_f32 v50, v62, v63
	v_exp_f32_e32 v57, v57
	s_nop 0
	v_cndmask_b32_e32 v53, v51, v55, vcc
	v_cvt_pk_bf16_f32 v51, v60, v61
	v_cvt_pk_bf16_f32 v52, v58, v59
	v_cvt_pk_bf16_f32 v53, v54, v53
	global_store_dwordx4 v[66:67], v[50:53], off offset:256
	v_cmp_gt_f32_e32 vcc, 0, v46
	s_nop 0
	v_and_b32_e32 v53, 0x7fffffff, v47
	v_and_b32_e32 v52, 0x7fffffff, v46
	v_pk_fma_f32 v[52:53], v[52:53], s[28:29], 1.0 op_sel_hi:[1,0,0]
	v_lshl_add_u64 v[50:51], v[150:151], 0, s[4:5]
	v_rcp_f32_e32 v52, v52
	v_rcp_f32_e32 v53, v53
	s_mov_b32 s4, 0x48000
	v_pk_fma_f32 v[54:55], v[52:53], s[30:31], v[122:123] op_sel_hi:[1,0,0]
	s_nop 0
	v_pk_fma_f32 v[54:55], v[52:53], v[54:55], s[52:53] op_sel_hi:[1,1,0]
	s_nop 0
	v_pk_fma_f32 v[54:55], v[52:53], v[54:55], s[54:55] op_sel_hi:[1,1,0]
	s_nop 0
	v_pk_fma_f32 v[54:55], v[52:53], v[54:55], s[56:57] op_sel_hi:[1,1,0]
	s_nop 0
	v_pk_mul_f32 v[52:53], v[52:53], v[54:55]
	v_pk_mul_f32 v[54:55], v[48:49], v[48:49]
	v_pk_mul_f32 v[52:53], v[56:57], v[52:53]
	s_nop 0
	v_pk_mul_f32 v[56:57], v[46:47], v[52:53]
	v_pk_fma_f32 v[52:53], v[46:47], v[52:53], v[46:47] neg_lo:[1,0,0] neg_hi:[1,0,0]
	v_and_b32_e32 v46, 0x7fffffff, v48
	v_cndmask_b32_e32 v56, v52, v56, vcc
	v_cmp_gt_f32_e32 vcc, 0, v47
	v_and_b32_e32 v47, 0x7fffffff, v49
	v_pk_fma_f32 v[46:47], v[46:47], s[28:29], 1.0 op_sel_hi:[1,0,0]
	v_cndmask_b32_e32 v57, v53, v57, vcc
	v_rcp_f32_e32 v46, v46
	v_rcp_f32_e32 v47, v47
	v_cmp_gt_f32_e32 vcc, 0, v48
	v_pk_fma_f32 v[52:53], v[46:47], s[30:31], v[122:123] op_sel_hi:[1,0,0]
	s_nop 0
	v_pk_fma_f32 v[52:53], v[46:47], v[52:53], s[52:53] op_sel_hi:[1,1,0]
	s_nop 0
	v_pk_fma_f32 v[52:53], v[46:47], v[52:53], s[54:55] op_sel_hi:[1,1,0]
; __device__ __forceinline__ unsigned cvt_pk_bf16(float lo, float hi) { unsigned r; asm volatile("v_cvt_pk_bf16_f32 %0, %1, %2" : "=v"(r) : "v"(lo), "v"(hi)); return r; }
; #define GAS __attribute__((address_space(1)))
; __device__ __forceinline__ f32x2 gelu_pk(f32x2 v) {
;     const f32x2 av = __builtin_elementwise_abs(v), d = av * 0.2316418882f + 1.0f;
;     f32x2 t; t.x = __builtin_amdgcn_rcpf(d.x); t.y = __builtin_amdgcn_rcpf(d.y);
;     f32x2 q = t * 0.5307027145f + (-0.7265760135f); q = q * t + 0.7107068705f; q = q * t + (-0.142248368f); q = q * t + 0.127414796f; q = q * t;
;     const f32x2 s = (v * v) * (-0.72134752044f);
;     f32x2 e; e.x = __builtin_amdgcn_exp2f(s.x); e.y = __builtin_amdgcn_exp2f(s.y);
;     const f32x2 m = v * (q * e), r = v - m;
;     f32x2 o; o.x = v.x < 0.f ? m.x : r.x; o.y = v.y < 0.f ? m.y : r.y; return o;
; }
;     __device__ __forceinline__ void operator()(const f32x4 (&acc)[2][2][4][2], const Unit& u, int wr, int wc, int fr, int fq, const float (&pre)[8]) const {
;     ...
;                     f32x4 v0 = acc[ai][bj][m][0], v1 = acc[ai][bj][m][1];
;                     if (RS == 1) { v0 = v0 * rsc; v1 = v1 * rsc; }
;                     if (RS == 2) { v0 = v0 * csc[bj][0]; v1 = v1 * csc[bj][1]; }
;                     if (ACT == 1) { const f32x2 a = gelu_pk((f32x2){v0[0], v0[1]}), b = gelu_pk((f32x2){v0[2], v0[3]}), c = gelu_pk((f32x2){v1[0], v1[1]}), d = gelu_pk((f32x2){v1[2], v1[3]});
;                         v0 = (f32x4){a.x, a.y, b.x, b.y}; v1 = (f32x4){c.x, c.y, d.x, d.y}; }
;                     v0 = v0 * sc; v1 = v1 * sc;
;                     if (STAT == 1) rs += (v0[0] * v0[0] + v0[1] * v0[1]) + (v0[2] * v0[2] + v0[3] * v0[3]) + (v1[0] * v1[0] + v1[1] * v1[1]) + (v1[2] * v1[2] + v1[3] * v1[3]);
;                     if (STAT == 2) {
; #pragma unroll
;                         for (int e = 0; e < 4; ++e) { cs[bj][0][e] += v0[e]; cq[bj][0][e] += v0[e] * v0[e]; cs[bj][1][e] += v1[e]; cq[bj][1][e] += v1[e] * v1[e]; } }
;                     u32x4 w; w.x = cvt_pk_bf16(v0[0], v0[1]); w.y = cvt_pk_bf16(v0[2], v0[3]); w.z = cvt_pk_bf16(v1[0], v1[1]); w.w = cvt_pk_bf16(v1[2], v1[3]);
;                     *(GAS u32x4*)(rowp + bj * 128) = w; }
	s_nop 0
	v_pk_fma_f32 v[52:53], v[46:47], v[52:53], s[56:57] op_sel_hi:[1,1,0]
	s_nop 0
	v_pk_mul_f32 v[46:47], v[46:47], v[52:53]
	v_pk_mul_f32 v[52:53], v[54:55], s[58:59] op_sel_hi:[1,0]
	s_nop 0
	v_exp_f32_e32 v52, v52
	v_exp_f32_e32 v53, v53
	s_nop 0
	v_pk_mul_f32 v[46:47], v[52:53], v[46:47]
	s_nop 0
	v_pk_mul_f32 v[52:53], v[48:49], v[46:47]
	v_pk_fma_f32 v[46:47], v[48:49], v[46:47], v[48:49] neg_lo:[1,0,0] neg_hi:[1,0,0]
	s_nop 0
	v_cndmask_b32_e32 v54, v46, v52, vcc
	v_cmp_gt_f32_e32 vcc, 0, v49
	v_and_b32_e32 v46, 0x7fffffff, v42
	s_nop 0
	v_cndmask_b32_e32 v55, v47, v53, vcc
	v_and_b32_e32 v47, 0x7fffffff, v43
	v_pk_fma_f32 v[46:47], v[46:47], s[28:29], 1.0 op_sel_hi:[1,0,0]
	v_pk_mul_f32 v[52:53], v[42:43], v[42:43]
	v_rcp_f32_e32 v46, v46
	v_rcp_f32_e32 v47, v47
	v_pk_mul_f32 v[52:53], v[52:53], s[58:59] op_sel_hi:[1,0]
	v_cmp_gt_f32_e32 vcc, 0, v42
	v_exp_f32_e32 v52, v52
	v_pk_fma_f32 v[48:49], v[46:47], s[30:31], v[122:123] op_sel_hi:[1,0,0]
	v_exp_f32_e32 v53, v53
	v_pk_fma_f32 v[48:49], v[46:47], v[48:49], s[52:53] op_sel_hi:[1,1,0]
	s_nop 0
	v_pk_fma_f32 v[48:49], v[46:47], v[48:49], s[54:55] op_sel_hi:[1,1,0]
	s_nop 0
	v_pk_fma_f32 v[48:49], v[46:47], v[48:49], s[56:57] op_sel_hi:[1,1,0]
	s_nop 0
	v_pk_mul_f32 v[46:47], v[46:47], v[48:49]
	v_pk_mul_f32 v[48:49], v[44:45], v[44:45]
	v_pk_mul_f32 v[46:47], v[52:53], v[46:47]
	s_nop 0
	v_pk_mul_f32 v[52:53], v[42:43], v[46:47]
	v_pk_fma_f32 v[46:47], v[42:43], v[46:47], v[42:43] neg_lo:[1,0,0] neg_hi:[1,0,0]
	v_and_b32_e32 v42, 0x7fffffff, v44
	v_cndmask_b32_e32 v52, v46, v52, vcc
	v_cmp_gt_f32_e32 vcc, 0, v43
	v_and_b32_e32 v43, 0x7fffffff, v45
	v_pk_fma_f32 v[42:43], v[42:43], s[28:29], 1.0 op_sel_hi:[1,0,0]
	v_cndmask_b32_e32 v53, v47, v53, vcc
	v_rcp_f32_e32 v42, v42
	v_rcp_f32_e32 v43, v43
	v_cmp_gt_f32_e32 vcc, 0, v44
	v_pk_fma_f32 v[46:47], v[42:43], s[30:31], v[122:123] op_sel_hi:[1,0,0]
	s_nop 0
	v_pk_fma_f32 v[46:47], v[42:43], v[46:47], s[52:53] op_sel_hi:[1,1,0]
	s_nop 0
	v_pk_fma_f32 v[46:47], v[42:43], v[46:47], s[54:55] op_sel_hi:[1,1,0]
	s_nop 0
	v_pk_fma_f32 v[46:47], v[42:43], v[46:47], s[56:57] op_sel_hi:[1,1,0]
	s_nop 0
	v_pk_mul_f32 v[42:43], v[42:43], v[46:47]
	v_pk_mul_f32 v[46:47], v[48:49], s[58:59] op_sel_hi:[1,0]
	s_nop 0
	v_exp_f32_e32 v46, v46
	v_exp_f32_e32 v47, v47
	s_nop 0
	v_pk_mul_f32 v[42:43], v[46:47], v[42:43]
	s_nop 0
	v_pk_mul_f32 v[46:47], v[44:45], v[42:43]
	v_pk_fma_f32 v[42:43], v[44:45], v[42:43], v[44:45] neg_lo:[1,0,0] neg_hi:[1,0,0]
	s_nop 0
	v_cndmask_b32_e32 v46, v42, v46, vcc
	v_cmp_gt_f32_e32 vcc, 0, v45
	v_cvt_pk_bf16_f32 v42, v56, v57
	s_nop 1
	v_cndmask_b32_e32 v45, v43, v47, vcc
	v_cvt_pk_bf16_f32 v43, v54, v55
	v_cvt_pk_bf16_f32 v44, v52, v53
	v_cvt_pk_bf16_f32 v45, v46, v45
	v_add_co_u32_e32 v46, vcc, s4, v150
	s_mov_b64 s[4:5], 0x50000
	s_nop 0
	v_addc_co_u32_e32 v47, vcc, 0, v151, vcc
	global_store_dwordx4 v[46:47], v[42:45], off
	v_pk_mul_f32 v[46:47], v[38:39], v[38:39]
	v_cmp_gt_f32_e32 vcc, 0, v38
	v_and_b32_e32 v43, 0x7fffffff, v39
	v_and_b32_e32 v42, 0x7fffffff, v38
	v_pk_fma_f32 v[42:43], v[42:43], s[28:29], 1.0 op_sel_hi:[1,0,0]
	v_pk_mul_f32 v[46:47], v[46:47], s[58:59] op_sel_hi:[1,0]
	v_rcp_f32_e32 v42, v42
	v_rcp_f32_e32 v43, v43
	v_exp_f32_e32 v46, v46
	v_exp_f32_e32 v47, v47
	v_pk_fma_f32 v[44:45], v[42:43], s[30:31], v[122:123] op_sel_hi:[1,0,0]
	s_nop 0
	v_pk_fma_f32 v[44:45], v[42:43], v[44:45], s[52:53] op_sel_hi:[1,1,0]
	s_nop 0
	v_pk_fma_f32 v[44:45], v[42:43], v[44:45], s[54:55] op_sel_hi:[1,1,0]
	s_nop 0
	v_pk_fma_f32 v[44:45], v[42:43], v[44:45], s[56:57] op_sel_hi:[1,1,0]
	s_nop 0
	v_pk_mul_f32 v[42:43], v[42:43], v[44:45]
	v_pk_mul_f32 v[44:45], v[40:41], v[40:41]
	v_pk_mul_f32 v[42:43], v[46:47], v[42:43]
	s_nop 0
	v_pk_mul_f32 v[46:47], v[38:39], v[42:43]
	v_pk_fma_f32 v[42:43], v[38:39], v[42:43], v[38:39] neg_lo:[1,0,0] neg_hi:[1,0,0]
	v_and_b32_e32 v38, 0x7fffffff, v40
	v_cndmask_b32_e32 v46, v42, v46, vcc
	v_cmp_gt_f32_e32 vcc, 0, v39
	v_and_b32_e32 v39, 0x7fffffff, v41
	v_pk_fma_f32 v[38:39], v[38:39], s[28:29], 1.0 op_sel_hi:[1,0,0]
	v_cndmask_b32_e32 v47, v43, v47, vcc
	v_rcp_f32_e32 v38, v38
	v_rcp_f32_e32 v39, v39
	v_cmp_gt_f32_e32 vcc, 0, v40
	v_pk_fma_f32 v[42:43], v[38:39], s[30:31], v[122:123] op_sel_hi:[1,0,0]
	s_nop 0
	v_pk_fma_f32 v[42:43], v[38:39], v[42:43], s[52:53] op_sel_hi:[1,1,0]
	s_nop 0
	v_pk_fma_f32 v[42:43], v[38:39], v[42:43], s[54:55] op_sel_hi:[1,1,0]
	s_nop 0
	v_pk_fma_f32 v[42:43], v[38:39], v[42:43], s[56:57] op_sel_hi:[1,1,0]
	s_nop 0
	v_pk_mul_f32 v[38:39], v[38:39], v[42:43]
	v_pk_mul_f32 v[42:43], v[44:45], s[58:59] op_sel_hi:[1,0]
	s_nop 0
	v_exp_f32_e32 v42, v42
	v_exp_f32_e32 v43, v43
	s_nop 0
	v_pk_mul_f32 v[38:39], v[42:43], v[38:39]
	s_nop 0
	v_pk_mul_f32 v[42:43], v[40:41], v[38:39]
	v_pk_fma_f32 v[38:39], v[40:41], v[38:39], v[40:41] neg_lo:[1,0,0] neg_hi:[1,0,0]
	s_nop 0
	v_cndmask_b32_e32 v44, v38, v42, vcc
	v_cmp_gt_f32_e32 vcc, 0, v41
	v_and_b32_e32 v38, 0x7fffffff, v34
	s_nop 0
	v_cndmask_b32_e32 v45, v39, v43, vcc
	v_and_b32_e32 v39, 0x7fffffff, v35
	v_pk_fma_f32 v[38:39], v[38:39], s[28:29], 1.0 op_sel_hi:[1,0,0]
	v_pk_mul_f32 v[42:43], v[34:35], v[34:35]
	v_rcp_f32_e32 v38, v38
	v_rcp_f32_e32 v39, v39
	v_pk_mul_f32 v[42:43], v[42:43], s[58:59] op_sel_hi:[1,0]
	v_cmp_gt_f32_e32 vcc, 0, v34
	v_exp_f32_e32 v42, v42
	v_pk_fma_f32 v[40:41], v[38:39], s[30:31], v[122:123] op_sel_hi:[1,0,0]
	v_exp_f32_e32 v43, v43
	v_pk_fma_f32 v[40:41], v[38:39], v[40:41], s[52:53] op_sel_hi:[1,1,0]
	s_nop 0
	v_pk_fma_f32 v[40:41], v[38:39], v[40:41], s[54:55] op_sel_hi:[1,1,0]
	s_nop 0
	v_pk_fma_f32 v[40:41], v[38:39], v[40:41], s[56:57] op_sel_hi:[1,1,0]
; __device__ __forceinline__ unsigned cvt_pk_bf16(float lo, float hi) { unsigned r; asm volatile("v_cvt_pk_bf16_f32 %0, %1, %2" : "=v"(r) : "v"(lo), "v"(hi)); return r; }
; #define GAS __attribute__((address_space(1)))
; __device__ __forceinline__ f32x2 gelu_pk(f32x2 v) {
;     const f32x2 av = __builtin_elementwise_abs(v), d = av * 0.2316418882f + 1.0f;
;     f32x2 t; t.x = __builtin_amdgcn_rcpf(d.x); t.y = __builtin_amdgcn_rcpf(d.y);
;     f32x2 q = t * 0.5307027145f + (-0.7265760135f); q = q * t + 0.7107068705f; q = q * t + (-0.142248368f); q = q * t + 0.127414796f; q = q * t;
;     const f32x2 s = (v * v) * (-0.72134752044f);
;     f32x2 e; e.x = __builtin_amdgcn_exp2f(s.x); e.y = __builtin_amdgcn_exp2f(s.y);
;     const f32x2 m = v * (q * e), r = v - m;
;     f32x2 o; o.x = v.x < 0.f ? m.x : r.x; o.y = v.y < 0.f ? m.y : r.y; return o;
; }
;     __device__ __forceinline__ void operator()(const f32x4 (&acc)[2][2][4][2], const Unit& u, int wr, int wc, int fr, int fq, const float (&pre)[8]) const {
;     ...
;                     f32x4 v0 = acc[ai][bj][m][0], v1 = acc[ai][bj][m][1];
;                     if (RS == 1) { v0 = v0 * rsc; v1 = v1 * rsc; }
;                     if (RS == 2) { v0 = v0 * csc[bj][0]; v1 = v1 * csc[bj][1]; }
;                     if (ACT == 1) { const f32x2 a = gelu_pk((f32x2){v0[0], v0[1]}), b = gelu_pk((f32x2){v0[2], v0[3]}), c = gelu_pk((f32x2){v1[0], v1[1]}), d = gelu_pk((f32x2){v1[2], v1[3]});
;                         v0 = (f32x4){a.x, a.y, b.x, b.y}; v1 = (f32x4){c.x, c.y, d.x, d.y}; }
;                     v0 = v0 * sc; v1 = v1 * sc;
;                     if (STAT == 1) rs += (v0[0] * v0[0] + v0[1] * v0[1]) + (v0[2] * v0[2] + v0[3] * v0[3]) + (v1[0] * v1[0] + v1[1] * v1[1]) + (v1[2] * v1[2] + v1[3] * v1[3]);
;                     if (STAT == 2) {
; #pragma unroll
;                         for (int e = 0; e < 4; ++e) { cs[bj][0][e] += v0[e]; cq[bj][0][e] += v0[e] * v0[e]; cs[bj][1][e] += v1[e]; cq[bj][1][e] += v1[e] * v1[e]; } }
;                     u32x4 w; w.x = cvt_pk_bf16(v0[0], v0[1]); w.y = cvt_pk_bf16(v0[2], v0[3]); w.z = cvt_pk_bf16(v1[0], v1[1]); w.w = cvt_pk_bf16(v1[2], v1[3]);
;                     *(GAS u32x4*)(rowp + bj * 128) = w; }
	s_nop 0
	v_pk_mul_f32 v[38:39], v[38:39], v[40:41]
	v_pk_mul_f32 v[40:41], v[36:37], v[36:37]
	v_pk_mul_f32 v[38:39], v[42:43], v[38:39]
	s_nop 0
	v_pk_mul_f32 v[42:43], v[34:35], v[38:39]
	v_pk_fma_f32 v[38:39], v[34:35], v[38:39], v[34:35] neg_lo:[1,0,0] neg_hi:[1,0,0]
	v_and_b32_e32 v34, 0x7fffffff, v36
	v_cndmask_b32_e32 v42, v38, v42, vcc
	v_cmp_gt_f32_e32 vcc, 0, v35
	v_and_b32_e32 v35, 0x7fffffff, v37
	v_pk_fma_f32 v[34:35], v[34:35], s[28:29], 1.0 op_sel_hi:[1,0,0]
	v_cndmask_b32_e32 v43, v39, v43, vcc
	v_rcp_f32_e32 v34, v34
	v_rcp_f32_e32 v35, v35
	v_cmp_gt_f32_e32 vcc, 0, v36
	v_pk_fma_f32 v[38:39], v[34:35], s[30:31], v[122:123] op_sel_hi:[1,0,0]
	s_nop 0
	v_pk_fma_f32 v[38:39], v[34:35], v[38:39], s[52:53] op_sel_hi:[1,1,0]
	s_nop 0
	v_pk_fma_f32 v[38:39], v[34:35], v[38:39], s[54:55] op_sel_hi:[1,1,0]
	s_nop 0
	v_pk_fma_f32 v[38:39], v[34:35], v[38:39], s[56:57] op_sel_hi:[1,1,0]
	s_nop 0
	v_pk_mul_f32 v[34:35], v[34:35], v[38:39]
	v_pk_mul_f32 v[38:39], v[40:41], s[58:59] op_sel_hi:[1,0]
	v_pk_mul_f32 v[40:41], v[28:29], v[28:29]
	v_exp_f32_e32 v38, v38
	v_exp_f32_e32 v39, v39
	v_pk_mul_f32 v[40:41], v[40:41], s[58:59] op_sel_hi:[1,0]
	v_pk_mul_f32 v[34:35], v[38:39], v[34:35]
	s_nop 0
	v_pk_mul_f32 v[38:39], v[36:37], v[34:35]
	v_pk_fma_f32 v[34:35], v[36:37], v[34:35], v[36:37] neg_lo:[1,0,0] neg_hi:[1,0,0]
	v_exp_f32_e32 v40, v40
	v_cndmask_b32_e32 v38, v34, v38, vcc
	v_cmp_gt_f32_e32 vcc, 0, v37
	v_cvt_pk_bf16_f32 v34, v46, v47
	v_exp_f32_e32 v41, v41
	s_nop 0
	v_cndmask_b32_e32 v37, v35, v39, vcc
	v_cvt_pk_bf16_f32 v35, v44, v45
	v_cvt_pk_bf16_f32 v36, v42, v43
	v_cvt_pk_bf16_f32 v37, v38, v37
	global_store_dwordx4 v[50:51], v[34:37], off offset:256
	v_cmp_gt_f32_e32 vcc, 0, v28
	s_nop 0
	v_and_b32_e32 v37, 0x7fffffff, v29
	v_and_b32_e32 v36, 0x7fffffff, v28
	v_pk_fma_f32 v[36:37], v[36:37], s[28:29], 1.0 op_sel_hi:[1,0,0]
	v_lshl_add_u64 v[34:35], v[150:151], 0, s[4:5]
	v_rcp_f32_e32 v36, v36
	v_rcp_f32_e32 v37, v37
	s_mov_b32 s4, 0x50000
	v_pk_fma_f32 v[38:39], v[36:37], s[30:31], v[122:123] op_sel_hi:[1,0,0]
	s_nop 0
	v_pk_fma_f32 v[38:39], v[36:37], v[38:39], s[52:53] op_sel_hi:[1,1,0]
	s_nop 0
	v_pk_fma_f32 v[38:39], v[36:37], v[38:39], s[54:55] op_sel_hi:[1,1,0]
	s_nop 0
	v_pk_fma_f32 v[38:39], v[36:37], v[38:39], s[56:57] op_sel_hi:[1,1,0]
	s_nop 0
	v_pk_mul_f32 v[36:37], v[36:37], v[38:39]
	v_pk_mul_f32 v[38:39], v[30:31], v[30:31]
	v_pk_mul_f32 v[36:37], v[40:41], v[36:37]
	s_nop 0
	v_pk_mul_f32 v[40:41], v[28:29], v[36:37]
	v_pk_fma_f32 v[36:37], v[28:29], v[36:37], v[28:29] neg_lo:[1,0,0] neg_hi:[1,0,0]
	v_and_b32_e32 v28, 0x7fffffff, v30
	v_cndmask_b32_e32 v40, v36, v40, vcc
	v_cmp_gt_f32_e32 vcc, 0, v29
	v_and_b32_e32 v29, 0x7fffffff, v31
	v_pk_fma_f32 v[28:29], v[28:29], s[28:29], 1.0 op_sel_hi:[1,0,0]
	v_cndmask_b32_e32 v41, v37, v41, vcc
	v_rcp_f32_e32 v28, v28
	v_rcp_f32_e32 v29, v29
	v_cmp_gt_f32_e32 vcc, 0, v30
	v_pk_fma_f32 v[36:37], v[28:29], s[30:31], v[122:123] op_sel_hi:[1,0,0]
	s_nop 0
	v_pk_fma_f32 v[36:37], v[28:29], v[36:37], s[52:53] op_sel_hi:[1,1,0]
	s_nop 0
	v_pk_fma_f32 v[36:37], v[28:29], v[36:37], s[54:55] op_sel_hi:[1,1,0]
	s_nop 0
	v_pk_fma_f32 v[36:37], v[28:29], v[36:37], s[56:57] op_sel_hi:[1,1,0]
	s_nop 0
	v_pk_mul_f32 v[28:29], v[28:29], v[36:37]
	v_pk_mul_f32 v[36:37], v[38:39], s[58:59] op_sel_hi:[1,0]
	s_nop 0
	v_exp_f32_e32 v36, v36
	v_exp_f32_e32 v37, v37
	s_nop 0
	v_pk_mul_f32 v[28:29], v[36:37], v[28:29]
	s_nop 0
	v_pk_mul_f32 v[36:37], v[30:31], v[28:29]
	v_pk_fma_f32 v[28:29], v[30:31], v[28:29], v[30:31] neg_lo:[1,0,0] neg_hi:[1,0,0]
	s_nop 0
	v_cndmask_b32_e32 v38, v28, v36, vcc
	v_cmp_gt_f32_e32 vcc, 0, v31
	v_and_b32_e32 v28, 0x7fffffff, v24
	s_nop 0
	v_cndmask_b32_e32 v39, v29, v37, vcc
	v_and_b32_e32 v29, 0x7fffffff, v25
	v_pk_fma_f32 v[28:29], v[28:29], s[28:29], 1.0 op_sel_hi:[1,0,0]
	v_pk_mul_f32 v[36:37], v[24:25], v[24:25]
	v_rcp_f32_e32 v28, v28
	v_rcp_f32_e32 v29, v29
	v_pk_mul_f32 v[36:37], v[36:37], s[58:59] op_sel_hi:[1,0]
	v_cmp_gt_f32_e32 vcc, 0, v24
	v_exp_f32_e32 v36, v36
	v_pk_fma_f32 v[30:31], v[28:29], s[30:31], v[122:123] op_sel_hi:[1,0,0]
	v_exp_f32_e32 v37, v37
	v_pk_fma_f32 v[30:31], v[28:29], v[30:31], s[52:53] op_sel_hi:[1,1,0]
	s_nop 0
	v_pk_fma_f32 v[30:31], v[28:29], v[30:31], s[54:55] op_sel_hi:[1,1,0]
	s_nop 0
	v_pk_fma_f32 v[30:31], v[28:29], v[30:31], s[56:57] op_sel_hi:[1,1,0]
	s_nop 0
	v_pk_mul_f32 v[28:29], v[28:29], v[30:31]
	v_pk_mul_f32 v[30:31], v[26:27], v[26:27]
	v_pk_mul_f32 v[28:29], v[36:37], v[28:29]
	s_nop 0
	v_pk_mul_f32 v[36:37], v[24:25], v[28:29]
	v_pk_fma_f32 v[28:29], v[24:25], v[28:29], v[24:25] neg_lo:[1,0,0] neg_hi:[1,0,0]
	v_and_b32_e32 v24, 0x7fffffff, v26
	v_cndmask_b32_e32 v36, v28, v36, vcc
	v_cmp_gt_f32_e32 vcc, 0, v25
	v_and_b32_e32 v25, 0x7fffffff, v27
	v_pk_fma_f32 v[24:25], v[24:25], s[28:29], 1.0 op_sel_hi:[1,0,0]
	v_cndmask_b32_e32 v37, v29, v37, vcc
	v_rcp_f32_e32 v24, v24
	v_rcp_f32_e32 v25, v25
	v_cmp_gt_f32_e32 vcc, 0, v26
	v_pk_fma_f32 v[28:29], v[24:25], s[30:31], v[122:123] op_sel_hi:[1,0,0]
	s_nop 0
	v_pk_fma_f32 v[28:29], v[24:25], v[28:29], s[52:53] op_sel_hi:[1,1,0]
	s_nop 0
	v_pk_fma_f32 v[28:29], v[24:25], v[28:29], s[54:55] op_sel_hi:[1,1,0]
	s_nop 0
	v_pk_fma_f32 v[28:29], v[24:25], v[28:29], s[56:57] op_sel_hi:[1,1,0]
	s_nop 0
	v_pk_mul_f32 v[24:25], v[24:25], v[28:29]
	v_pk_mul_f32 v[28:29], v[30:31], s[58:59] op_sel_hi:[1,0]
	s_nop 0
	v_exp_f32_e32 v28, v28
	v_exp_f32_e32 v29, v29
	s_nop 0
	v_pk_mul_f32 v[24:25], v[28:29], v[24:25]
	s_nop 0
	v_pk_mul_f32 v[28:29], v[26:27], v[24:25]
	v_pk_fma_f32 v[24:25], v[26:27], v[24:25], v[26:27] neg_lo:[1,0,0] neg_hi:[1,0,0]
	s_nop 0
; __device__ __forceinline__ unsigned cvt_pk_bf16(float lo, float hi) { unsigned r; asm volatile("v_cvt_pk_bf16_f32 %0, %1, %2" : "=v"(r) : "v"(lo), "v"(hi)); return r; }
; #define GAS __attribute__((address_space(1)))
; __device__ __forceinline__ f32x2 gelu_pk(f32x2 v) {
;     const f32x2 av = __builtin_elementwise_abs(v), d = av * 0.2316418882f + 1.0f;
;     f32x2 t; t.x = __builtin_amdgcn_rcpf(d.x); t.y = __builtin_amdgcn_rcpf(d.y);
;     f32x2 q = t * 0.5307027145f + (-0.7265760135f); q = q * t + 0.7107068705f; q = q * t + (-0.142248368f); q = q * t + 0.127414796f; q = q * t;
;     const f32x2 s = (v * v) * (-0.72134752044f);
;     f32x2 e; e.x = __builtin_amdgcn_exp2f(s.x); e.y = __builtin_amdgcn_exp2f(s.y);
;     const f32x2 m = v * (q * e), r = v - m;
;     f32x2 o; o.x = v.x < 0.f ? m.x : r.x; o.y = v.y < 0.f ? m.y : r.y; return o;
; }
;     __device__ __forceinline__ void operator()(const f32x4 (&acc)[2][2][4][2], const Unit& u, int wr, int wc, int fr, int fq, const float (&pre)[8]) const {
;     ...
;                     f32x4 v0 = acc[ai][bj][m][0], v1 = acc[ai][bj][m][1];
;                     if (RS == 1) { v0 = v0 * rsc; v1 = v1 * rsc; }
;                     if (RS == 2) { v0 = v0 * csc[bj][0]; v1 = v1 * csc[bj][1]; }
;                     if (ACT == 1) { const f32x2 a = gelu_pk((f32x2){v0[0], v0[1]}), b = gelu_pk((f32x2){v0[2], v0[3]}), c = gelu_pk((f32x2){v1[0], v1[1]}), d = gelu_pk((f32x2){v1[2], v1[3]});
;                         v0 = (f32x4){a.x, a.y, b.x, b.y}; v1 = (f32x4){c.x, c.y, d.x, d.y}; }
;                     v0 = v0 * sc; v1 = v1 * sc;
;                     if (STAT == 1) rs += (v0[0] * v0[0] + v0[1] * v0[1]) + (v0[2] * v0[2] + v0[3] * v0[3]) + (v1[0] * v1[0] + v1[1] * v1[1]) + (v1[2] * v1[2] + v1[3] * v1[3]);
;                     if (STAT == 2) {
; #pragma unroll
;                         for (int e = 0; e < 4; ++e) { cs[bj][0][e] += v0[e]; cq[bj][0][e] += v0[e] * v0[e]; cs[bj][1][e] += v1[e]; cq[bj][1][e] += v1[e] * v1[e]; } }
;                     u32x4 w; w.x = cvt_pk_bf16(v0[0], v0[1]); w.y = cvt_pk_bf16(v0[2], v0[3]); w.z = cvt_pk_bf16(v1[0], v1[1]); w.w = cvt_pk_bf16(v1[2], v1[3]);
;                     *(GAS u32x4*)(rowp + bj * 128) = w; }
	v_cndmask_b32_e32 v28, v24, v28, vcc
	v_cmp_gt_f32_e32 vcc, 0, v27
	v_cvt_pk_bf16_f32 v24, v40, v41
	s_nop 1
	v_cndmask_b32_e32 v27, v25, v29, vcc
	v_cvt_pk_bf16_f32 v25, v38, v39
	v_cvt_pk_bf16_f32 v26, v36, v37
	v_cvt_pk_bf16_f32 v27, v28, v27
	v_add_co_u32_e32 v28, vcc, s4, v150
	s_mov_b64 s[4:5], 0x58000
	s_nop 0
	v_addc_co_u32_e32 v29, vcc, 0, v151, vcc
	global_store_dwordx4 v[28:29], v[24:27], off
	v_pk_mul_f32 v[28:29], v[20:21], v[20:21]
	v_cmp_gt_f32_e32 vcc, 0, v20
	v_and_b32_e32 v25, 0x7fffffff, v21
	v_and_b32_e32 v24, 0x7fffffff, v20
	v_pk_fma_f32 v[24:25], v[24:25], s[28:29], 1.0 op_sel_hi:[1,0,0]
	v_pk_mul_f32 v[28:29], v[28:29], s[58:59] op_sel_hi:[1,0]
	v_rcp_f32_e32 v24, v24
	v_rcp_f32_e32 v25, v25
	v_exp_f32_e32 v28, v28
	v_exp_f32_e32 v29, v29
	v_pk_fma_f32 v[26:27], v[24:25], s[30:31], v[122:123] op_sel_hi:[1,0,0]
	s_nop 0
	v_pk_fma_f32 v[26:27], v[24:25], v[26:27], s[52:53] op_sel_hi:[1,1,0]
	s_nop 0
	v_pk_fma_f32 v[26:27], v[24:25], v[26:27], s[54:55] op_sel_hi:[1,1,0]
	s_nop 0
	v_pk_fma_f32 v[26:27], v[24:25], v[26:27], s[56:57] op_sel_hi:[1,1,0]
	s_nop 0
	v_pk_mul_f32 v[24:25], v[24:25], v[26:27]
	v_pk_mul_f32 v[26:27], v[22:23], v[22:23]
	v_pk_mul_f32 v[24:25], v[28:29], v[24:25]
	s_nop 0
	v_pk_mul_f32 v[28:29], v[20:21], v[24:25]
	v_pk_fma_f32 v[24:25], v[20:21], v[24:25], v[20:21] neg_lo:[1,0,0] neg_hi:[1,0,0]
	v_and_b32_e32 v20, 0x7fffffff, v22
	v_cndmask_b32_e32 v28, v24, v28, vcc
	v_cmp_gt_f32_e32 vcc, 0, v21
	v_and_b32_e32 v21, 0x7fffffff, v23
	v_pk_fma_f32 v[20:21], v[20:21], s[28:29], 1.0 op_sel_hi:[1,0,0]
	v_cndmask_b32_e32 v29, v25, v29, vcc
	v_rcp_f32_e32 v20, v20
	v_rcp_f32_e32 v21, v21
	v_cmp_gt_f32_e32 vcc, 0, v22
	v_pk_fma_f32 v[24:25], v[20:21], s[30:31], v[122:123] op_sel_hi:[1,0,0]
	s_nop 0
	v_pk_fma_f32 v[24:25], v[20:21], v[24:25], s[52:53] op_sel_hi:[1,1,0]
	s_nop 0
	v_pk_fma_f32 v[24:25], v[20:21], v[24:25], s[54:55] op_sel_hi:[1,1,0]
	s_nop 0
	v_pk_fma_f32 v[24:25], v[20:21], v[24:25], s[56:57] op_sel_hi:[1,1,0]
	s_nop 0
	v_pk_mul_f32 v[20:21], v[20:21], v[24:25]
	v_pk_mul_f32 v[24:25], v[26:27], s[58:59] op_sel_hi:[1,0]
	s_nop 0
	v_exp_f32_e32 v24, v24
	v_exp_f32_e32 v25, v25
	s_nop 0
	v_pk_mul_f32 v[20:21], v[24:25], v[20:21]
	s_nop 0
	v_pk_mul_f32 v[24:25], v[22:23], v[20:21]
	v_pk_fma_f32 v[20:21], v[22:23], v[20:21], v[22:23] neg_lo:[1,0,0] neg_hi:[1,0,0]
	s_nop 0
	v_cndmask_b32_e32 v26, v20, v24, vcc
	v_cmp_gt_f32_e32 vcc, 0, v23
	v_and_b32_e32 v20, 0x7fffffff, v16
	s_nop 0
	v_cndmask_b32_e32 v27, v21, v25, vcc
	v_and_b32_e32 v21, 0x7fffffff, v17
	v_pk_fma_f32 v[20:21], v[20:21], s[28:29], 1.0 op_sel_hi:[1,0,0]
	v_pk_mul_f32 v[24:25], v[16:17], v[16:17]
	v_rcp_f32_e32 v20, v20
	v_rcp_f32_e32 v21, v21
	v_pk_mul_f32 v[24:25], v[24:25], s[58:59] op_sel_hi:[1,0]
	v_cmp_gt_f32_e32 vcc, 0, v16
	v_exp_f32_e32 v24, v24
	v_pk_fma_f32 v[22:23], v[20:21], s[30:31], v[122:123] op_sel_hi:[1,0,0]
	v_exp_f32_e32 v25, v25
	v_pk_fma_f32 v[22:23], v[20:21], v[22:23], s[52:53] op_sel_hi:[1,1,0]
	s_nop 0
	v_pk_fma_f32 v[22:23], v[20:21], v[22:23], s[54:55] op_sel_hi:[1,1,0]
	s_nop 0
	v_pk_fma_f32 v[22:23], v[20:21], v[22:23], s[56:57] op_sel_hi:[1,1,0]
	s_nop 0
	v_pk_mul_f32 v[20:21], v[20:21], v[22:23]
	v_pk_mul_f32 v[22:23], v[18:19], v[18:19]
	v_pk_mul_f32 v[20:21], v[24:25], v[20:21]
	s_nop 0
	v_pk_mul_f32 v[24:25], v[16:17], v[20:21]
	v_pk_fma_f32 v[20:21], v[16:17], v[20:21], v[16:17] neg_lo:[1,0,0] neg_hi:[1,0,0]
	v_and_b32_e32 v16, 0x7fffffff, v18
	v_cndmask_b32_e32 v24, v20, v24, vcc
	v_cmp_gt_f32_e32 vcc, 0, v17
	v_and_b32_e32 v17, 0x7fffffff, v19
	v_pk_fma_f32 v[16:17], v[16:17], s[28:29], 1.0 op_sel_hi:[1,0,0]
	v_cndmask_b32_e32 v25, v21, v25, vcc
	v_rcp_f32_e32 v16, v16
	v_rcp_f32_e32 v17, v17
	v_cmp_gt_f32_e32 vcc, 0, v18
	v_pk_fma_f32 v[20:21], v[16:17], s[30:31], v[122:123] op_sel_hi:[1,0,0]
	s_nop 0
	v_pk_fma_f32 v[20:21], v[16:17], v[20:21], s[52:53] op_sel_hi:[1,1,0]
	s_nop 0
	v_pk_fma_f32 v[20:21], v[16:17], v[20:21], s[54:55] op_sel_hi:[1,1,0]
	s_nop 0
	v_pk_fma_f32 v[20:21], v[16:17], v[20:21], s[56:57] op_sel_hi:[1,1,0]
	s_nop 0
	v_pk_mul_f32 v[16:17], v[16:17], v[20:21]
	v_pk_mul_f32 v[20:21], v[22:23], s[58:59] op_sel_hi:[1,0]
	v_pk_mul_f32 v[22:23], v[12:13], v[12:13]
	v_exp_f32_e32 v20, v20
	v_exp_f32_e32 v21, v21
	v_pk_mul_f32 v[22:23], v[22:23], s[58:59] op_sel_hi:[1,0]
	v_pk_mul_f32 v[16:17], v[20:21], v[16:17]
	s_nop 0
	v_pk_mul_f32 v[20:21], v[18:19], v[16:17]
	v_pk_fma_f32 v[16:17], v[18:19], v[16:17], v[18:19] neg_lo:[1,0,0] neg_hi:[1,0,0]
	v_exp_f32_e32 v22, v22
	v_cndmask_b32_e32 v20, v16, v20, vcc
	v_cmp_gt_f32_e32 vcc, 0, v19
	v_cvt_pk_bf16_f32 v16, v28, v29
	v_exp_f32_e32 v23, v23
	s_nop 0
	v_cndmask_b32_e32 v19, v17, v21, vcc
	v_cvt_pk_bf16_f32 v17, v26, v27
	v_cvt_pk_bf16_f32 v18, v24, v25
	v_cvt_pk_bf16_f32 v19, v20, v19
	global_store_dwordx4 v[34:35], v[16:19], off offset:256
	v_cmp_gt_f32_e32 vcc, 0, v12
	s_nop 0
	v_and_b32_e32 v19, 0x7fffffff, v13
	v_and_b32_e32 v18, 0x7fffffff, v12
	v_pk_fma_f32 v[18:19], v[18:19], s[28:29], 1.0 op_sel_hi:[1,0,0]
	v_lshl_add_u64 v[16:17], v[150:151], 0, s[4:5]
	v_rcp_f32_e32 v18, v18
	v_rcp_f32_e32 v19, v19
	s_mov_b32 s4, 0x58000
	v_pk_fma_f32 v[20:21], v[18:19], s[30:31], v[122:123] op_sel_hi:[1,0,0]
	s_nop 0
	v_pk_fma_f32 v[20:21], v[18:19], v[20:21], s[52:53] op_sel_hi:[1,1,0]
	s_nop 0
	v_pk_fma_f32 v[20:21], v[18:19], v[20:21], s[54:55] op_sel_hi:[1,1,0]
	s_nop 0
	v_pk_fma_f32 v[20:21], v[18:19], v[20:21], s[56:57] op_sel_hi:[1,1,0]
	s_nop 0
	v_pk_mul_f32 v[18:19], v[18:19], v[20:21]
	v_pk_mul_f32 v[20:21], v[14:15], v[14:15]
	v_pk_mul_f32 v[18:19], v[22:23], v[18:19]
	s_nop 0
	v_pk_mul_f32 v[22:23], v[12:13], v[18:19]
; __device__ __forceinline__ unsigned cvt_pk_bf16(float lo, float hi) { unsigned r; asm volatile("v_cvt_pk_bf16_f32 %0, %1, %2" : "=v"(r) : "v"(lo), "v"(hi)); return r; }
; #define GAS __attribute__((address_space(1)))
; __device__ __forceinline__ f32x2 gelu_pk(f32x2 v) {
;     const f32x2 av = __builtin_elementwise_abs(v), d = av * 0.2316418882f + 1.0f;
;     f32x2 t; t.x = __builtin_amdgcn_rcpf(d.x); t.y = __builtin_amdgcn_rcpf(d.y);
;     f32x2 q = t * 0.5307027145f + (-0.7265760135f); q = q * t + 0.7107068705f; q = q * t + (-0.142248368f); q = q * t + 0.127414796f; q = q * t;
;     const f32x2 s = (v * v) * (-0.72134752044f);
;     f32x2 e; e.x = __builtin_amdgcn_exp2f(s.x); e.y = __builtin_amdgcn_exp2f(s.y);
;     const f32x2 m = v * (q * e), r = v - m;
;     f32x2 o; o.x = v.x < 0.f ? m.x : r.x; o.y = v.y < 0.f ? m.y : r.y; return o;
; }
;     __device__ __forceinline__ void operator()(const f32x4 (&acc)[2][2][4][2], const Unit& u, int wr, int wc, int fr, int fq, const float (&pre)[8]) const {
;     ...
;                     f32x4 v0 = acc[ai][bj][m][0], v1 = acc[ai][bj][m][1];
;                     if (RS == 1) { v0 = v0 * rsc; v1 = v1 * rsc; }
;                     if (RS == 2) { v0 = v0 * csc[bj][0]; v1 = v1 * csc[bj][1]; }
;                     if (ACT == 1) { const f32x2 a = gelu_pk((f32x2){v0[0], v0[1]}), b = gelu_pk((f32x2){v0[2], v0[3]}), c = gelu_pk((f32x2){v1[0], v1[1]}), d = gelu_pk((f32x2){v1[2], v1[3]});
;                         v0 = (f32x4){a.x, a.y, b.x, b.y}; v1 = (f32x4){c.x, c.y, d.x, d.y}; }
;                     v0 = v0 * sc; v1 = v1 * sc;
;                     if (STAT == 1) rs += (v0[0] * v0[0] + v0[1] * v0[1]) + (v0[2] * v0[2] + v0[3] * v0[3]) + (v1[0] * v1[0] + v1[1] * v1[1]) + (v1[2] * v1[2] + v1[3] * v1[3]);
;                     if (STAT == 2) {
; #pragma unroll
;                         for (int e = 0; e < 4; ++e) { cs[bj][0][e] += v0[e]; cq[bj][0][e] += v0[e] * v0[e]; cs[bj][1][e] += v1[e]; cq[bj][1][e] += v1[e] * v1[e]; } }
;                     u32x4 w; w.x = cvt_pk_bf16(v0[0], v0[1]); w.y = cvt_pk_bf16(v0[2], v0[3]); w.z = cvt_pk_bf16(v1[0], v1[1]); w.w = cvt_pk_bf16(v1[2], v1[3]);
;                     *(GAS u32x4*)(rowp + bj * 128) = w; }
	v_pk_fma_f32 v[18:19], v[12:13], v[18:19], v[12:13] neg_lo:[1,0,0] neg_hi:[1,0,0]
	v_and_b32_e32 v12, 0x7fffffff, v14
	v_cndmask_b32_e32 v22, v18, v22, vcc
	v_cmp_gt_f32_e32 vcc, 0, v13
	v_and_b32_e32 v13, 0x7fffffff, v15
	v_pk_fma_f32 v[12:13], v[12:13], s[28:29], 1.0 op_sel_hi:[1,0,0]
	v_cndmask_b32_e32 v23, v19, v23, vcc
	v_rcp_f32_e32 v12, v12
	v_rcp_f32_e32 v13, v13
	v_cmp_gt_f32_e32 vcc, 0, v14
	v_pk_fma_f32 v[18:19], v[12:13], s[30:31], v[122:123] op_sel_hi:[1,0,0]
	s_nop 0
	v_pk_fma_f32 v[18:19], v[12:13], v[18:19], s[52:53] op_sel_hi:[1,1,0]
	s_nop 0
	v_pk_fma_f32 v[18:19], v[12:13], v[18:19], s[54:55] op_sel_hi:[1,1,0]
	s_nop 0
	v_pk_fma_f32 v[18:19], v[12:13], v[18:19], s[56:57] op_sel_hi:[1,1,0]
	s_nop 0
	v_pk_mul_f32 v[12:13], v[12:13], v[18:19]
	v_pk_mul_f32 v[18:19], v[20:21], s[58:59] op_sel_hi:[1,0]
	s_nop 0
	v_exp_f32_e32 v18, v18
	v_exp_f32_e32 v19, v19
	s_nop 0
	v_pk_mul_f32 v[12:13], v[18:19], v[12:13]
	s_nop 0
	v_pk_mul_f32 v[18:19], v[14:15], v[12:13]
	v_pk_fma_f32 v[12:13], v[14:15], v[12:13], v[14:15] neg_lo:[1,0,0] neg_hi:[1,0,0]
	s_nop 0
	v_cndmask_b32_e32 v20, v12, v18, vcc
	v_cmp_gt_f32_e32 vcc, 0, v15
	v_and_b32_e32 v12, 0x7fffffff, v8
	s_nop 0
	v_cndmask_b32_e32 v21, v13, v19, vcc
	v_and_b32_e32 v13, 0x7fffffff, v9
	v_pk_fma_f32 v[12:13], v[12:13], s[28:29], 1.0 op_sel_hi:[1,0,0]
	v_pk_mul_f32 v[18:19], v[8:9], v[8:9]
	v_rcp_f32_e32 v12, v12
	v_rcp_f32_e32 v13, v13
	v_pk_mul_f32 v[18:19], v[18:19], s[58:59] op_sel_hi:[1,0]
	v_cmp_gt_f32_e32 vcc, 0, v8
	v_exp_f32_e32 v18, v18
	v_pk_fma_f32 v[14:15], v[12:13], s[30:31], v[122:123] op_sel_hi:[1,0,0]
	v_exp_f32_e32 v19, v19
	v_pk_fma_f32 v[14:15], v[12:13], v[14:15], s[52:53] op_sel_hi:[1,1,0]
	s_nop 0
	v_pk_fma_f32 v[14:15], v[12:13], v[14:15], s[54:55] op_sel_hi:[1,1,0]
	s_nop 0
	v_pk_fma_f32 v[14:15], v[12:13], v[14:15], s[56:57] op_sel_hi:[1,1,0]
	s_nop 0
	v_pk_mul_f32 v[12:13], v[12:13], v[14:15]
	v_pk_mul_f32 v[14:15], v[10:11], v[10:11]
	v_pk_mul_f32 v[12:13], v[18:19], v[12:13]
	s_nop 0
	v_pk_mul_f32 v[18:19], v[8:9], v[12:13]
	v_pk_fma_f32 v[12:13], v[8:9], v[12:13], v[8:9] neg_lo:[1,0,0] neg_hi:[1,0,0]
	v_and_b32_e32 v8, 0x7fffffff, v10
	v_cndmask_b32_e32 v18, v12, v18, vcc
	v_cmp_gt_f32_e32 vcc, 0, v9
	v_and_b32_e32 v9, 0x7fffffff, v11
	v_pk_fma_f32 v[8:9], v[8:9], s[28:29], 1.0 op_sel_hi:[1,0,0]
	v_cndmask_b32_e32 v19, v13, v19, vcc
	v_rcp_f32_e32 v8, v8
	v_rcp_f32_e32 v9, v9
	v_cmp_gt_f32_e32 vcc, 0, v10
	v_pk_fma_f32 v[12:13], v[8:9], s[30:31], v[122:123] op_sel_hi:[1,0,0]
	s_nop 0
	v_pk_fma_f32 v[12:13], v[8:9], v[12:13], s[52:53] op_sel_hi:[1,1,0]
	s_nop 0
	v_pk_fma_f32 v[12:13], v[8:9], v[12:13], s[54:55] op_sel_hi:[1,1,0]
	s_nop 0
	v_pk_fma_f32 v[12:13], v[8:9], v[12:13], s[56:57] op_sel_hi:[1,1,0]
	s_nop 0
	v_pk_mul_f32 v[8:9], v[8:9], v[12:13]
	v_pk_mul_f32 v[12:13], v[14:15], s[58:59] op_sel_hi:[1,0]
	s_nop 0
	v_exp_f32_e32 v12, v12
	v_exp_f32_e32 v13, v13
	s_nop 0
	v_pk_mul_f32 v[8:9], v[12:13], v[8:9]
	s_nop 0
	v_pk_mul_f32 v[12:13], v[10:11], v[8:9]
	v_pk_fma_f32 v[8:9], v[10:11], v[8:9], v[10:11] neg_lo:[1,0,0] neg_hi:[1,0,0]
	s_nop 0
	v_cndmask_b32_e32 v12, v8, v12, vcc
	v_cmp_gt_f32_e32 vcc, 0, v11
	v_cvt_pk_bf16_f32 v8, v22, v23
	s_nop 1
	v_cndmask_b32_e32 v11, v9, v13, vcc
	v_cvt_pk_bf16_f32 v9, v20, v21
	v_cvt_pk_bf16_f32 v10, v18, v19
	v_cvt_pk_bf16_f32 v11, v12, v11
	v_add_co_u32_e32 v12, vcc, s4, v150
	s_nop 1
	v_addc_co_u32_e32 v13, vcc, 0, v151, vcc
	global_store_dwordx4 v[12:13], v[8:11], off
	v_pk_mul_f32 v[12:13], v[4:5], v[4:5]
	v_cmp_gt_f32_e32 vcc, 0, v4
	v_and_b32_e32 v9, 0x7fffffff, v5
	v_and_b32_e32 v8, 0x7fffffff, v4
	v_pk_fma_f32 v[8:9], v[8:9], s[28:29], 1.0 op_sel_hi:[1,0,0]
	v_pk_mul_f32 v[12:13], v[12:13], s[58:59] op_sel_hi:[1,0]
	v_rcp_f32_e32 v8, v8
	v_rcp_f32_e32 v9, v9
	v_exp_f32_e32 v12, v12
	v_exp_f32_e32 v13, v13
	v_pk_fma_f32 v[10:11], v[8:9], s[30:31], v[122:123] op_sel_hi:[1,0,0]
	s_nop 0
	v_pk_fma_f32 v[10:11], v[8:9], v[10:11], s[52:53] op_sel_hi:[1,1,0]
	s_nop 0
	v_pk_fma_f32 v[10:11], v[8:9], v[10:11], s[54:55] op_sel_hi:[1,1,0]
	s_nop 0
; #define GAS __attribute__((address_space(1)))
; __device__ __forceinline__ f32x2 gelu_pk(f32x2 v) {
;     const f32x2 av = __builtin_elementwise_abs(v), d = av * 0.2316418882f + 1.0f;
;     f32x2 t; t.x = __builtin_amdgcn_rcpf(d.x); t.y = __builtin_amdgcn_rcpf(d.y);
;     f32x2 q = t * 0.5307027145f + (-0.7265760135f); q = q * t + 0.7107068705f; q = q * t + (-0.142248368f); q = q * t + 0.127414796f; q = q * t;
;     const f32x2 s = (v * v) * (-0.72134752044f);
;     f32x2 e; e.x = __builtin_amdgcn_exp2f(s.x); e.y = __builtin_amdgcn_exp2f(s.y);
;     const f32x2 m = v * (q * e), r = v - m;
;     f32x2 o; o.x = v.x < 0.f ? m.x : r.x; o.y = v.y < 0.f ? m.y : r.y; return o;
; }
;     __device__ __forceinline__ void prefetch(const Unit& u, int wr, int fr, float (&pre)[8]) const {
; #pragma unroll
;         for (int i = 0; i < 8; ++i) pre[i] = *(const GAS float*)(rs + u.pm * 256 + wr * 64 + fr + (i >> 2) * 128 + (i & 3) * 16);
;     }
	v_pk_fma_f32 v[10:11], v[8:9], v[10:11], s[56:57] op_sel_hi:[1,1,0]
	s_nop 0
	v_pk_mul_f32 v[8:9], v[8:9], v[10:11]
	v_pk_mul_f32 v[10:11], v[6:7], v[6:7]
	v_pk_mul_f32 v[8:9], v[12:13], v[8:9]
	s_nop 0
	v_pk_mul_f32 v[12:13], v[4:5], v[8:9]
	v_pk_fma_f32 v[8:9], v[4:5], v[8:9], v[4:5] neg_lo:[1,0,0] neg_hi:[1,0,0]
	v_and_b32_e32 v4, 0x7fffffff, v6
	v_cndmask_b32_e32 v12, v8, v12, vcc
	v_cmp_gt_f32_e32 vcc, 0, v5
	v_and_b32_e32 v5, 0x7fffffff, v7
	v_pk_fma_f32 v[4:5], v[4:5], s[28:29], 1.0 op_sel_hi:[1,0,0]
	v_cndmask_b32_e32 v13, v9, v13, vcc
	v_rcp_f32_e32 v4, v4
	v_rcp_f32_e32 v5, v5
	v_cmp_gt_f32_e32 vcc, 0, v6
	v_pk_fma_f32 v[8:9], v[4:5], s[30:31], v[122:123] op_sel_hi:[1,0,0]
	s_nop 0
	v_pk_fma_f32 v[8:9], v[4:5], v[8:9], s[52:53] op_sel_hi:[1,1,0]
	s_nop 0
	v_pk_fma_f32 v[8:9], v[4:5], v[8:9], s[54:55] op_sel_hi:[1,1,0]
	s_nop 0
	v_pk_fma_f32 v[8:9], v[4:5], v[8:9], s[56:57] op_sel_hi:[1,1,0]
	s_nop 0
	v_pk_mul_f32 v[4:5], v[4:5], v[8:9]
	v_pk_mul_f32 v[8:9], v[10:11], s[58:59] op_sel_hi:[1,0]
	s_nop 0
	v_exp_f32_e32 v8, v8
	v_exp_f32_e32 v9, v9
	s_nop 0
	v_pk_mul_f32 v[4:5], v[8:9], v[4:5]
	s_nop 0
	v_pk_mul_f32 v[8:9], v[6:7], v[4:5]
	v_pk_fma_f32 v[4:5], v[6:7], v[4:5], v[6:7] neg_lo:[1,0,0] neg_hi:[1,0,0]
	s_nop 0
	v_cndmask_b32_e32 v10, v4, v8, vcc
	v_cmp_gt_f32_e32 vcc, 0, v7
	v_and_b32_e32 v4, 0x7fffffff, v0
	s_nop 0
	v_cndmask_b32_e32 v11, v5, v9, vcc
	v_and_b32_e32 v5, 0x7fffffff, v1
	v_pk_fma_f32 v[4:5], v[4:5], s[28:29], 1.0 op_sel_hi:[1,0,0]
	v_pk_mul_f32 v[8:9], v[0:1], v[0:1]
	v_rcp_f32_e32 v4, v4
	v_rcp_f32_e32 v5, v5
	v_pk_mul_f32 v[8:9], v[8:9], s[58:59] op_sel_hi:[1,0]
	v_cmp_gt_f32_e32 vcc, 0, v0
	v_exp_f32_e32 v8, v8
	v_pk_fma_f32 v[6:7], v[4:5], s[30:31], v[122:123] op_sel_hi:[1,0,0]
	v_exp_f32_e32 v9, v9
	v_pk_fma_f32 v[6:7], v[4:5], v[6:7], s[52:53] op_sel_hi:[1,1,0]
	s_nop 0
	v_pk_fma_f32 v[6:7], v[4:5], v[6:7], s[54:55] op_sel_hi:[1,1,0]
	s_nop 0
	v_pk_fma_f32 v[6:7], v[4:5], v[6:7], s[56:57] op_sel_hi:[1,1,0]
	s_nop 0
	v_pk_mul_f32 v[4:5], v[4:5], v[6:7]
	v_pk_mul_f32 v[6:7], v[2:3], v[2:3]
	v_pk_mul_f32 v[4:5], v[8:9], v[4:5]
	s_nop 0
	v_pk_mul_f32 v[8:9], v[0:1], v[4:5]
	v_pk_fma_f32 v[4:5], v[0:1], v[4:5], v[0:1] neg_lo:[1,0,0] neg_hi:[1,0,0]
	v_and_b32_e32 v0, 0x7fffffff, v2
	v_cndmask_b32_e32 v8, v4, v8, vcc
	v_cmp_gt_f32_e32 vcc, 0, v1
	v_and_b32_e32 v1, 0x7fffffff, v3
	v_pk_fma_f32 v[0:1], v[0:1], s[28:29], 1.0 op_sel_hi:[1,0,0]
	v_cndmask_b32_e32 v9, v5, v9, vcc
	v_rcp_f32_e32 v0, v0
	v_rcp_f32_e32 v1, v1
	v_cmp_gt_f32_e32 vcc, 0, v2
	v_pk_fma_f32 v[4:5], v[0:1], s[30:31], v[122:123] op_sel_hi:[1,0,0]
	s_nop 0
	v_pk_fma_f32 v[4:5], v[0:1], v[4:5], s[52:53] op_sel_hi:[1,1,0]
	s_nop 0
	v_pk_fma_f32 v[4:5], v[0:1], v[4:5], s[54:55] op_sel_hi:[1,1,0]
	s_nop 0
	v_pk_fma_f32 v[4:5], v[0:1], v[4:5], s[56:57] op_sel_hi:[1,1,0]
	s_nop 0
	v_pk_mul_f32 v[0:1], v[0:1], v[4:5]
	v_pk_mul_f32 v[4:5], v[6:7], s[58:59] op_sel_hi:[1,0]
	s_nop 0
	v_exp_f32_e32 v4, v4
	v_exp_f32_e32 v5, v5
	s_nop 0
	v_pk_mul_f32 v[0:1], v[4:5], v[0:1]
	s_nop 0
	v_pk_mul_f32 v[4:5], v[2:3], v[0:1]
	v_pk_fma_f32 v[0:1], v[2:3], v[0:1], v[2:3] neg_lo:[1,0,0] neg_hi:[1,0,0]
	s_nop 0
	v_cndmask_b32_e32 v4, v0, v4, vcc
	v_cmp_gt_f32_e32 vcc, 0, v3
	v_cvt_pk_bf16_f32 v0, v12, v13
	s_nop 1
	v_cndmask_b32_e32 v3, v1, v5, vcc
	s_andn2_b64 vcc, exec, s[96:97]
	v_cvt_pk_bf16_f32 v1, v10, v11
	v_cvt_pk_bf16_f32 v2, v8, v9
	v_cvt_pk_bf16_f32 v3, v4, v3
	global_store_dwordx4 v[16:17], v[0:3], off offset:256
	s_cbranch_vccnz .LBB0_109
	s_lshl_b32 s4, s90, 8
	s_ashr_i32 s5, s4, 31
	v_lshl_add_u64 v[0:1], s[4:5], 2, v[138:139]
	global_load_dword v172, v[0:1], off
	global_load_dword v158, v[0:1], off offset:64
	global_load_dword v156, v[0:1], off offset:128
	global_load_dword v154, v[0:1], off offset:192
	global_load_dword v152, v[0:1], off offset:512
	global_load_dword v148, v[0:1], off offset:576
	global_load_dword v146, v[0:1], off offset:640
	global_load_dword v144, v[0:1], off offset:704
	v_readlane_b32 s4, v254, 49
	v_readlane_b32 s5, v254, 50
	s_andn2_b64 vcc, exec, s[4:5]
	s_cbranch_vccnz .LBB0_108
	s_barrier
	s_branch .LBB0_108

; __device__ __forceinline__ unsigned cvt_pk_bf16(float lo, float hi) { unsigned r; asm volatile("v_cvt_pk_bf16_f32 %0, %1, %2" : "=v"(r) : "v"(lo), "v"(hi)); return r; }
; #define GAS __attribute__((address_space(1)))
; __device__ __forceinline__ float silu_mul(float g, float u) { const float e = __builtin_amdgcn_exp2f(-1.4426950408889634f * g); return g * __builtin_amdgcn_rcpf(1.0f + e) * u; }
;     __device__ __forceinline__ void operator()(const f32x4 (&acc)[2][2][4][2], const Unit& u, int wr, int wc, int fr, int fq, const float (&pre)[8]) const {
;         const int row0 = u.pm * 256 + wr * 64 + fr, col0 = u.pn * 128 + wc * 32 + 8 * fq;
; #pragma unroll
;         for (int ai = 0; ai < 2; ++ai)
; #pragma unroll
;             for (int m = 0; m < 4; ++m) {
;                 const float rsc = pre[ai * 4 + m];
;                 const f32x4 g0 = acc[ai][0][m][0] * rsc, g1 = acc[ai][0][m][1] * rsc, u0 = acc[ai][1][m][0] * rsc, u1 = acc[ai][1][m][1] * rsc;
;                 u32x4 w; w.x = cvt_pk_bf16(silu_mul(g0[0], u0[0]), silu_mul(g0[1], u0[1])); w.y = cvt_pk_bf16(silu_mul(g0[2], u0[2]), silu_mul(g0[3], u0[3]));
;                 w.z = cvt_pk_bf16(silu_mul(g1[0], u1[0]), silu_mul(g1[1], u1[1])); w.w = cvt_pk_bf16(silu_mul(g1[2], u1[2]), silu_mul(g1[3], u1[3]));
;                 *(GAS u32x4*)(O + (size_t)(row0 + ai * 128 + m * 16) * DFF + col0) = w; }
;     }
.LBB0_447:
	v_pk_mul_f32 v[126:127], v[158:159], v[126:127] op_sel_hi:[0,1]
	v_mul_f32_e32 v153, 0xbfb8aa3b, v126
	v_exp_f32_e32 v153, v153
	v_pk_mul_f32 v[118:119], v[158:159], v[118:119] op_sel_hi:[0,1]
	v_pk_mul_f32 v[128:129], v[158:159], v[128:129] op_sel_hi:[0,1]
	v_pk_mul_f32 v[120:121], v[158:159], v[120:121] op_sel_hi:[0,1]
	v_add_f32_e32 v153, 1.0, v153
	v_rcp_f32_e32 v153, v153
	v_pk_mul_f32 v[122:123], v[158:159], v[122:123] op_sel_hi:[0,1]
	v_pk_mul_f32 v[114:115], v[158:159], v[114:115] op_sel_hi:[0,1]
	v_pk_mul_f32 v[124:125], v[158:159], v[124:125] op_sel_hi:[0,1]
	v_mul_f32_e32 v126, v126, v153
	v_mul_f32_e32 v118, v126, v118
	v_mul_f32_e32 v126, 0xbfb8aa3b, v127
	v_exp_f32_e32 v126, v126
	v_pk_mul_f32 v[116:117], v[158:159], v[116:117] op_sel_hi:[0,1]
	v_lshl_or_b32 v160, s44, 7, v147
	v_lshl_add_u32 v151, s46, 8, v33
	v_add_f32_e32 v126, 1.0, v126
	v_rcp_f32_e32 v126, v126
	v_ashrrev_i32_e32 v161, 31, v160
	v_pk_mul_f32 v[110:111], v[156:157], v[110:111] op_sel_hi:[0,1]
	v_pk_mul_f32 v[102:103], v[156:157], v[102:103] op_sel_hi:[0,1]
	v_mul_f32_e32 v126, v127, v126
	v_mul_f32_e32 v119, v126, v119
	v_cvt_pk_bf16_f32 v118, v118, v119
	v_mul_f32_e32 v119, 0xbfb8aa3b, v128
	v_exp_f32_e32 v119, v119
	v_pk_mul_f32 v[112:113], v[156:157], v[112:113] op_sel_hi:[0,1]
	v_pk_mul_f32 v[104:105], v[156:157], v[104:105] op_sel_hi:[0,1]
	v_pk_mul_f32 v[106:107], v[156:157], v[106:107] op_sel_hi:[0,1]
	v_add_f32_e32 v119, 1.0, v119
	v_rcp_f32_e32 v119, v119
	v_pk_mul_f32 v[108:109], v[156:157], v[108:109] op_sel_hi:[0,1]
	v_pk_mul_f32 v[94:95], v[154:155], v[94:95] op_sel_hi:[0,1]
	v_pk_mul_f32 v[86:87], v[154:155], v[86:87] op_sel_hi:[0,1]
	v_mul_f32_e32 v119, v128, v119
	v_mul_f32_e32 v119, v119, v120
	v_mul_f32_e32 v120, 0xbfb8aa3b, v129
	v_exp_f32_e32 v120, v120
	v_pk_mul_f32 v[96:97], v[154:155], v[96:97] op_sel_hi:[0,1]
	v_pk_mul_f32 v[88:89], v[154:155], v[88:89] op_sel_hi:[0,1]
	v_pk_mul_f32 v[90:91], v[154:155], v[90:91] op_sel_hi:[0,1]
	v_add_f32_e32 v120, 1.0, v120
	v_rcp_f32_e32 v120, v120
	v_pk_mul_f32 v[92:93], v[154:155], v[92:93] op_sel_hi:[0,1]
	v_pk_mul_f32 v[78:79], v[152:153], v[78:79] op_sel_hi:[0,1]
	v_pk_mul_f32 v[70:71], v[152:153], v[70:71] op_sel_hi:[0,1]
	v_mul_f32_e32 v120, v129, v120
	v_mul_f32_e32 v120, v120, v121
	v_cvt_pk_bf16_f32 v119, v119, v120
	v_mul_f32_e32 v120, 0xbfb8aa3b, v122
	v_exp_f32_e32 v120, v120
	v_pk_mul_f32 v[80:81], v[152:153], v[80:81] op_sel_hi:[0,1]
	v_pk_mul_f32 v[72:73], v[152:153], v[72:73] op_sel_hi:[0,1]
	v_pk_mul_f32 v[74:75], v[152:153], v[74:75] op_sel_hi:[0,1]
	v_add_f32_e32 v120, 1.0, v120
	v_rcp_f32_e32 v120, v120
	v_pk_mul_f32 v[76:77], v[152:153], v[76:77] op_sel_hi:[0,1]
	v_pk_mul_f32 v[62:63], v[150:151], v[62:63] op_sel_hi:[0,1]
	v_pk_mul_f32 v[54:55], v[150:151], v[54:55] op_sel_hi:[0,1]
	v_mul_f32_e32 v120, v122, v120
	v_mul_f32_e32 v114, v120, v114
	v_mul_f32_e32 v120, 0xbfb8aa3b, v123
	v_exp_f32_e32 v120, v120
	v_pk_mul_f32 v[64:65], v[150:151], v[64:65] op_sel_hi:[0,1]
	v_pk_mul_f32 v[56:57], v[150:151], v[56:57] op_sel_hi:[0,1]
	v_pk_mul_f32 v[58:59], v[150:151], v[58:59] op_sel_hi:[0,1]
	v_add_f32_e32 v120, 1.0, v120
	v_rcp_f32_e32 v120, v120
	v_pk_mul_f32 v[60:61], v[150:151], v[60:61] op_sel_hi:[0,1]
	v_pk_mul_f32 v[46:47], v[148:149], v[46:47] op_sel_hi:[0,1]
	v_pk_mul_f32 v[38:39], v[148:149], v[38:39] op_sel_hi:[0,1]
	v_mul_f32_e32 v120, v123, v120
	v_mul_f32_e32 v115, v120, v115
	v_cvt_pk_bf16_f32 v120, v114, v115
	v_mul_f32_e32 v114, 0xbfb8aa3b, v124
	v_mul_f32_e32 v115, 0xbfb8aa3b, v125
	v_exp_f32_e32 v114, v114
	v_exp_f32_e32 v115, v115
	v_pk_mul_f32 v[48:49], v[148:149], v[48:49] op_sel_hi:[0,1]
	v_pk_mul_f32 v[40:41], v[148:149], v[40:41] op_sel_hi:[0,1]
	v_add_f32_e32 v114, 1.0, v114
	v_add_f32_e32 v115, 1.0, v115
	v_rcp_f32_e32 v114, v114
	v_rcp_f32_e32 v115, v115
	v_pk_mul_f32 v[42:43], v[148:149], v[42:43] op_sel_hi:[0,1]
	v_pk_mul_f32 v[44:45], v[148:149], v[44:45] op_sel_hi:[0,1]
	v_mul_f32_e32 v114, v124, v114
	v_mul_f32_e32 v115, v125, v115
	v_mul_f32_e32 v114, v114, v116
	v_mul_f32_e32 v115, v115, v117
	v_cvt_pk_bf16_f32 v121, v114, v115
	v_mov_b64_e32 v[114:115], s[64:65]
	v_mad_i64_i32 v[122:123], s[38:39], v151, s29, v[114:115]
	v_lshlrev_b64 v[116:117], 1, v[160:161]
	v_lshl_add_u64 v[122:123], v[122:123], 0, v[116:117]
	global_store_dwordx4 v[122:123], v[118:121], off
	v_pk_mul_f32 v[28:29], v[146:147], v[28:29] op_sel_hi:[0,1]
	v_pk_mul_f32 v[20:21], v[146:147], v[20:21] op_sel_hi:[0,1]
	v_pk_mul_f32 v[118:119], v[156:157], v[100:101] op_sel_hi:[0,1]
	v_pk_mul_f32 v[100:101], v[156:157], v[98:99] op_sel_hi:[0,1]
	v_mul_f32_e32 v98, 0xbfb8aa3b, v110
	v_mul_f32_e32 v99, 0xbfb8aa3b, v111
	v_exp_f32_e32 v98, v98
	v_exp_f32_e32 v99, v99
	v_pk_mul_f32 v[30:31], v[146:147], v[30:31] op_sel_hi:[0,1]
	v_pk_mul_f32 v[22:23], v[146:147], v[22:23] op_sel_hi:[0,1]
	v_add_f32_e32 v98, 1.0, v98
	v_add_f32_e32 v99, 1.0, v99
	v_rcp_f32_e32 v98, v98
	v_rcp_f32_e32 v99, v99
	v_pk_mul_f32 v[24:25], v[146:147], v[24:25] op_sel_hi:[0,1]
	v_pk_mul_f32 v[26:27], v[146:147], v[26:27] op_sel_hi:[0,1]
	v_mul_f32_e32 v98, v110, v98
	v_mul_f32_e32 v99, v111, v99
	v_mul_f32_e32 v98, v98, v102
	v_mul_f32_e32 v99, v99, v103
	v_cvt_pk_bf16_f32 v98, v98, v99
	v_mul_f32_e32 v99, 0xbfb8aa3b, v112
	v_mul_f32_e32 v102, 0xbfb8aa3b, v113
	v_exp_f32_e32 v99, v99
	v_exp_f32_e32 v102, v102
	v_pk_mul_f32 v[12:13], v[144:145], v[12:13] op_sel_hi:[0,1]
	v_pk_mul_f32 v[4:5], v[144:145], v[4:5] op_sel_hi:[0,1]
	v_add_f32_e32 v99, 1.0, v99
	v_add_f32_e32 v102, 1.0, v102
	v_rcp_f32_e32 v99, v99
	v_rcp_f32_e32 v102, v102
	v_pk_mul_f32 v[14:15], v[144:145], v[14:15] op_sel_hi:[0,1]
; __device__ __forceinline__ unsigned cvt_pk_bf16(float lo, float hi) { unsigned r; asm volatile("v_cvt_pk_bf16_f32 %0, %1, %2" : "=v"(r) : "v"(lo), "v"(hi)); return r; }
; #define GAS __attribute__((address_space(1)))
; __device__ __forceinline__ float silu_mul(float g, float u) { const float e = __builtin_amdgcn_exp2f(-1.4426950408889634f * g); return g * __builtin_amdgcn_rcpf(1.0f + e) * u; }
;     __device__ __forceinline__ void operator()(const f32x4 (&acc)[2][2][4][2], const Unit& u, int wr, int wc, int fr, int fq, const float (&pre)[8]) const {
;         const int row0 = u.pm * 256 + wr * 64 + fr, col0 = u.pn * 128 + wc * 32 + 8 * fq;
; #pragma unroll
;         for (int ai = 0; ai < 2; ++ai)
; #pragma unroll
;             for (int m = 0; m < 4; ++m) {
;                 const float rsc = pre[ai * 4 + m];
;                 const f32x4 g0 = acc[ai][0][m][0] * rsc, g1 = acc[ai][0][m][1] * rsc, u0 = acc[ai][1][m][0] * rsc, u1 = acc[ai][1][m][1] * rsc;
;                 u32x4 w; w.x = cvt_pk_bf16(silu_mul(g0[0], u0[0]), silu_mul(g0[1], u0[1])); w.y = cvt_pk_bf16(silu_mul(g0[2], u0[2]), silu_mul(g0[3], u0[3]));
;                 w.z = cvt_pk_bf16(silu_mul(g1[0], u1[0]), silu_mul(g1[1], u1[1])); w.w = cvt_pk_bf16(silu_mul(g1[2], u1[2]), silu_mul(g1[3], u1[3]));
;                 *(GAS u32x4*)(O + (size_t)(row0 + ai * 128 + m * 16) * DFF + col0) = w; }
;     }
	v_pk_mul_f32 v[6:7], v[144:145], v[6:7] op_sel_hi:[0,1]
	v_mul_f32_e32 v99, v112, v99
	v_mul_f32_e32 v102, v113, v102
	v_mul_f32_e32 v99, v99, v104
	v_mul_f32_e32 v102, v102, v105
	v_cvt_pk_bf16_f32 v99, v99, v102
	v_mul_f32_e32 v102, 0xbfb8aa3b, v106
	v_exp_f32_e32 v102, v102
	v_pk_mul_f32 v[8:9], v[144:145], v[8:9] op_sel_hi:[0,1]
	v_pk_mul_f32 v[10:11], v[144:145], v[10:11] op_sel_hi:[0,1]
	s_mov_b64 s[44:45], -1
	v_add_f32_e32 v102, 1.0, v102
	v_rcp_f32_e32 v102, v102
	s_andn2_b64 vcc, exec, s[80:81]
	v_mul_f32_e32 v102, v106, v102
	v_mul_f32_e32 v100, v102, v100
	v_mul_f32_e32 v102, 0xbfb8aa3b, v107
	v_exp_f32_e32 v102, v102
	s_nop 0
	v_add_f32_e32 v102, 1.0, v102
	v_rcp_f32_e32 v102, v102
	s_nop 0
	v_mul_f32_e32 v102, v107, v102
	v_mul_f32_e32 v101, v102, v101
	v_cvt_pk_bf16_f32 v100, v100, v101
	v_mul_f32_e32 v101, 0xbfb8aa3b, v108
	v_mul_f32_e32 v102, 0xbfb8aa3b, v109
	v_exp_f32_e32 v101, v101
	v_exp_f32_e32 v102, v102
	v_add_f32_e32 v101, 1.0, v101
	v_add_f32_e32 v102, 1.0, v102
	v_rcp_f32_e32 v101, v101
	v_rcp_f32_e32 v102, v102
	v_mul_f32_e32 v101, v108, v101
	v_mul_f32_e32 v102, v109, v102
	v_mul_f32_e32 v101, v101, v118
	v_mul_f32_e32 v102, v102, v119
	v_cvt_pk_bf16_f32 v101, v101, v102
	v_or_b32_e32 v102, 16, v151
	v_mad_i64_i32 v[102:103], s[38:39], v102, s29, v[114:115]
	v_lshl_add_u64 v[102:103], v[102:103], 0, v[116:117]
	global_store_dwordx4 v[102:103], v[98:101], off
	s_nop 1
	v_pk_mul_f32 v[98:99], v[154:155], v[84:85] op_sel_hi:[0,1]
	v_pk_mul_f32 v[84:85], v[154:155], v[82:83] op_sel_hi:[0,1]
	v_mul_f32_e32 v82, 0xbfb8aa3b, v94
	v_mul_f32_e32 v83, 0xbfb8aa3b, v95
	v_exp_f32_e32 v82, v82
	v_exp_f32_e32 v83, v83
	v_add_f32_e32 v82, 1.0, v82
	v_add_f32_e32 v83, 1.0, v83
	v_rcp_f32_e32 v82, v82
	v_rcp_f32_e32 v83, v83
	v_mul_f32_e32 v82, v94, v82
	v_mul_f32_e32 v83, v95, v83
	v_mul_f32_e32 v82, v82, v86
	v_mul_f32_e32 v83, v83, v87
	v_cvt_pk_bf16_f32 v82, v82, v83
	v_mul_f32_e32 v83, 0xbfb8aa3b, v96
	v_mul_f32_e32 v86, 0xbfb8aa3b, v97
	v_exp_f32_e32 v83, v83
	v_exp_f32_e32 v86, v86
	v_add_f32_e32 v83, 1.0, v83
	v_add_f32_e32 v86, 1.0, v86
	v_rcp_f32_e32 v83, v83
	v_rcp_f32_e32 v86, v86
	v_mul_f32_e32 v83, v96, v83
	v_mul_f32_e32 v86, v97, v86
	v_mul_f32_e32 v83, v83, v88
	v_mul_f32_e32 v86, v86, v89
	v_cvt_pk_bf16_f32 v83, v83, v86
	v_mul_f32_e32 v86, 0xbfb8aa3b, v90
	v_exp_f32_e32 v86, v86
	s_nop 0
	v_add_f32_e32 v86, 1.0, v86
	v_rcp_f32_e32 v86, v86
	s_nop 0
	v_mul_f32_e32 v86, v90, v86
	v_mul_f32_e32 v84, v86, v84
	v_mul_f32_e32 v86, 0xbfb8aa3b, v91
	v_exp_f32_e32 v86, v86
	s_nop 0
	v_add_f32_e32 v86, 1.0, v86
	v_rcp_f32_e32 v86, v86
	s_nop 0
	v_mul_f32_e32 v86, v91, v86
	v_mul_f32_e32 v85, v86, v85
	v_cvt_pk_bf16_f32 v84, v84, v85
	v_mul_f32_e32 v85, 0xbfb8aa3b, v92
	v_mul_f32_e32 v86, 0xbfb8aa3b, v93
	v_exp_f32_e32 v85, v85
	v_exp_f32_e32 v86, v86
	v_add_f32_e32 v85, 1.0, v85
	v_add_f32_e32 v86, 1.0, v86
	v_rcp_f32_e32 v85, v85
	v_rcp_f32_e32 v86, v86
	v_mul_f32_e32 v85, v92, v85
	v_mul_f32_e32 v86, v93, v86
	v_mul_f32_e32 v85, v85, v98
	v_mul_f32_e32 v86, v86, v99
	v_cvt_pk_bf16_f32 v85, v85, v86
	v_or_b32_e32 v86, 32, v151
	v_mad_i64_i32 v[86:87], s[38:39], v86, s29, v[114:115]
	v_lshl_add_u64 v[86:87], v[86:87], 0, v[116:117]
	global_store_dwordx4 v[86:87], v[82:85], off
	s_nop 1
	v_pk_mul_f32 v[82:83], v[152:153], v[68:69] op_sel_hi:[0,1]
	v_pk_mul_f32 v[68:69], v[152:153], v[66:67] op_sel_hi:[0,1]
	v_mul_f32_e32 v66, 0xbfb8aa3b, v78
	v_mul_f32_e32 v67, 0xbfb8aa3b, v79
	v_exp_f32_e32 v66, v66
	v_exp_f32_e32 v67, v67
	v_add_f32_e32 v66, 1.0, v66
	v_add_f32_e32 v67, 1.0, v67
	v_rcp_f32_e32 v66, v66
	v_rcp_f32_e32 v67, v67
	v_mul_f32_e32 v66, v78, v66
	v_mul_f32_e32 v67, v79, v67
	v_mul_f32_e32 v66, v66, v70
	v_mul_f32_e32 v67, v67, v71
	v_cvt_pk_bf16_f32 v66, v66, v67
	v_mul_f32_e32 v67, 0xbfb8aa3b, v80
	v_mul_f32_e32 v70, 0xbfb8aa3b, v81
	v_exp_f32_e32 v67, v67
	v_exp_f32_e32 v70, v70
	v_add_f32_e32 v67, 1.0, v67
	v_add_f32_e32 v70, 1.0, v70
	v_rcp_f32_e32 v67, v67
	v_rcp_f32_e32 v70, v70
	v_mul_f32_e32 v67, v80, v67
	v_mul_f32_e32 v70, v81, v70
	v_mul_f32_e32 v67, v67, v72
	v_mul_f32_e32 v70, v70, v73
	v_cvt_pk_bf16_f32 v67, v67, v70
	v_mul_f32_e32 v70, 0xbfb8aa3b, v74
	v_exp_f32_e32 v70, v70
	s_nop 0
	v_add_f32_e32 v70, 1.0, v70
	v_rcp_f32_e32 v70, v70
	s_nop 0
	v_mul_f32_e32 v70, v74, v70
	v_mul_f32_e32 v68, v70, v68
	v_mul_f32_e32 v70, 0xbfb8aa3b, v75
	v_exp_f32_e32 v70, v70
	s_nop 0
	v_add_f32_e32 v70, 1.0, v70
	v_rcp_f32_e32 v70, v70
	s_nop 0
	v_mul_f32_e32 v70, v75, v70
	v_mul_f32_e32 v69, v70, v69
	v_cvt_pk_bf16_f32 v68, v68, v69
	v_mul_f32_e32 v69, 0xbfb8aa3b, v76
	v_mul_f32_e32 v70, 0xbfb8aa3b, v77
	v_exp_f32_e32 v69, v69
	v_exp_f32_e32 v70, v70
	v_add_f32_e32 v69, 1.0, v69
	v_add_f32_e32 v70, 1.0, v70
	v_rcp_f32_e32 v69, v69
	v_rcp_f32_e32 v70, v70
	v_mul_f32_e32 v69, v76, v69
	v_mul_f32_e32 v70, v77, v70
	v_mul_f32_e32 v69, v69, v82
	v_mul_f32_e32 v70, v70, v83
	v_cvt_pk_bf16_f32 v69, v69, v70
	v_or_b32_e32 v70, 48, v151
	v_mad_i64_i32 v[70:71], s[38:39], v70, s29, v[114:115]
	v_lshl_add_u64 v[70:71], v[70:71], 0, v[116:117]
	global_store_dwordx4 v[70:71], v[66:69], off
	s_nop 1
	v_pk_mul_f32 v[66:67], v[150:151], v[52:53] op_sel_hi:[0,1]
	v_pk_mul_f32 v[52:53], v[150:151], v[50:51] op_sel_hi:[0,1]
	v_mul_f32_e32 v50, 0xbfb8aa3b, v62
	v_mul_f32_e32 v51, 0xbfb8aa3b, v63
	v_exp_f32_e32 v50, v50
	v_exp_f32_e32 v51, v51
	v_add_u32_e32 v68, 0x80, v151
	v_add_f32_e32 v50, 1.0, v50
	v_add_f32_e32 v51, 1.0, v51
	v_rcp_f32_e32 v50, v50
	v_rcp_f32_e32 v51, v51
	v_mul_f32_e32 v50, v62, v50
	v_mul_f32_e32 v51, v63, v51
	v_mul_f32_e32 v50, v50, v54
	v_mul_f32_e32 v51, v51, v55
	v_cvt_pk_bf16_f32 v50, v50, v51
; __device__ __forceinline__ unsigned cvt_pk_bf16(float lo, float hi) { unsigned r; asm volatile("v_cvt_pk_bf16_f32 %0, %1, %2" : "=v"(r) : "v"(lo), "v"(hi)); return r; }
; #define GAS __attribute__((address_space(1)))
; __device__ __forceinline__ float silu_mul(float g, float u) { const float e = __builtin_amdgcn_exp2f(-1.4426950408889634f * g); return g * __builtin_amdgcn_rcpf(1.0f + e) * u; }
;     __device__ __forceinline__ void operator()(const f32x4 (&acc)[2][2][4][2], const Unit& u, int wr, int wc, int fr, int fq, const float (&pre)[8]) const {
;         const int row0 = u.pm * 256 + wr * 64 + fr, col0 = u.pn * 128 + wc * 32 + 8 * fq;
; #pragma unroll
;         for (int ai = 0; ai < 2; ++ai)
; #pragma unroll
;             for (int m = 0; m < 4; ++m) {
;                 const float rsc = pre[ai * 4 + m];
;                 const f32x4 g0 = acc[ai][0][m][0] * rsc, g1 = acc[ai][0][m][1] * rsc, u0 = acc[ai][1][m][0] * rsc, u1 = acc[ai][1][m][1] * rsc;
;                 u32x4 w; w.x = cvt_pk_bf16(silu_mul(g0[0], u0[0]), silu_mul(g0[1], u0[1])); w.y = cvt_pk_bf16(silu_mul(g0[2], u0[2]), silu_mul(g0[3], u0[3]));
;                 w.z = cvt_pk_bf16(silu_mul(g1[0], u1[0]), silu_mul(g1[1], u1[1])); w.w = cvt_pk_bf16(silu_mul(g1[2], u1[2]), silu_mul(g1[3], u1[3]));
;                 *(GAS u32x4*)(O + (size_t)(row0 + ai * 128 + m * 16) * DFF + col0) = w; }
;     }
	v_mul_f32_e32 v51, 0xbfb8aa3b, v64
	v_mul_f32_e32 v54, 0xbfb8aa3b, v65
	v_exp_f32_e32 v51, v51
	v_exp_f32_e32 v54, v54
	v_add_f32_e32 v51, 1.0, v51
	v_add_f32_e32 v54, 1.0, v54
	v_rcp_f32_e32 v51, v51
	v_rcp_f32_e32 v54, v54
	v_mul_f32_e32 v51, v64, v51
	v_mul_f32_e32 v54, v65, v54
	v_mul_f32_e32 v51, v51, v56
	v_mul_f32_e32 v54, v54, v57
	v_cvt_pk_bf16_f32 v51, v51, v54
	v_mul_f32_e32 v54, 0xbfb8aa3b, v58
	v_exp_f32_e32 v54, v54
	s_nop 0
	v_add_f32_e32 v54, 1.0, v54
	v_rcp_f32_e32 v54, v54
	s_nop 0
	v_mul_f32_e32 v54, v58, v54
	v_mul_f32_e32 v52, v54, v52
	v_mul_f32_e32 v54, 0xbfb8aa3b, v59
	v_exp_f32_e32 v54, v54
	s_nop 0
	v_add_f32_e32 v54, 1.0, v54
	v_rcp_f32_e32 v54, v54
	s_nop 0
	v_mul_f32_e32 v54, v59, v54
	v_mul_f32_e32 v53, v54, v53
	v_cvt_pk_bf16_f32 v52, v52, v53
	v_mul_f32_e32 v53, 0xbfb8aa3b, v60
	v_mul_f32_e32 v54, 0xbfb8aa3b, v61
	v_exp_f32_e32 v53, v53
	v_exp_f32_e32 v54, v54
	v_add_f32_e32 v53, 1.0, v53
	v_add_f32_e32 v54, 1.0, v54
	v_rcp_f32_e32 v53, v53
	v_rcp_f32_e32 v54, v54
	v_mul_f32_e32 v53, v60, v53
	v_mul_f32_e32 v54, v61, v54
	v_mul_f32_e32 v53, v53, v66
	v_mul_f32_e32 v54, v54, v67
	v_cvt_pk_bf16_f32 v53, v53, v54
	v_mad_i64_i32 v[54:55], s[38:39], v68, s29, v[114:115]
	v_lshl_add_u64 v[54:55], v[54:55], 0, v[116:117]
	global_store_dwordx4 v[54:55], v[50:53], off
	s_nop 1
	v_pk_mul_f32 v[50:51], v[148:149], v[36:37] op_sel_hi:[0,1]
	v_pk_mul_f32 v[36:37], v[148:149], v[34:35] op_sel_hi:[0,1]
	v_mul_f32_e32 v34, 0xbfb8aa3b, v46
	v_mul_f32_e32 v35, 0xbfb8aa3b, v47
	v_exp_f32_e32 v34, v34
	v_exp_f32_e32 v35, v35
	v_add_f32_e32 v34, 1.0, v34
	v_add_f32_e32 v35, 1.0, v35
	v_rcp_f32_e32 v34, v34
	v_rcp_f32_e32 v35, v35
	v_mul_f32_e32 v34, v46, v34
	v_mul_f32_e32 v35, v47, v35
	v_mul_f32_e32 v34, v34, v38
	v_mul_f32_e32 v35, v35, v39
	v_cvt_pk_bf16_f32 v34, v34, v35
	v_mul_f32_e32 v35, 0xbfb8aa3b, v48
	v_mul_f32_e32 v38, 0xbfb8aa3b, v49
	v_exp_f32_e32 v35, v35
	v_exp_f32_e32 v38, v38
	v_add_f32_e32 v35, 1.0, v35
	v_add_f32_e32 v38, 1.0, v38
	v_rcp_f32_e32 v35, v35
	v_rcp_f32_e32 v38, v38
	v_mul_f32_e32 v35, v48, v35
	v_mul_f32_e32 v38, v49, v38
	v_mul_f32_e32 v35, v35, v40
	v_mul_f32_e32 v38, v38, v41
	v_cvt_pk_bf16_f32 v35, v35, v38
	v_mul_f32_e32 v38, 0xbfb8aa3b, v42
	v_exp_f32_e32 v38, v38
	s_nop 0
	v_add_f32_e32 v38, 1.0, v38
	v_rcp_f32_e32 v38, v38
	s_nop 0
	v_mul_f32_e32 v38, v42, v38
	v_mul_f32_e32 v36, v38, v36
	v_mul_f32_e32 v38, 0xbfb8aa3b, v43
	v_exp_f32_e32 v38, v38
	s_nop 0
	v_add_f32_e32 v38, 1.0, v38
	v_rcp_f32_e32 v38, v38
	s_nop 0
	v_mul_f32_e32 v38, v43, v38
	v_mul_f32_e32 v37, v38, v37
	v_cvt_pk_bf16_f32 v36, v36, v37
	v_mul_f32_e32 v37, 0xbfb8aa3b, v44
	v_mul_f32_e32 v38, 0xbfb8aa3b, v45
	v_exp_f32_e32 v37, v37
	v_exp_f32_e32 v38, v38
	v_add_f32_e32 v37, 1.0, v37
	v_add_f32_e32 v38, 1.0, v38
	v_rcp_f32_e32 v37, v37
	v_rcp_f32_e32 v38, v38
	v_mul_f32_e32 v37, v44, v37
	v_mul_f32_e32 v38, v45, v38
	v_mul_f32_e32 v37, v37, v50
	v_mul_f32_e32 v38, v38, v51
	v_cvt_pk_bf16_f32 v37, v37, v38
	v_add_u32_e32 v38, 0x90, v151
	v_mad_i64_i32 v[38:39], s[38:39], v38, s29, v[114:115]
	v_lshl_add_u64 v[38:39], v[38:39], 0, v[116:117]
	global_store_dwordx4 v[38:39], v[34:37], off
	s_nop 1
	v_pk_mul_f32 v[34:35], v[146:147], v[18:19] op_sel_hi:[0,1]
	v_pk_mul_f32 v[18:19], v[146:147], v[16:17] op_sel_hi:[0,1]
	v_mul_f32_e32 v16, 0xbfb8aa3b, v28
	v_mul_f32_e32 v17, 0xbfb8aa3b, v29
	v_exp_f32_e32 v16, v16
	v_exp_f32_e32 v17, v17
	v_add_f32_e32 v16, 1.0, v16
	v_add_f32_e32 v17, 1.0, v17
	v_rcp_f32_e32 v16, v16
	v_rcp_f32_e32 v17, v17
	v_mul_f32_e32 v16, v28, v16
	v_mul_f32_e32 v17, v29, v17
	v_mul_f32_e32 v16, v16, v20
	v_mul_f32_e32 v17, v17, v21
	v_cvt_pk_bf16_f32 v16, v16, v17
	v_mul_f32_e32 v17, 0xbfb8aa3b, v30
	v_mul_f32_e32 v20, 0xbfb8aa3b, v31
	v_exp_f32_e32 v17, v17
	v_exp_f32_e32 v20, v20
	v_add_f32_e32 v17, 1.0, v17
	v_add_f32_e32 v20, 1.0, v20
	v_rcp_f32_e32 v17, v17
	v_rcp_f32_e32 v20, v20
	v_mul_f32_e32 v17, v30, v17
	v_mul_f32_e32 v20, v31, v20
	v_mul_f32_e32 v17, v17, v22
	v_mul_f32_e32 v20, v20, v23
	v_cvt_pk_bf16_f32 v17, v17, v20
	v_mul_f32_e32 v20, 0xbfb8aa3b, v24
	v_exp_f32_e32 v20, v20
	s_nop 0
	v_add_f32_e32 v20, 1.0, v20
	v_rcp_f32_e32 v20, v20
	s_nop 0
	v_mul_f32_e32 v20, v24, v20
	v_mul_f32_e32 v18, v20, v18
	v_mul_f32_e32 v20, 0xbfb8aa3b, v25
	v_exp_f32_e32 v20, v20
	s_nop 0
	v_add_f32_e32 v20, 1.0, v20
	v_rcp_f32_e32 v20, v20
	s_nop 0
	v_mul_f32_e32 v20, v25, v20
	v_mul_f32_e32 v19, v20, v19
	v_cvt_pk_bf16_f32 v18, v18, v19
	v_mul_f32_e32 v19, 0xbfb8aa3b, v26
	v_mul_f32_e32 v20, 0xbfb8aa3b, v27
	v_exp_f32_e32 v19, v19
	v_exp_f32_e32 v20, v20
	v_add_f32_e32 v19, 1.0, v19
	v_add_f32_e32 v20, 1.0, v20
	v_rcp_f32_e32 v19, v19
	v_rcp_f32_e32 v20, v20
	v_mul_f32_e32 v19, v26, v19
	v_mul_f32_e32 v20, v27, v20
	v_mul_f32_e32 v19, v19, v34
	v_mul_f32_e32 v20, v20, v35
	v_cvt_pk_bf16_f32 v19, v19, v20
	v_add_u32_e32 v20, 0xa0, v151
	v_mad_i64_i32 v[20:21], s[38:39], v20, s29, v[114:115]
	v_lshl_add_u64 v[20:21], v[20:21], 0, v[116:117]
	global_store_dwordx4 v[20:21], v[16:19], off
	s_nop 1
	v_pk_mul_f32 v[16:17], v[144:145], v[2:3] op_sel_hi:[0,1]
	v_pk_mul_f32 v[2:3], v[144:145], v[0:1] op_sel_hi:[0,1]
	v_mul_f32_e32 v0, 0xbfb8aa3b, v12
	v_mul_f32_e32 v1, 0xbfb8aa3b, v13
	v_exp_f32_e32 v0, v0
	v_exp_f32_e32 v1, v1
	v_add_f32_e32 v0, 1.0, v0
	v_add_f32_e32 v1, 1.0, v1
	v_rcp_f32_e32 v0, v0
	v_rcp_f32_e32 v1, v1
	v_mul_f32_e32 v0, v12, v0
	v_mul_f32_e32 v1, v13, v1
	v_mul_f32_e32 v0, v0, v4
	v_mul_f32_e32 v1, v1, v5
	v_cvt_pk_bf16_f32 v0, v0, v1
	v_mul_f32_e32 v1, 0xbfb8aa3b, v14
	v_mul_f32_e32 v4, 0xbfb8aa3b, v15
	v_exp_f32_e32 v1, v1
	v_exp_f32_e32 v4, v4
	v_add_f32_e32 v1, 1.0, v1
	v_add_f32_e32 v4, 1.0, v4
	v_rcp_f32_e32 v1, v1
	v_rcp_f32_e32 v4, v4
	v_mul_f32_e32 v1, v14, v1
	v_mul_f32_e32 v4, v15, v4
	v_mul_f32_e32 v1, v1, v6
	v_mul_f32_e32 v4, v4, v7
	v_cvt_pk_bf16_f32 v1, v1, v4
	v_mul_f32_e32 v4, 0xbfb8aa3b, v8
	v_exp_f32_e32 v4, v4
	s_nop 0
	v_add_f32_e32 v4, 1.0, v4
	v_rcp_f32_e32 v4, v4
	s_nop 0
	v_mul_f32_e32 v4, v8, v4
	v_mul_f32_e32 v2, v4, v2
	v_mul_f32_e32 v4, 0xbfb8aa3b, v9
	v_exp_f32_e32 v4, v4
	s_nop 0
	v_add_f32_e32 v4, 1.0, v4
	v_rcp_f32_e32 v4, v4
	s_nop 0
	v_mul_f32_e32 v4, v9, v4
	v_mul_f32_e32 v3, v4, v3
	v_cvt_pk_bf16_f32 v2, v2, v3
	v_mul_f32_e32 v3, 0xbfb8aa3b, v10
	v_mul_f32_e32 v4, 0xbfb8aa3b, v11
	v_exp_f32_e32 v3, v3
	v_exp_f32_e32 v4, v4
	v_add_f32_e32 v3, 1.0, v3
	v_add_f32_e32 v4, 1.0, v4
	v_rcp_f32_e32 v3, v3
	v_rcp_f32_e32 v4, v4
	v_mul_f32_e32 v3, v10, v3
	v_mul_f32_e32 v4, v11, v4
	v_mul_f32_e32 v3, v3, v16
	v_mul_f32_e32 v4, v4, v17
	v_cvt_pk_bf16_f32 v3, v3, v4
	v_add_u32_e32 v4, 0xb0, v151
	v_mad_i64_i32 v[4:5], s[38:39], v4, s29, v[114:115]
	v_lshl_add_u64 v[4:5], v[4:5], 0, v[116:117]
	global_store_dwordx4 v[4:5], v[0:3], off
	s_cbranch_vccnz .LBB0_439
; #define PG8_BAR __builtin_amdgcn_s_barrier()
; #define GAS __attribute__((address_space(1)))
; template <class Epi, class Sched, bool ALIGN_EPI = false, bool SP2 = false>
; __device__ __forceinline__ void gemm_phase(PG8_LAS unsigned char* lds, const Gemm g, const Sched& S, const Epi& E) {
;     ...
;         if constexpr (Epi::PREFETCH) E.prefetch(cur, wr, fr, epre);
;         if constexpr (ALIGN_EPI) { if (wr == 1) PG8_BAR; }
;     __device__ __forceinline__ void prefetch(const Unit& u, int wr, int fr, float (&pre)[8]) const {
; #pragma unroll
;         for (int i = 0; i < 8; ++i) pre[i] = *(const GAS float*)(rs + u.pm * 256 + wr * 64 + fr + (i >> 2) * 128 + (i & 3) * 16);
	s_lshl_b32 s38, s42, 8
	s_ashr_i32 s39, s38, 31
	v_lshl_add_u64 v[0:1], s[38:39], 2, v[138:139]
	global_load_dword v158, v[0:1], off
	global_load_dword v156, v[0:1], off offset:64
	global_load_dword v154, v[0:1], off offset:128
	global_load_dword v152, v[0:1], off offset:192
	global_load_dword v150, v[0:1], off offset:512
	global_load_dword v148, v[0:1], off offset:576
	global_load_dword v146, v[0:1], off offset:640
	global_load_dword v144, v[0:1], off offset:704
	s_andn2_b64 vcc, exec, s[2:3]
	s_cbranch_vccnz .LBB0_438
	s_barrier
	s_branch .LBB0_438

; __device__ __forceinline__ unsigned cvt_pk_bf16(float lo, float hi) { unsigned r; asm volatile("v_cvt_pk_bf16_f32 %0, %1, %2" : "=v"(r) : "v"(lo), "v"(hi)); return r; }
; #define GAS __attribute__((address_space(1)))
; __device__ __forceinline__ float silu_mul(float g, float u) { const float e = __builtin_amdgcn_exp2f(-1.4426950408889634f * g); return g * __builtin_amdgcn_rcpf(1.0f + e) * u; }
;     __device__ __forceinline__ void operator()(const f32x4 (&acc)[2][2][4][2], const Unit& u, int wr, int wc, int fr, int fq, const float (&pre)[8]) const {
;         const int row0 = u.pm * 256 + wr * 64 + fr, col0 = u.pn * 128 + wc * 32 + 8 * fq;
; #pragma unroll
;         for (int ai = 0; ai < 2; ++ai)
; #pragma unroll
;             for (int m = 0; m < 4; ++m) {
;                 const float rsc = pre[ai * 4 + m];
;                 const f32x4 g0 = acc[ai][0][m][0] * rsc, g1 = acc[ai][0][m][1] * rsc, u0 = acc[ai][1][m][0] * rsc, u1 = acc[ai][1][m][1] * rsc;
;                 u32x4 w; w.x = cvt_pk_bf16(silu_mul(g0[0], u0[0]), silu_mul(g0[1], u0[1])); w.y = cvt_pk_bf16(silu_mul(g0[2], u0[2]), silu_mul(g0[3], u0[3]));
;                 w.z = cvt_pk_bf16(silu_mul(g1[0], u1[0]), silu_mul(g1[1], u1[1])); w.w = cvt_pk_bf16(silu_mul(g1[2], u1[2]), silu_mul(g1[3], u1[3]));
;                 *(GAS u32x4*)(O + (size_t)(row0 + ai * 128 + m * 16) * DFF + col0) = w; }
;     }
.LBB0_583:
	v_pk_mul_f32 v[126:127], v[158:159], v[126:127] op_sel_hi:[0,1]
	v_mul_f32_e32 v153, 0xbfb8aa3b, v126
	v_exp_f32_e32 v153, v153
	v_pk_mul_f32 v[118:119], v[158:159], v[118:119] op_sel_hi:[0,1]
	v_pk_mul_f32 v[128:129], v[158:159], v[128:129] op_sel_hi:[0,1]
	v_pk_mul_f32 v[120:121], v[158:159], v[120:121] op_sel_hi:[0,1]
	v_add_f32_e32 v153, 1.0, v153
	v_rcp_f32_e32 v153, v153
	v_pk_mul_f32 v[122:123], v[158:159], v[122:123] op_sel_hi:[0,1]
	v_pk_mul_f32 v[114:115], v[158:159], v[114:115] op_sel_hi:[0,1]
	v_pk_mul_f32 v[124:125], v[158:159], v[124:125] op_sel_hi:[0,1]
	v_mul_f32_e32 v126, v126, v153
	v_mul_f32_e32 v118, v126, v118
	v_mul_f32_e32 v126, 0xbfb8aa3b, v127
	v_exp_f32_e32 v126, v126
	v_pk_mul_f32 v[116:117], v[158:159], v[116:117] op_sel_hi:[0,1]
	v_lshl_or_b32 v160, s45, 7, v147
	v_lshl_add_u32 v151, s44, 8, v33
	v_add_f32_e32 v126, 1.0, v126
	v_rcp_f32_e32 v126, v126
	v_ashrrev_i32_e32 v161, 31, v160
	v_pk_mul_f32 v[110:111], v[156:157], v[110:111] op_sel_hi:[0,1]
	v_pk_mul_f32 v[102:103], v[156:157], v[102:103] op_sel_hi:[0,1]
	v_mul_f32_e32 v126, v127, v126
	v_mul_f32_e32 v119, v126, v119
	v_cvt_pk_bf16_f32 v118, v118, v119
	v_mul_f32_e32 v119, 0xbfb8aa3b, v128
	v_exp_f32_e32 v119, v119
	v_pk_mul_f32 v[112:113], v[156:157], v[112:113] op_sel_hi:[0,1]
	v_pk_mul_f32 v[104:105], v[156:157], v[104:105] op_sel_hi:[0,1]
	v_pk_mul_f32 v[106:107], v[156:157], v[106:107] op_sel_hi:[0,1]
	v_add_f32_e32 v119, 1.0, v119
	v_rcp_f32_e32 v119, v119
	v_pk_mul_f32 v[108:109], v[156:157], v[108:109] op_sel_hi:[0,1]
	v_pk_mul_f32 v[94:95], v[154:155], v[94:95] op_sel_hi:[0,1]
	v_pk_mul_f32 v[86:87], v[154:155], v[86:87] op_sel_hi:[0,1]
	v_mul_f32_e32 v119, v128, v119
	v_mul_f32_e32 v119, v119, v120
	v_mul_f32_e32 v120, 0xbfb8aa3b, v129
	v_exp_f32_e32 v120, v120
	v_pk_mul_f32 v[96:97], v[154:155], v[96:97] op_sel_hi:[0,1]
	v_pk_mul_f32 v[88:89], v[154:155], v[88:89] op_sel_hi:[0,1]
	v_pk_mul_f32 v[90:91], v[154:155], v[90:91] op_sel_hi:[0,1]
	v_add_f32_e32 v120, 1.0, v120
	v_rcp_f32_e32 v120, v120
	v_pk_mul_f32 v[92:93], v[154:155], v[92:93] op_sel_hi:[0,1]
	v_pk_mul_f32 v[78:79], v[152:153], v[78:79] op_sel_hi:[0,1]
	v_pk_mul_f32 v[70:71], v[152:153], v[70:71] op_sel_hi:[0,1]
	v_mul_f32_e32 v120, v129, v120
	v_mul_f32_e32 v120, v120, v121
	v_cvt_pk_bf16_f32 v119, v119, v120
	v_mul_f32_e32 v120, 0xbfb8aa3b, v122
	v_exp_f32_e32 v120, v120
	v_pk_mul_f32 v[80:81], v[152:153], v[80:81] op_sel_hi:[0,1]
	v_pk_mul_f32 v[72:73], v[152:153], v[72:73] op_sel_hi:[0,1]
	v_pk_mul_f32 v[74:75], v[152:153], v[74:75] op_sel_hi:[0,1]
	v_add_f32_e32 v120, 1.0, v120
	v_rcp_f32_e32 v120, v120
	v_pk_mul_f32 v[76:77], v[152:153], v[76:77] op_sel_hi:[0,1]
	v_pk_mul_f32 v[62:63], v[150:151], v[62:63] op_sel_hi:[0,1]
	v_pk_mul_f32 v[54:55], v[150:151], v[54:55] op_sel_hi:[0,1]
	v_mul_f32_e32 v120, v122, v120
	v_mul_f32_e32 v114, v120, v114
	v_mul_f32_e32 v120, 0xbfb8aa3b, v123
	v_exp_f32_e32 v120, v120
	v_pk_mul_f32 v[64:65], v[150:151], v[64:65] op_sel_hi:[0,1]
	v_pk_mul_f32 v[56:57], v[150:151], v[56:57] op_sel_hi:[0,1]
	v_pk_mul_f32 v[58:59], v[150:151], v[58:59] op_sel_hi:[0,1]
	v_add_f32_e32 v120, 1.0, v120
	v_rcp_f32_e32 v120, v120
	v_pk_mul_f32 v[60:61], v[150:151], v[60:61] op_sel_hi:[0,1]
	v_pk_mul_f32 v[46:47], v[148:149], v[46:47] op_sel_hi:[0,1]
	v_pk_mul_f32 v[38:39], v[148:149], v[38:39] op_sel_hi:[0,1]
	v_mul_f32_e32 v120, v123, v120
	v_mul_f32_e32 v115, v120, v115
	v_cvt_pk_bf16_f32 v120, v114, v115
	v_mul_f32_e32 v114, 0xbfb8aa3b, v124
	v_mul_f32_e32 v115, 0xbfb8aa3b, v125
	v_exp_f32_e32 v114, v114
	v_exp_f32_e32 v115, v115
	v_pk_mul_f32 v[48:49], v[148:149], v[48:49] op_sel_hi:[0,1]
	v_pk_mul_f32 v[40:41], v[148:149], v[40:41] op_sel_hi:[0,1]
	v_add_f32_e32 v114, 1.0, v114
	v_add_f32_e32 v115, 1.0, v115
	v_rcp_f32_e32 v114, v114
	v_rcp_f32_e32 v115, v115
	v_pk_mul_f32 v[42:43], v[148:149], v[42:43] op_sel_hi:[0,1]
	v_pk_mul_f32 v[44:45], v[148:149], v[44:45] op_sel_hi:[0,1]
	v_mul_f32_e32 v114, v124, v114
	v_mul_f32_e32 v115, v125, v115
	v_mul_f32_e32 v114, v114, v116
	v_mul_f32_e32 v115, v115, v117
	v_cvt_pk_bf16_f32 v121, v114, v115
	v_mov_b64_e32 v[114:115], s[64:65]
	v_mad_i64_i32 v[122:123], s[44:45], v151, s29, v[114:115]
	v_lshlrev_b64 v[116:117], 1, v[160:161]
	v_lshl_add_u64 v[122:123], v[122:123], 0, v[116:117]
	global_store_dwordx4 v[122:123], v[118:121], off
	v_pk_mul_f32 v[28:29], v[146:147], v[28:29] op_sel_hi:[0,1]
	v_pk_mul_f32 v[20:21], v[146:147], v[20:21] op_sel_hi:[0,1]
	v_pk_mul_f32 v[118:119], v[156:157], v[100:101] op_sel_hi:[0,1]
	v_pk_mul_f32 v[100:101], v[156:157], v[98:99] op_sel_hi:[0,1]
	v_mul_f32_e32 v98, 0xbfb8aa3b, v110
	v_mul_f32_e32 v99, 0xbfb8aa3b, v111
	v_exp_f32_e32 v98, v98
	v_exp_f32_e32 v99, v99
	v_pk_mul_f32 v[30:31], v[146:147], v[30:31] op_sel_hi:[0,1]
	v_pk_mul_f32 v[22:23], v[146:147], v[22:23] op_sel_hi:[0,1]
	v_add_f32_e32 v98, 1.0, v98
	v_add_f32_e32 v99, 1.0, v99
	v_rcp_f32_e32 v98, v98
	v_rcp_f32_e32 v99, v99
	v_pk_mul_f32 v[24:25], v[146:147], v[24:25] op_sel_hi:[0,1]
	v_pk_mul_f32 v[26:27], v[146:147], v[26:27] op_sel_hi:[0,1]
	v_mul_f32_e32 v98, v110, v98
	v_mul_f32_e32 v99, v111, v99
	v_mul_f32_e32 v98, v98, v102
	v_mul_f32_e32 v99, v99, v103
	v_cvt_pk_bf16_f32 v98, v98, v99
	v_mul_f32_e32 v99, 0xbfb8aa3b, v112
	v_mul_f32_e32 v102, 0xbfb8aa3b, v113
	v_exp_f32_e32 v99, v99
	v_exp_f32_e32 v102, v102
	v_pk_mul_f32 v[12:13], v[144:145], v[12:13] op_sel_hi:[0,1]
	v_pk_mul_f32 v[4:5], v[144:145], v[4:5] op_sel_hi:[0,1]
	v_add_f32_e32 v99, 1.0, v99
	v_add_f32_e32 v102, 1.0, v102
	v_rcp_f32_e32 v99, v99
	v_rcp_f32_e32 v102, v102
	v_pk_mul_f32 v[14:15], v[144:145], v[14:15] op_sel_hi:[0,1]
; __device__ __forceinline__ unsigned cvt_pk_bf16(float lo, float hi) { unsigned r; asm volatile("v_cvt_pk_bf16_f32 %0, %1, %2" : "=v"(r) : "v"(lo), "v"(hi)); return r; }
; #define GAS __attribute__((address_space(1)))
; __device__ __forceinline__ float silu_mul(float g, float u) { const float e = __builtin_amdgcn_exp2f(-1.4426950408889634f * g); return g * __builtin_amdgcn_rcpf(1.0f + e) * u; }
;     __device__ __forceinline__ void operator()(const f32x4 (&acc)[2][2][4][2], const Unit& u, int wr, int wc, int fr, int fq, const float (&pre)[8]) const {
;         const int row0 = u.pm * 256 + wr * 64 + fr, col0 = u.pn * 128 + wc * 32 + 8 * fq;
; #pragma unroll
;         for (int ai = 0; ai < 2; ++ai)
; #pragma unroll
;             for (int m = 0; m < 4; ++m) {
;                 const float rsc = pre[ai * 4 + m];
;                 const f32x4 g0 = acc[ai][0][m][0] * rsc, g1 = acc[ai][0][m][1] * rsc, u0 = acc[ai][1][m][0] * rsc, u1 = acc[ai][1][m][1] * rsc;
;                 u32x4 w; w.x = cvt_pk_bf16(silu_mul(g0[0], u0[0]), silu_mul(g0[1], u0[1])); w.y = cvt_pk_bf16(silu_mul(g0[2], u0[2]), silu_mul(g0[3], u0[3]));
;                 w.z = cvt_pk_bf16(silu_mul(g1[0], u1[0]), silu_mul(g1[1], u1[1])); w.w = cvt_pk_bf16(silu_mul(g1[2], u1[2]), silu_mul(g1[3], u1[3]));
;                 *(GAS u32x4*)(O + (size_t)(row0 + ai * 128 + m * 16) * DFF + col0) = w; }
;     }
	v_pk_mul_f32 v[6:7], v[144:145], v[6:7] op_sel_hi:[0,1]
	v_mul_f32_e32 v99, v112, v99
	v_mul_f32_e32 v102, v113, v102
	v_mul_f32_e32 v99, v99, v104
	v_mul_f32_e32 v102, v102, v105
	v_cvt_pk_bf16_f32 v99, v99, v102
	v_mul_f32_e32 v102, 0xbfb8aa3b, v106
	v_exp_f32_e32 v102, v102
	v_pk_mul_f32 v[8:9], v[144:145], v[8:9] op_sel_hi:[0,1]
	v_pk_mul_f32 v[10:11], v[144:145], v[10:11] op_sel_hi:[0,1]
	s_andn2_b64 vcc, exec, s[42:43]
	v_add_f32_e32 v102, 1.0, v102
	v_rcp_f32_e32 v102, v102
	s_nop 0
	v_mul_f32_e32 v102, v106, v102
	v_mul_f32_e32 v100, v102, v100
	v_mul_f32_e32 v102, 0xbfb8aa3b, v107
	v_exp_f32_e32 v102, v102
	s_nop 0
	v_add_f32_e32 v102, 1.0, v102
	v_rcp_f32_e32 v102, v102
	s_nop 0
	v_mul_f32_e32 v102, v107, v102
	v_mul_f32_e32 v101, v102, v101
	v_cvt_pk_bf16_f32 v100, v100, v101
	v_mul_f32_e32 v101, 0xbfb8aa3b, v108
	v_mul_f32_e32 v102, 0xbfb8aa3b, v109
	v_exp_f32_e32 v101, v101
	v_exp_f32_e32 v102, v102
	v_add_f32_e32 v101, 1.0, v101
	v_add_f32_e32 v102, 1.0, v102
	v_rcp_f32_e32 v101, v101
	v_rcp_f32_e32 v102, v102
	v_mul_f32_e32 v101, v108, v101
	v_mul_f32_e32 v102, v109, v102
	v_mul_f32_e32 v101, v101, v118
	v_mul_f32_e32 v102, v102, v119
	v_cvt_pk_bf16_f32 v101, v101, v102
	v_or_b32_e32 v102, 16, v151
	v_mad_i64_i32 v[102:103], s[44:45], v102, s29, v[114:115]
	v_lshl_add_u64 v[102:103], v[102:103], 0, v[116:117]
	global_store_dwordx4 v[102:103], v[98:101], off
	s_nop 1
	v_pk_mul_f32 v[98:99], v[154:155], v[84:85] op_sel_hi:[0,1]
	v_pk_mul_f32 v[84:85], v[154:155], v[82:83] op_sel_hi:[0,1]
	v_mul_f32_e32 v82, 0xbfb8aa3b, v94
	v_mul_f32_e32 v83, 0xbfb8aa3b, v95
	v_exp_f32_e32 v82, v82
	v_exp_f32_e32 v83, v83
	v_add_f32_e32 v82, 1.0, v82
	v_add_f32_e32 v83, 1.0, v83
	v_rcp_f32_e32 v82, v82
	v_rcp_f32_e32 v83, v83
	v_mul_f32_e32 v82, v94, v82
	v_mul_f32_e32 v83, v95, v83
	v_mul_f32_e32 v82, v82, v86
	v_mul_f32_e32 v83, v83, v87
	v_cvt_pk_bf16_f32 v82, v82, v83
	v_mul_f32_e32 v83, 0xbfb8aa3b, v96
	v_mul_f32_e32 v86, 0xbfb8aa3b, v97
	v_exp_f32_e32 v83, v83
	v_exp_f32_e32 v86, v86
	v_add_f32_e32 v83, 1.0, v83
	v_add_f32_e32 v86, 1.0, v86
	v_rcp_f32_e32 v83, v83
	v_rcp_f32_e32 v86, v86
	v_mul_f32_e32 v83, v96, v83
	v_mul_f32_e32 v86, v97, v86
	v_mul_f32_e32 v83, v83, v88
	v_mul_f32_e32 v86, v86, v89
	v_cvt_pk_bf16_f32 v83, v83, v86
	v_mul_f32_e32 v86, 0xbfb8aa3b, v90
	v_exp_f32_e32 v86, v86
	s_nop 0
	v_add_f32_e32 v86, 1.0, v86
	v_rcp_f32_e32 v86, v86
	s_nop 0
	v_mul_f32_e32 v86, v90, v86
	v_mul_f32_e32 v84, v86, v84
	v_mul_f32_e32 v86, 0xbfb8aa3b, v91
	v_exp_f32_e32 v86, v86
	s_nop 0
	v_add_f32_e32 v86, 1.0, v86
	v_rcp_f32_e32 v86, v86
	s_nop 0
	v_mul_f32_e32 v86, v91, v86
	v_mul_f32_e32 v85, v86, v85
	v_cvt_pk_bf16_f32 v84, v84, v85
	v_mul_f32_e32 v85, 0xbfb8aa3b, v92
	v_mul_f32_e32 v86, 0xbfb8aa3b, v93
	v_exp_f32_e32 v85, v85
	v_exp_f32_e32 v86, v86
	v_add_f32_e32 v85, 1.0, v85
	v_add_f32_e32 v86, 1.0, v86
	v_rcp_f32_e32 v85, v85
	v_rcp_f32_e32 v86, v86
	v_mul_f32_e32 v85, v92, v85
	v_mul_f32_e32 v86, v93, v86
	v_mul_f32_e32 v85, v85, v98
	v_mul_f32_e32 v86, v86, v99
	v_cvt_pk_bf16_f32 v85, v85, v86
	v_or_b32_e32 v86, 32, v151
	v_mad_i64_i32 v[86:87], s[44:45], v86, s29, v[114:115]
	v_lshl_add_u64 v[86:87], v[86:87], 0, v[116:117]
	global_store_dwordx4 v[86:87], v[82:85], off
	s_nop 1
	v_pk_mul_f32 v[82:83], v[152:153], v[68:69] op_sel_hi:[0,1]
	v_pk_mul_f32 v[68:69], v[152:153], v[66:67] op_sel_hi:[0,1]
	v_mul_f32_e32 v66, 0xbfb8aa3b, v78
	v_mul_f32_e32 v67, 0xbfb8aa3b, v79
	v_exp_f32_e32 v66, v66
	v_exp_f32_e32 v67, v67
	v_add_f32_e32 v66, 1.0, v66
	v_add_f32_e32 v67, 1.0, v67
	v_rcp_f32_e32 v66, v66
	v_rcp_f32_e32 v67, v67
	v_mul_f32_e32 v66, v78, v66
	v_mul_f32_e32 v67, v79, v67
	v_mul_f32_e32 v66, v66, v70
	v_mul_f32_e32 v67, v67, v71
	v_cvt_pk_bf16_f32 v66, v66, v67
	v_mul_f32_e32 v67, 0xbfb8aa3b, v80
	v_mul_f32_e32 v70, 0xbfb8aa3b, v81
	v_exp_f32_e32 v67, v67
	v_exp_f32_e32 v70, v70
	v_add_f32_e32 v67, 1.0, v67
	v_add_f32_e32 v70, 1.0, v70
	v_rcp_f32_e32 v67, v67
	v_rcp_f32_e32 v70, v70
	v_mul_f32_e32 v67, v80, v67
	v_mul_f32_e32 v70, v81, v70
	v_mul_f32_e32 v67, v67, v72
	v_mul_f32_e32 v70, v70, v73
	v_cvt_pk_bf16_f32 v67, v67, v70
	v_mul_f32_e32 v70, 0xbfb8aa3b, v74
	v_exp_f32_e32 v70, v70
	s_nop 0
	v_add_f32_e32 v70, 1.0, v70
	v_rcp_f32_e32 v70, v70
	s_nop 0
	v_mul_f32_e32 v70, v74, v70
	v_mul_f32_e32 v68, v70, v68
	v_mul_f32_e32 v70, 0xbfb8aa3b, v75
	v_exp_f32_e32 v70, v70
	s_nop 0
	v_add_f32_e32 v70, 1.0, v70
	v_rcp_f32_e32 v70, v70
	s_nop 0
	v_mul_f32_e32 v70, v75, v70
	v_mul_f32_e32 v69, v70, v69
	v_cvt_pk_bf16_f32 v68, v68, v69
	v_mul_f32_e32 v69, 0xbfb8aa3b, v76
	v_mul_f32_e32 v70, 0xbfb8aa3b, v77
	v_exp_f32_e32 v69, v69
	v_exp_f32_e32 v70, v70
	v_add_f32_e32 v69, 1.0, v69
	v_add_f32_e32 v70, 1.0, v70
	v_rcp_f32_e32 v69, v69
	v_rcp_f32_e32 v70, v70
	v_mul_f32_e32 v69, v76, v69
	v_mul_f32_e32 v70, v77, v70
	v_mul_f32_e32 v69, v69, v82
	v_mul_f32_e32 v70, v70, v83
	v_cvt_pk_bf16_f32 v69, v69, v70
	v_or_b32_e32 v70, 48, v151
	v_mad_i64_i32 v[70:71], s[44:45], v70, s29, v[114:115]
	v_lshl_add_u64 v[70:71], v[70:71], 0, v[116:117]
	global_store_dwordx4 v[70:71], v[66:69], off
	s_nop 1
	v_pk_mul_f32 v[66:67], v[150:151], v[52:53] op_sel_hi:[0,1]
	v_pk_mul_f32 v[52:53], v[150:151], v[50:51] op_sel_hi:[0,1]
	v_mul_f32_e32 v50, 0xbfb8aa3b, v62
	v_mul_f32_e32 v51, 0xbfb8aa3b, v63
	v_exp_f32_e32 v50, v50
	v_exp_f32_e32 v51, v51
	v_add_u32_e32 v68, 0x80, v151
	v_add_f32_e32 v50, 1.0, v50
	v_add_f32_e32 v51, 1.0, v51
	v_rcp_f32_e32 v50, v50
	v_rcp_f32_e32 v51, v51
	v_mul_f32_e32 v50, v62, v50
	v_mul_f32_e32 v51, v63, v51
	v_mul_f32_e32 v50, v50, v54
	v_mul_f32_e32 v51, v51, v55
	v_cvt_pk_bf16_f32 v50, v50, v51
; __device__ __forceinline__ unsigned cvt_pk_bf16(float lo, float hi) { unsigned r; asm volatile("v_cvt_pk_bf16_f32 %0, %1, %2" : "=v"(r) : "v"(lo), "v"(hi)); return r; }
; #define GAS __attribute__((address_space(1)))
; __device__ __forceinline__ float silu_mul(float g, float u) { const float e = __builtin_amdgcn_exp2f(-1.4426950408889634f * g); return g * __builtin_amdgcn_rcpf(1.0f + e) * u; }
;     __device__ __forceinline__ void operator()(const f32x4 (&acc)[2][2][4][2], const Unit& u, int wr, int wc, int fr, int fq, const float (&pre)[8]) const {
;         const int row0 = u.pm * 256 + wr * 64 + fr, col0 = u.pn * 128 + wc * 32 + 8 * fq;
; #pragma unroll
;         for (int ai = 0; ai < 2; ++ai)
; #pragma unroll
;             for (int m = 0; m < 4; ++m) {
;                 const float rsc = pre[ai * 4 + m];
;                 const f32x4 g0 = acc[ai][0][m][0] * rsc, g1 = acc[ai][0][m][1] * rsc, u0 = acc[ai][1][m][0] * rsc, u1 = acc[ai][1][m][1] * rsc;
;                 u32x4 w; w.x = cvt_pk_bf16(silu_mul(g0[0], u0[0]), silu_mul(g0[1], u0[1])); w.y = cvt_pk_bf16(silu_mul(g0[2], u0[2]), silu_mul(g0[3], u0[3]));
;                 w.z = cvt_pk_bf16(silu_mul(g1[0], u1[0]), silu_mul(g1[1], u1[1])); w.w = cvt_pk_bf16(silu_mul(g1[2], u1[2]), silu_mul(g1[3], u1[3]));
;                 *(GAS u32x4*)(O + (size_t)(row0 + ai * 128 + m * 16) * DFF + col0) = w; }
;     }
	v_mul_f32_e32 v51, 0xbfb8aa3b, v64
	v_mul_f32_e32 v54, 0xbfb8aa3b, v65
	v_exp_f32_e32 v51, v51
	v_exp_f32_e32 v54, v54
	v_add_f32_e32 v51, 1.0, v51
	v_add_f32_e32 v54, 1.0, v54
	v_rcp_f32_e32 v51, v51
	v_rcp_f32_e32 v54, v54
	v_mul_f32_e32 v51, v64, v51
	v_mul_f32_e32 v54, v65, v54
	v_mul_f32_e32 v51, v51, v56
	v_mul_f32_e32 v54, v54, v57
	v_cvt_pk_bf16_f32 v51, v51, v54
	v_mul_f32_e32 v54, 0xbfb8aa3b, v58
	v_exp_f32_e32 v54, v54
	s_nop 0
	v_add_f32_e32 v54, 1.0, v54
	v_rcp_f32_e32 v54, v54
	s_nop 0
	v_mul_f32_e32 v54, v58, v54
	v_mul_f32_e32 v52, v54, v52
	v_mul_f32_e32 v54, 0xbfb8aa3b, v59
	v_exp_f32_e32 v54, v54
	s_nop 0
	v_add_f32_e32 v54, 1.0, v54
	v_rcp_f32_e32 v54, v54
	s_nop 0
	v_mul_f32_e32 v54, v59, v54
	v_mul_f32_e32 v53, v54, v53
	v_cvt_pk_bf16_f32 v52, v52, v53
	v_mul_f32_e32 v53, 0xbfb8aa3b, v60
	v_mul_f32_e32 v54, 0xbfb8aa3b, v61
	v_exp_f32_e32 v53, v53
	v_exp_f32_e32 v54, v54
	v_add_f32_e32 v53, 1.0, v53
	v_add_f32_e32 v54, 1.0, v54
	v_rcp_f32_e32 v53, v53
	v_rcp_f32_e32 v54, v54
	v_mul_f32_e32 v53, v60, v53
	v_mul_f32_e32 v54, v61, v54
	v_mul_f32_e32 v53, v53, v66
	v_mul_f32_e32 v54, v54, v67
	v_cvt_pk_bf16_f32 v53, v53, v54
	v_mad_i64_i32 v[54:55], s[44:45], v68, s29, v[114:115]
	v_lshl_add_u64 v[54:55], v[54:55], 0, v[116:117]
	global_store_dwordx4 v[54:55], v[50:53], off
	s_nop 1
	v_pk_mul_f32 v[50:51], v[148:149], v[36:37] op_sel_hi:[0,1]
	v_pk_mul_f32 v[36:37], v[148:149], v[34:35] op_sel_hi:[0,1]
	v_mul_f32_e32 v34, 0xbfb8aa3b, v46
	v_mul_f32_e32 v35, 0xbfb8aa3b, v47
	v_exp_f32_e32 v34, v34
	v_exp_f32_e32 v35, v35
	v_add_f32_e32 v34, 1.0, v34
	v_add_f32_e32 v35, 1.0, v35
	v_rcp_f32_e32 v34, v34
	v_rcp_f32_e32 v35, v35
	v_mul_f32_e32 v34, v46, v34
	v_mul_f32_e32 v35, v47, v35
	v_mul_f32_e32 v34, v34, v38
	v_mul_f32_e32 v35, v35, v39
	v_cvt_pk_bf16_f32 v34, v34, v35
	v_mul_f32_e32 v35, 0xbfb8aa3b, v48
	v_mul_f32_e32 v38, 0xbfb8aa3b, v49
	v_exp_f32_e32 v35, v35
	v_exp_f32_e32 v38, v38
	v_add_f32_e32 v35, 1.0, v35
	v_add_f32_e32 v38, 1.0, v38
	v_rcp_f32_e32 v35, v35
	v_rcp_f32_e32 v38, v38
	v_mul_f32_e32 v35, v48, v35
	v_mul_f32_e32 v38, v49, v38
	v_mul_f32_e32 v35, v35, v40
	v_mul_f32_e32 v38, v38, v41
	v_cvt_pk_bf16_f32 v35, v35, v38
	v_mul_f32_e32 v38, 0xbfb8aa3b, v42
	v_exp_f32_e32 v38, v38
	s_nop 0
	v_add_f32_e32 v38, 1.0, v38
	v_rcp_f32_e32 v38, v38
	s_nop 0
	v_mul_f32_e32 v38, v42, v38
	v_mul_f32_e32 v36, v38, v36
	v_mul_f32_e32 v38, 0xbfb8aa3b, v43
	v_exp_f32_e32 v38, v38
	s_nop 0
	v_add_f32_e32 v38, 1.0, v38
	v_rcp_f32_e32 v38, v38
	s_nop 0
	v_mul_f32_e32 v38, v43, v38
	v_mul_f32_e32 v37, v38, v37
	v_cvt_pk_bf16_f32 v36, v36, v37
	v_mul_f32_e32 v37, 0xbfb8aa3b, v44
	v_mul_f32_e32 v38, 0xbfb8aa3b, v45
	v_exp_f32_e32 v37, v37
	v_exp_f32_e32 v38, v38
	v_add_f32_e32 v37, 1.0, v37
	v_add_f32_e32 v38, 1.0, v38
	v_rcp_f32_e32 v37, v37
	v_rcp_f32_e32 v38, v38
	v_mul_f32_e32 v37, v44, v37
	v_mul_f32_e32 v38, v45, v38
	v_mul_f32_e32 v37, v37, v50
	v_mul_f32_e32 v38, v38, v51
	v_cvt_pk_bf16_f32 v37, v37, v38
	v_add_u32_e32 v38, 0x90, v151
	v_mad_i64_i32 v[38:39], s[44:45], v38, s29, v[114:115]
	v_lshl_add_u64 v[38:39], v[38:39], 0, v[116:117]
	global_store_dwordx4 v[38:39], v[34:37], off
	s_nop 1
	v_pk_mul_f32 v[34:35], v[146:147], v[18:19] op_sel_hi:[0,1]
	v_pk_mul_f32 v[18:19], v[146:147], v[16:17] op_sel_hi:[0,1]
	v_mul_f32_e32 v16, 0xbfb8aa3b, v28
	v_mul_f32_e32 v17, 0xbfb8aa3b, v29
	v_exp_f32_e32 v16, v16
	v_exp_f32_e32 v17, v17
	v_add_f32_e32 v16, 1.0, v16
	v_add_f32_e32 v17, 1.0, v17
	v_rcp_f32_e32 v16, v16
	v_rcp_f32_e32 v17, v17
	v_mul_f32_e32 v16, v28, v16
	v_mul_f32_e32 v17, v29, v17
	v_mul_f32_e32 v16, v16, v20
	v_mul_f32_e32 v17, v17, v21
	v_cvt_pk_bf16_f32 v16, v16, v17
	v_mul_f32_e32 v17, 0xbfb8aa3b, v30
	v_mul_f32_e32 v20, 0xbfb8aa3b, v31
	v_exp_f32_e32 v17, v17
	v_exp_f32_e32 v20, v20
	v_add_f32_e32 v17, 1.0, v17
	v_add_f32_e32 v20, 1.0, v20
	v_rcp_f32_e32 v17, v17
	v_rcp_f32_e32 v20, v20
	v_mul_f32_e32 v17, v30, v17
	v_mul_f32_e32 v20, v31, v20
	v_mul_f32_e32 v17, v17, v22
	v_mul_f32_e32 v20, v20, v23
	v_cvt_pk_bf16_f32 v17, v17, v20
	v_mul_f32_e32 v20, 0xbfb8aa3b, v24
	v_exp_f32_e32 v20, v20
	s_nop 0
	v_add_f32_e32 v20, 1.0, v20
	v_rcp_f32_e32 v20, v20
	s_nop 0
	v_mul_f32_e32 v20, v24, v20
	v_mul_f32_e32 v18, v20, v18
	v_mul_f32_e32 v20, 0xbfb8aa3b, v25
	v_exp_f32_e32 v20, v20
	s_nop 0
	v_add_f32_e32 v20, 1.0, v20
	v_rcp_f32_e32 v20, v20
	s_nop 0
	v_mul_f32_e32 v20, v25, v20
	v_mul_f32_e32 v19, v20, v19
	v_cvt_pk_bf16_f32 v18, v18, v19
	v_mul_f32_e32 v19, 0xbfb8aa3b, v26
	v_mul_f32_e32 v20, 0xbfb8aa3b, v27
	v_exp_f32_e32 v19, v19
	v_exp_f32_e32 v20, v20
	v_add_f32_e32 v19, 1.0, v19
	v_add_f32_e32 v20, 1.0, v20
	v_rcp_f32_e32 v19, v19
	v_rcp_f32_e32 v20, v20
	v_mul_f32_e32 v19, v26, v19
	v_mul_f32_e32 v20, v27, v20
	v_mul_f32_e32 v19, v19, v34
	v_mul_f32_e32 v20, v20, v35
	v_cvt_pk_bf16_f32 v19, v19, v20
	v_add_u32_e32 v20, 0xa0, v151
	v_mad_i64_i32 v[20:21], s[44:45], v20, s29, v[114:115]
	v_lshl_add_u64 v[20:21], v[20:21], 0, v[116:117]
	global_store_dwordx4 v[20:21], v[16:19], off
	s_nop 1
	v_pk_mul_f32 v[16:17], v[144:145], v[2:3] op_sel_hi:[0,1]
	v_pk_mul_f32 v[2:3], v[144:145], v[0:1] op_sel_hi:[0,1]
	v_mul_f32_e32 v0, 0xbfb8aa3b, v12
	v_mul_f32_e32 v1, 0xbfb8aa3b, v13
	v_exp_f32_e32 v0, v0
	v_exp_f32_e32 v1, v1
	v_add_f32_e32 v0, 1.0, v0
	v_add_f32_e32 v1, 1.0, v1
	v_rcp_f32_e32 v0, v0
	v_rcp_f32_e32 v1, v1
	v_mul_f32_e32 v0, v12, v0
	v_mul_f32_e32 v1, v13, v1
	v_mul_f32_e32 v0, v0, v4
	v_mul_f32_e32 v1, v1, v5
	v_cvt_pk_bf16_f32 v0, v0, v1
	v_mul_f32_e32 v1, 0xbfb8aa3b, v14
	v_mul_f32_e32 v4, 0xbfb8aa3b, v15
	v_exp_f32_e32 v1, v1
	v_exp_f32_e32 v4, v4
	v_add_f32_e32 v1, 1.0, v1
	v_add_f32_e32 v4, 1.0, v4
	v_rcp_f32_e32 v1, v1
	v_rcp_f32_e32 v4, v4
	v_mul_f32_e32 v1, v14, v1
	v_mul_f32_e32 v4, v15, v4
	v_mul_f32_e32 v1, v1, v6
	v_mul_f32_e32 v4, v4, v7
	v_cvt_pk_bf16_f32 v1, v1, v4
	v_mul_f32_e32 v4, 0xbfb8aa3b, v8
	v_exp_f32_e32 v4, v4
	s_nop 0
	v_add_f32_e32 v4, 1.0, v4
	v_rcp_f32_e32 v4, v4
	s_nop 0
	v_mul_f32_e32 v4, v8, v4
	v_mul_f32_e32 v2, v4, v2
	v_mul_f32_e32 v4, 0xbfb8aa3b, v9
	v_exp_f32_e32 v4, v4
	s_nop 0
	v_add_f32_e32 v4, 1.0, v4
	v_rcp_f32_e32 v4, v4
	s_nop 0
	v_mul_f32_e32 v4, v9, v4
	v_mul_f32_e32 v3, v4, v3
	v_cvt_pk_bf16_f32 v2, v2, v3
	v_mul_f32_e32 v3, 0xbfb8aa3b, v10
	v_mul_f32_e32 v4, 0xbfb8aa3b, v11
	v_exp_f32_e32 v3, v3
	v_exp_f32_e32 v4, v4
	v_add_f32_e32 v3, 1.0, v3
	v_add_f32_e32 v4, 1.0, v4
	v_rcp_f32_e32 v3, v3
	v_rcp_f32_e32 v4, v4
	v_mul_f32_e32 v3, v10, v3
	v_mul_f32_e32 v4, v11, v4
	v_mul_f32_e32 v3, v3, v16
	v_mul_f32_e32 v4, v4, v17
	v_cvt_pk_bf16_f32 v3, v3, v4
	v_add_u32_e32 v4, 0xb0, v151
	v_mad_i64_i32 v[4:5], s[44:45], v4, s29, v[114:115]
	v_lshl_add_u64 v[4:5], v[4:5], 0, v[116:117]
	s_mov_b64 s[44:45], -1
	global_store_dwordx4 v[4:5], v[0:3], off
	s_cbranch_vccnz .LBB0_575
; #define PG8_BAR __builtin_amdgcn_s_barrier()
; #define GAS __attribute__((address_space(1)))
; template <class Epi, class Sched, bool ALIGN_EPI = false, bool SP2 = false>
; __device__ __forceinline__ void gemm_phase(PG8_LAS unsigned char* lds, const Gemm g, const Sched& S, const Epi& E) {
;     ...
;         cur = nxt; cA = nA; cB = nB; ++ui;
;         if constexpr (Epi::PREFETCH) E.prefetch(cur, wr, fr, epre);
;         if constexpr (ALIGN_EPI) { if (wr == 1) PG8_BAR; }
;     __device__ __forceinline__ void prefetch(const Unit& u, int wr, int fr, float (&pre)[8]) const {
; #pragma unroll
;         for (int i = 0; i < 8; ++i) pre[i] = *(const GAS float*)(rs + u.pm * 256 + wr * 64 + fr + (i >> 2) * 128 + (i & 3) * 16);
;     }
	s_lshl_b32 s42, s8, 8
	s_ashr_i32 s43, s42, 31
	v_lshl_add_u64 v[0:1], s[42:43], 2, v[138:139]
	global_load_dword v158, v[0:1], off
	global_load_dword v156, v[0:1], off offset:64
	global_load_dword v154, v[0:1], off offset:128
	global_load_dword v152, v[0:1], off offset:192
	global_load_dword v150, v[0:1], off offset:512
	global_load_dword v148, v[0:1], off offset:576
	global_load_dword v146, v[0:1], off offset:640
	global_load_dword v144, v[0:1], off offset:704
	s_andn2_b64 vcc, exec, s[2:3]
	s_cbranch_vccnz .LBB0_574
	s_barrier
	s_branch .LBB0_574
